# P5 and P10 row phases: loads three rows ahead (4 row buffers) instead of two
# baseline (speedup 1.0000x reference)
.LBB0_569:
	s_or_b64 exec, exec, s[2:3]
	s_waitcnt lgkmcnt(0)
	v_mov_b32_e32 v0, v208
	s_barrier
	v_lshrrev_b32_e32 v192, 6, v208
	v_and_b32_e32 v193, 63, v208
	v_readfirstlane_b32 s42, v192
	v_lshlrev_b32_e32 v200, 4, v193
	v_lshlrev_b32_e32 v201, 3, v193
	s_nop 1
	s_add_u32 s1, s60, s42
	s_lshl_b32 s42, s1, 16
	s_add_u32 s2, s52, s42
	s_addc_u32 s3, s53, 0
	s_add_u32 s8, s90, s42
	s_addc_u32 s9, s91, 0
	s_add_u32 s8, s8, 0xec00000
	s_addc_u32 s9, s9, 0
	s_lshr_b32 s42, s42, 1
	s_add_u32 s6, s90, s42
	s_addc_u32 s7, s91, 0
	s_add_u32 s12, s6, 0x2400000
	s_addc_u32 s13, s7, 0
	s_add_u32 s6, s6, 0x16c00000
	s_addc_u32 s7, s7, 0
	s_lshr_b32 s42, s1, 7
	s_mul_i32 s42, s42, 0x3000
	s_add_u32 s38, s90, s42
	s_addc_u32 s39, s91, 0
	s_add_u32 s38, s38, 0x21b3000
	s_addc_u32 s39, s39, 0
	s_add_u32 s40, s38, 0x1000
	s_addc_u32 s41, s39, 0
	global_load_dwordx4 v[0:3], v200, s[64:65] offset:0
	global_load_dwordx4 v[4:7], v200, s[64:65] offset:1024
	global_load_dwordx4 v[8:11], v200, s[64:65] offset:2048
	global_load_dwordx4 v[12:15], v200, s[64:65] offset:3072
	global_load_dwordx4 v[16:19], v200, s[66:67] offset:0
	global_load_dwordx4 v[20:23], v200, s[66:67] offset:1024
	global_load_dwordx4 v[24:27], v200, s[66:67] offset:2048
	global_load_dwordx4 v[28:31], v200, s[66:67] offset:3072
	global_load_dwordx4 v[32:35], v200, s[40:41] offset:0
	global_load_dwordx4 v[36:39], v200, s[40:41] offset:1024
	global_load_dwordx4 v[40:43], v200, s[40:41] offset:2048
	global_load_dwordx4 v[44:47], v200, s[40:41] offset:3072
	global_load_dwordx4 v[48:51], v200, s[38:39] offset:0
	global_load_dwordx4 v[52:55], v200, s[38:39] offset:1024
	global_load_dwordx4 v[56:59], v200, s[38:39] offset:2048
	global_load_dwordx4 v[60:63], v200, s[38:39] offset:3072
	v_mov_b32_e32 v196, 0xba800000
	v_mov_b32_e32 v197, 0xba800000
	v_mov_b32_e32 v202, 0x3a800000
	v_mov_b32_e32 v203, 0x358637bd
	s_mov_b32 s44, 0x3fb504f3
	s_mov_b32 s45, 0x3fb504f3
	global_load_dwordx4 v[64:67], v200, s[2:3] offset:0
	global_load_dwordx4 v[68:71], v200, s[2:3] offset:1024
	global_load_dwordx4 v[72:75], v200, s[2:3] offset:2048
	global_load_dwordx4 v[76:79], v200, s[2:3] offset:3072
	global_load_dwordx2 v[128:129], v201, s[6:7] offset:0
	global_load_dwordx2 v[130:131], v201, s[6:7] offset:512
	global_load_dwordx2 v[132:133], v201, s[6:7] offset:1024
	global_load_dwordx2 v[134:135], v201, s[6:7] offset:1536
	s_add_u32 s2, s2, 0x1000
	s_addc_u32 s3, s3, 0
	s_add_u32 s6, s6, 0x800
	s_addc_u32 s7, s7, 0
	global_load_dwordx4 v[80:83], v200, s[2:3] offset:0
	global_load_dwordx4 v[84:87], v200, s[2:3] offset:1024
	global_load_dwordx4 v[88:91], v200, s[2:3] offset:2048
	global_load_dwordx4 v[92:95], v200, s[2:3] offset:3072
	global_load_dwordx2 v[136:137], v201, s[6:7] offset:0
	global_load_dwordx2 v[138:139], v201, s[6:7] offset:512
	global_load_dwordx2 v[140:141], v201, s[6:7] offset:1024
	global_load_dwordx2 v[142:143], v201, s[6:7] offset:1536
	s_add_u32 s2, s2, 0x1000
	s_addc_u32 s3, s3, 0
	s_add_u32 s6, s6, 0x800
	s_addc_u32 s7, s7, 0
	global_load_dwordx4 v[96:99], v200, s[2:3] offset:0
	global_load_dwordx4 v[100:103], v200, s[2:3] offset:1024
	global_load_dwordx4 v[104:107], v200, s[2:3] offset:2048
	global_load_dwordx4 v[108:111], v200, s[2:3] offset:3072
	global_load_dwordx2 v[144:145], v201, s[6:7] offset:0
	global_load_dwordx2 v[146:147], v201, s[6:7] offset:512
	global_load_dwordx2 v[148:149], v201, s[6:7] offset:1024
	global_load_dwordx2 v[150:151], v201, s[6:7] offset:1536
	s_add_u32 s2, s2, 0x1000
	s_addc_u32 s3, s3, 0
	s_add_u32 s6, s6, 0x800
	s_addc_u32 s7, s7, 0
	global_load_dwordx4 v[112:115], v200, s[2:3] offset:0
	global_load_dwordx4 v[116:119], v200, s[2:3] offset:1024
	global_load_dwordx4 v[120:123], v200, s[2:3] offset:2048
	global_load_dwordx4 v[124:127], v200, s[2:3] offset:3072
	global_load_dwordx2 v[152:153], v201, s[6:7] offset:0
	global_load_dwordx2 v[154:155], v201, s[6:7] offset:512
	global_load_dwordx2 v[156:157], v201, s[6:7] offset:1024
	global_load_dwordx2 v[158:159], v201, s[6:7] offset:1536
	s_add_u32 s2, s2, 0x1000
	s_addc_u32 s3, s3, 0
	s_add_u32 s6, s6, 0x800
	s_addc_u32 s7, s7, 0
	s_waitcnt vmcnt(24)
	v_pk_add_f32 v[32:33], v[32:33], 1.0 op_sel_hi:[1,0]
	v_pk_add_f32 v[34:35], v[34:35], 1.0 op_sel_hi:[1,0]
	v_pk_add_f32 v[36:37], v[36:37], 1.0 op_sel_hi:[1,0]
	v_pk_add_f32 v[38:39], v[38:39], 1.0 op_sel_hi:[1,0]
	v_pk_add_f32 v[40:41], v[40:41], 1.0 op_sel_hi:[1,0]
	v_pk_add_f32 v[42:43], v[42:43], 1.0 op_sel_hi:[1,0]
	v_pk_add_f32 v[44:45], v[44:45], 1.0 op_sel_hi:[1,0]
	v_pk_add_f32 v[46:47], v[46:47], 1.0 op_sel_hi:[1,0]
	v_lshlrev_b32_e32 v160, 16, v128
	v_and_b32_e32 v161, 0xffff0000, v128
	v_lshlrev_b32_e32 v162, 16, v129
	v_and_b32_e32 v163, 0xffff0000, v129
	v_lshlrev_b32_e32 v164, 16, v130
	v_and_b32_e32 v165, 0xffff0000, v130
	v_lshlrev_b32_e32 v166, 16, v131
	v_and_b32_e32 v167, 0xffff0000, v131
	v_lshlrev_b32_e32 v168, 16, v132
	v_and_b32_e32 v169, 0xffff0000, v132
	v_lshlrev_b32_e32 v170, 16, v133
	v_and_b32_e32 v171, 0xffff0000, v133
	v_lshlrev_b32_e32 v172, 16, v134
	v_and_b32_e32 v173, 0xffff0000, v134
	v_lshlrev_b32_e32 v174, 16, v135
	v_and_b32_e32 v175, 0xffff0000, v135
	v_pk_fma_f32 v[160:161], v[64:65], s[44:45], v[160:161]
	v_pk_fma_f32 v[162:163], v[66:67], s[44:45], v[162:163]
	v_pk_fma_f32 v[164:165], v[68:69], s[44:45], v[164:165]
	v_pk_fma_f32 v[166:167], v[70:71], s[44:45], v[166:167]
	v_pk_fma_f32 v[168:169], v[72:73], s[44:45], v[168:169]
	v_pk_fma_f32 v[170:171], v[74:75], s[44:45], v[170:171]
	v_pk_fma_f32 v[172:173], v[76:77], s[44:45], v[172:173]
	v_pk_fma_f32 v[174:175], v[78:79], s[44:45], v[174:175]
	v_pk_add_f32 v[176:177], v[160:161], v[162:163]
	v_pk_add_f32 v[176:177], v[176:177], v[164:165]
	v_pk_add_f32 v[176:177], v[176:177], v[166:167]
	v_pk_add_f32 v[176:177], v[176:177], v[168:169]
	v_pk_add_f32 v[176:177], v[176:177], v[170:171]
	v_pk_add_f32 v[176:177], v[176:177], v[172:173]
	v_pk_add_f32 v[176:177], v[176:177], v[174:175]
	v_add_f32_e32 v194, v176, v177
	s_nop 1
	v_add_f32_dpp v192, v194, v194 quad_perm:[1,0,3,2] row_mask:0xf bank_mask:0xf
	s_nop 1
	v_add_f32_dpp v192, v192, v192 quad_perm:[2,3,0,1] row_mask:0xf bank_mask:0xf
	s_nop 1
	v_add_f32_dpp v192, v192, v192 row_half_mirror row_mask:0xf bank_mask:0xf
	s_nop 1
	v_add_f32_dpp v192, v192, v192 row_mirror row_mask:0xf bank_mask:0xf
	s_nop 1
	v_add_f32_dpp v192, v192, v192 row_bcast:15 row_mask:0xa bank_mask:0xf
	s_nop 1
	v_add_f32_dpp v192, v192, v192 row_bcast:31 row_mask:0xc bank_mask:0xf
	s_nop 1
	v_readlane_b32 s42, v192, 63
	s_nop 3
	s_mov_b32 s43, s42
	v_pk_fma_f32 v[160:161], s[42:43], v[196:197], v[160:161]
	v_pk_fma_f32 v[162:163], s[42:43], v[196:197], v[162:163]
	v_pk_fma_f32 v[164:165], s[42:43], v[196:197], v[164:165]
	v_pk_fma_f32 v[166:167], s[42:43], v[196:197], v[166:167]
	v_pk_fma_f32 v[168:169], s[42:43], v[196:197], v[168:169]
	v_pk_fma_f32 v[170:171], s[42:43], v[196:197], v[170:171]
	v_pk_fma_f32 v[172:173], s[42:43], v[196:197], v[172:173]
	v_pk_fma_f32 v[174:175], s[42:43], v[196:197], v[174:175]
	v_pk_mul_f32 v[176:177], v[160:161], v[160:161]
	v_pk_fma_f32 v[176:177], v[162:163], v[162:163], v[176:177]
	v_pk_fma_f32 v[176:177], v[164:165], v[164:165], v[176:177]
	v_pk_fma_f32 v[176:177], v[166:167], v[166:167], v[176:177]
	v_pk_fma_f32 v[176:177], v[168:169], v[168:169], v[176:177]
	v_pk_fma_f32 v[176:177], v[170:171], v[170:171], v[176:177]
	v_pk_fma_f32 v[176:177], v[172:173], v[172:173], v[176:177]
	v_pk_fma_f32 v[176:177], v[174:175], v[174:175], v[176:177]
	v_add_f32_e32 v194, v176, v177
	s_nop 1
	v_add_f32_dpp v192, v194, v194 quad_perm:[1,0,3,2] row_mask:0xf bank_mask:0xf
	s_nop 1
	v_add_f32_dpp v192, v192, v192 quad_perm:[2,3,0,1] row_mask:0xf bank_mask:0xf
	s_nop 1
	v_add_f32_dpp v192, v192, v192 row_half_mirror row_mask:0xf bank_mask:0xf
	s_nop 1
	v_add_f32_dpp v192, v192, v192 row_mirror row_mask:0xf bank_mask:0xf
	s_nop 1
	v_add_f32_dpp v192, v192, v192 row_bcast:15 row_mask:0xa bank_mask:0xf
	s_nop 1
	v_add_f32_dpp v192, v192, v192 row_bcast:31 row_mask:0xc bank_mask:0xf
	s_nop 1
	v_readlane_b32 s42, v192, 63
	s_nop 3
	v_fma_f32 v198, s42, v202, v203
	v_rsq_f32_e32 v198, v198
	s_nop 0
	v_pk_mul_f32 v[160:161], v[160:161], v[198:199] op_sel_hi:[1,0]
	v_pk_mul_f32 v[162:163], v[162:163], v[198:199] op_sel_hi:[1,0]
	v_pk_mul_f32 v[164:165], v[164:165], v[198:199] op_sel_hi:[1,0]
	v_pk_mul_f32 v[166:167], v[166:167], v[198:199] op_sel_hi:[1,0]
	v_pk_mul_f32 v[168:169], v[168:169], v[198:199] op_sel_hi:[1,0]
	v_pk_mul_f32 v[170:171], v[170:171], v[198:199] op_sel_hi:[1,0]
	v_pk_mul_f32 v[172:173], v[172:173], v[198:199] op_sel_hi:[1,0]
	v_pk_mul_f32 v[174:175], v[174:175], v[198:199] op_sel_hi:[1,0]
	v_pk_fma_f32 v[160:161], v[160:161], v[0:1], v[16:17]
	v_pk_fma_f32 v[162:163], v[162:163], v[2:3], v[18:19]
	v_pk_fma_f32 v[164:165], v[164:165], v[4:5], v[20:21]
	v_pk_fma_f32 v[166:167], v[166:167], v[6:7], v[22:23]
	v_pk_fma_f32 v[168:169], v[168:169], v[8:9], v[24:25]
	v_pk_fma_f32 v[170:171], v[170:171], v[10:11], v[26:27]
	v_pk_fma_f32 v[172:173], v[172:173], v[12:13], v[28:29]
	v_pk_fma_f32 v[174:175], v[174:175], v[14:15], v[30:31]
	global_store_dwordx4 v200, v[160:163], s[8:9] offset:0
	global_store_dwordx4 v200, v[164:167], s[8:9] offset:1024
	global_store_dwordx4 v200, v[168:171], s[8:9] offset:2048
	global_store_dwordx4 v200, v[172:175], s[8:9] offset:3072
	v_pk_add_f32 v[176:177], v[160:161], v[162:163]
	v_pk_add_f32 v[176:177], v[176:177], v[164:165]
	v_pk_add_f32 v[176:177], v[176:177], v[166:167]
	v_pk_add_f32 v[176:177], v[176:177], v[168:169]
	v_pk_add_f32 v[176:177], v[176:177], v[170:171]
	v_pk_add_f32 v[176:177], v[176:177], v[172:173]
	v_pk_add_f32 v[176:177], v[176:177], v[174:175]
	v_add_f32_e32 v194, v176, v177
	s_nop 1
	v_add_f32_dpp v192, v194, v194 quad_perm:[1,0,3,2] row_mask:0xf bank_mask:0xf
	s_nop 1
	v_add_f32_dpp v192, v192, v192 quad_perm:[2,3,0,1] row_mask:0xf bank_mask:0xf
	s_nop 1
	v_add_f32_dpp v192, v192, v192 row_half_mirror row_mask:0xf bank_mask:0xf
	s_nop 1
	v_add_f32_dpp v192, v192, v192 row_mirror row_mask:0xf bank_mask:0xf
	s_nop 1
	v_add_f32_dpp v192, v192, v192 row_bcast:15 row_mask:0xa bank_mask:0xf
	s_nop 1
	v_add_f32_dpp v192, v192, v192 row_bcast:31 row_mask:0xc bank_mask:0xf
	s_nop 1
	v_readlane_b32 s42, v192, 63
	s_nop 3
	s_mov_b32 s43, s42
	v_pk_fma_f32 v[160:161], s[42:43], v[196:197], v[160:161]
	v_pk_fma_f32 v[162:163], s[42:43], v[196:197], v[162:163]
	v_pk_fma_f32 v[164:165], s[42:43], v[196:197], v[164:165]
	v_pk_fma_f32 v[166:167], s[42:43], v[196:197], v[166:167]
	v_pk_fma_f32 v[168:169], s[42:43], v[196:197], v[168:169]
	v_pk_fma_f32 v[170:171], s[42:43], v[196:197], v[170:171]
	v_pk_fma_f32 v[172:173], s[42:43], v[196:197], v[172:173]
	v_pk_fma_f32 v[174:175], s[42:43], v[196:197], v[174:175]
	v_pk_mul_f32 v[176:177], v[160:161], v[160:161]
	v_pk_fma_f32 v[176:177], v[162:163], v[162:163], v[176:177]
	v_pk_fma_f32 v[176:177], v[164:165], v[164:165], v[176:177]
	v_pk_fma_f32 v[176:177], v[166:167], v[166:167], v[176:177]
	v_pk_fma_f32 v[176:177], v[168:169], v[168:169], v[176:177]
	v_pk_fma_f32 v[176:177], v[170:171], v[170:171], v[176:177]
	v_pk_fma_f32 v[176:177], v[172:173], v[172:173], v[176:177]
	v_pk_fma_f32 v[176:177], v[174:175], v[174:175], v[176:177]
	v_add_f32_e32 v194, v176, v177
	s_nop 1
	v_add_f32_dpp v192, v194, v194 quad_perm:[1,0,3,2] row_mask:0xf bank_mask:0xf
	s_nop 1
	v_add_f32_dpp v192, v192, v192 quad_perm:[2,3,0,1] row_mask:0xf bank_mask:0xf
	s_nop 1
	v_add_f32_dpp v192, v192, v192 row_half_mirror row_mask:0xf bank_mask:0xf
	s_nop 1
	v_add_f32_dpp v192, v192, v192 row_mirror row_mask:0xf bank_mask:0xf
	s_nop 1
	v_add_f32_dpp v192, v192, v192 row_bcast:15 row_mask:0xa bank_mask:0xf
	s_nop 1
	v_add_f32_dpp v192, v192, v192 row_bcast:31 row_mask:0xc bank_mask:0xf
	s_nop 1
	v_readlane_b32 s42, v192, 63
	s_nop 3
	v_fma_f32 v198, s42, v202, v203
	v_rsq_f32_e32 v198, v198
	s_nop 0
	v_pk_mul_f32 v[160:161], v[160:161], v[198:199] op_sel_hi:[1,0]
	v_pk_mul_f32 v[162:163], v[162:163], v[198:199] op_sel_hi:[1,0]
	v_pk_mul_f32 v[164:165], v[164:165], v[198:199] op_sel_hi:[1,0]
	v_pk_mul_f32 v[166:167], v[166:167], v[198:199] op_sel_hi:[1,0]
	v_pk_mul_f32 v[168:169], v[168:169], v[198:199] op_sel_hi:[1,0]
	v_pk_mul_f32 v[170:171], v[170:171], v[198:199] op_sel_hi:[1,0]
	v_pk_mul_f32 v[172:173], v[172:173], v[198:199] op_sel_hi:[1,0]
	v_pk_mul_f32 v[174:175], v[174:175], v[198:199] op_sel_hi:[1,0]
	v_pk_fma_f32 v[160:161], v[160:161], v[32:33], v[48:49]
	v_pk_fma_f32 v[162:163], v[162:163], v[34:35], v[50:51]
	v_pk_fma_f32 v[164:165], v[164:165], v[36:37], v[52:53]
	v_pk_fma_f32 v[166:167], v[166:167], v[38:39], v[54:55]
	v_pk_fma_f32 v[168:169], v[168:169], v[40:41], v[56:57]
	v_pk_fma_f32 v[170:171], v[170:171], v[42:43], v[58:59]
	v_pk_fma_f32 v[172:173], v[172:173], v[44:45], v[60:61]
	v_pk_fma_f32 v[174:175], v[174:175], v[46:47], v[62:63]
	v_cvt_pk_bf16_f32 v176, v160, v161
	v_cvt_pk_bf16_f32 v177, v162, v163
	v_cvt_pk_bf16_f32 v178, v164, v165
	v_cvt_pk_bf16_f32 v179, v166, v167
	v_cvt_pk_bf16_f32 v180, v168, v169
	v_cvt_pk_bf16_f32 v181, v170, v171
	v_cvt_pk_bf16_f32 v182, v172, v173
	v_cvt_pk_bf16_f32 v183, v174, v175
	global_store_dwordx2 v201, v[176:177], s[12:13] offset:0
	global_store_dwordx2 v201, v[178:179], s[12:13] offset:512
	global_store_dwordx2 v201, v[180:181], s[12:13] offset:1024
	global_store_dwordx2 v201, v[182:183], s[12:13] offset:1536
	s_add_u32 s8, s8, 0x1000
	s_addc_u32 s9, s9, 0
	s_add_u32 s12, s12, 0x800
	s_addc_u32 s13, s13, 0
	global_load_dwordx4 v[64:67], v200, s[2:3] offset:0
	global_load_dwordx4 v[68:71], v200, s[2:3] offset:1024
	global_load_dwordx4 v[72:75], v200, s[2:3] offset:2048
	global_load_dwordx4 v[76:79], v200, s[2:3] offset:3072
	global_load_dwordx2 v[128:129], v201, s[6:7] offset:0
	global_load_dwordx2 v[130:131], v201, s[6:7] offset:512
	global_load_dwordx2 v[132:133], v201, s[6:7] offset:1024
	global_load_dwordx2 v[134:135], v201, s[6:7] offset:1536
	s_add_u32 s2, s2, 0x1000
	s_addc_u32 s3, s3, 0
	s_add_u32 s6, s6, 0x800
	s_addc_u32 s7, s7, 0
	s_waitcnt vmcnt(32)
	v_lshlrev_b32_e32 v160, 16, v136
	v_and_b32_e32 v161, 0xffff0000, v136
	v_lshlrev_b32_e32 v162, 16, v137
	v_and_b32_e32 v163, 0xffff0000, v137
	v_lshlrev_b32_e32 v164, 16, v138
	v_and_b32_e32 v165, 0xffff0000, v138
	v_lshlrev_b32_e32 v166, 16, v139
	v_and_b32_e32 v167, 0xffff0000, v139
	v_lshlrev_b32_e32 v168, 16, v140
	v_and_b32_e32 v169, 0xffff0000, v140
	v_lshlrev_b32_e32 v170, 16, v141
	v_and_b32_e32 v171, 0xffff0000, v141
	v_lshlrev_b32_e32 v172, 16, v142
	v_and_b32_e32 v173, 0xffff0000, v142
	v_lshlrev_b32_e32 v174, 16, v143
	v_and_b32_e32 v175, 0xffff0000, v143
	v_pk_fma_f32 v[160:161], v[80:81], s[44:45], v[160:161]
	v_pk_fma_f32 v[162:163], v[82:83], s[44:45], v[162:163]
	v_pk_fma_f32 v[164:165], v[84:85], s[44:45], v[164:165]
	v_pk_fma_f32 v[166:167], v[86:87], s[44:45], v[166:167]
	v_pk_fma_f32 v[168:169], v[88:89], s[44:45], v[168:169]
	v_pk_fma_f32 v[170:171], v[90:91], s[44:45], v[170:171]
	v_pk_fma_f32 v[172:173], v[92:93], s[44:45], v[172:173]
	v_pk_fma_f32 v[174:175], v[94:95], s[44:45], v[174:175]
	v_pk_add_f32 v[176:177], v[160:161], v[162:163]
	v_pk_add_f32 v[176:177], v[176:177], v[164:165]
	v_pk_add_f32 v[176:177], v[176:177], v[166:167]
	v_pk_add_f32 v[176:177], v[176:177], v[168:169]
	v_pk_add_f32 v[176:177], v[176:177], v[170:171]
	v_pk_add_f32 v[176:177], v[176:177], v[172:173]
	v_pk_add_f32 v[176:177], v[176:177], v[174:175]
	v_add_f32_e32 v194, v176, v177
	s_nop 1
	v_add_f32_dpp v192, v194, v194 quad_perm:[1,0,3,2] row_mask:0xf bank_mask:0xf
	s_nop 1
	v_add_f32_dpp v192, v192, v192 quad_perm:[2,3,0,1] row_mask:0xf bank_mask:0xf
	s_nop 1
	v_add_f32_dpp v192, v192, v192 row_half_mirror row_mask:0xf bank_mask:0xf
	s_nop 1
	v_add_f32_dpp v192, v192, v192 row_mirror row_mask:0xf bank_mask:0xf
	s_nop 1
	v_add_f32_dpp v192, v192, v192 row_bcast:15 row_mask:0xa bank_mask:0xf
	s_nop 1
	v_add_f32_dpp v192, v192, v192 row_bcast:31 row_mask:0xc bank_mask:0xf
	s_nop 1
	v_readlane_b32 s42, v192, 63
	s_nop 3
	s_mov_b32 s43, s42
	v_pk_fma_f32 v[160:161], s[42:43], v[196:197], v[160:161]
	v_pk_fma_f32 v[162:163], s[42:43], v[196:197], v[162:163]
	v_pk_fma_f32 v[164:165], s[42:43], v[196:197], v[164:165]
	v_pk_fma_f32 v[166:167], s[42:43], v[196:197], v[166:167]
	v_pk_fma_f32 v[168:169], s[42:43], v[196:197], v[168:169]
	v_pk_fma_f32 v[170:171], s[42:43], v[196:197], v[170:171]
	v_pk_fma_f32 v[172:173], s[42:43], v[196:197], v[172:173]
	v_pk_fma_f32 v[174:175], s[42:43], v[196:197], v[174:175]
	v_pk_mul_f32 v[176:177], v[160:161], v[160:161]
	v_pk_fma_f32 v[176:177], v[162:163], v[162:163], v[176:177]
	v_pk_fma_f32 v[176:177], v[164:165], v[164:165], v[176:177]
	v_pk_fma_f32 v[176:177], v[166:167], v[166:167], v[176:177]
	v_pk_fma_f32 v[176:177], v[168:169], v[168:169], v[176:177]
	v_pk_fma_f32 v[176:177], v[170:171], v[170:171], v[176:177]
	v_pk_fma_f32 v[176:177], v[172:173], v[172:173], v[176:177]
	v_pk_fma_f32 v[176:177], v[174:175], v[174:175], v[176:177]
	v_add_f32_e32 v194, v176, v177
	s_nop 1
	v_add_f32_dpp v192, v194, v194 quad_perm:[1,0,3,2] row_mask:0xf bank_mask:0xf
	s_nop 1
	v_add_f32_dpp v192, v192, v192 quad_perm:[2,3,0,1] row_mask:0xf bank_mask:0xf
	s_nop 1
	v_add_f32_dpp v192, v192, v192 row_half_mirror row_mask:0xf bank_mask:0xf
	s_nop 1
	v_add_f32_dpp v192, v192, v192 row_mirror row_mask:0xf bank_mask:0xf
	s_nop 1
	v_add_f32_dpp v192, v192, v192 row_bcast:15 row_mask:0xa bank_mask:0xf
	s_nop 1
	v_add_f32_dpp v192, v192, v192 row_bcast:31 row_mask:0xc bank_mask:0xf
	s_nop 1
	v_readlane_b32 s42, v192, 63
	s_nop 3
	v_fma_f32 v198, s42, v202, v203
	v_rsq_f32_e32 v198, v198
	s_nop 0
	v_pk_mul_f32 v[160:161], v[160:161], v[198:199] op_sel_hi:[1,0]
	v_pk_mul_f32 v[162:163], v[162:163], v[198:199] op_sel_hi:[1,0]
	v_pk_mul_f32 v[164:165], v[164:165], v[198:199] op_sel_hi:[1,0]
	v_pk_mul_f32 v[166:167], v[166:167], v[198:199] op_sel_hi:[1,0]
	v_pk_mul_f32 v[168:169], v[168:169], v[198:199] op_sel_hi:[1,0]
	v_pk_mul_f32 v[170:171], v[170:171], v[198:199] op_sel_hi:[1,0]
	v_pk_mul_f32 v[172:173], v[172:173], v[198:199] op_sel_hi:[1,0]
	v_pk_mul_f32 v[174:175], v[174:175], v[198:199] op_sel_hi:[1,0]
	v_pk_fma_f32 v[160:161], v[160:161], v[0:1], v[16:17]
	v_pk_fma_f32 v[162:163], v[162:163], v[2:3], v[18:19]
	v_pk_fma_f32 v[164:165], v[164:165], v[4:5], v[20:21]
	v_pk_fma_f32 v[166:167], v[166:167], v[6:7], v[22:23]
	v_pk_fma_f32 v[168:169], v[168:169], v[8:9], v[24:25]
	v_pk_fma_f32 v[170:171], v[170:171], v[10:11], v[26:27]
	v_pk_fma_f32 v[172:173], v[172:173], v[12:13], v[28:29]
	v_pk_fma_f32 v[174:175], v[174:175], v[14:15], v[30:31]
	global_store_dwordx4 v200, v[160:163], s[8:9] offset:0
	global_store_dwordx4 v200, v[164:167], s[8:9] offset:1024
	global_store_dwordx4 v200, v[168:171], s[8:9] offset:2048
	global_store_dwordx4 v200, v[172:175], s[8:9] offset:3072
	v_pk_add_f32 v[176:177], v[160:161], v[162:163]
	v_pk_add_f32 v[176:177], v[176:177], v[164:165]
	v_pk_add_f32 v[176:177], v[176:177], v[166:167]
	v_pk_add_f32 v[176:177], v[176:177], v[168:169]
	v_pk_add_f32 v[176:177], v[176:177], v[170:171]
	v_pk_add_f32 v[176:177], v[176:177], v[172:173]
	v_pk_add_f32 v[176:177], v[176:177], v[174:175]
	v_add_f32_e32 v194, v176, v177
	s_nop 1
	v_add_f32_dpp v192, v194, v194 quad_perm:[1,0,3,2] row_mask:0xf bank_mask:0xf
	s_nop 1
	v_add_f32_dpp v192, v192, v192 quad_perm:[2,3,0,1] row_mask:0xf bank_mask:0xf
	s_nop 1
	v_add_f32_dpp v192, v192, v192 row_half_mirror row_mask:0xf bank_mask:0xf
	s_nop 1
	v_add_f32_dpp v192, v192, v192 row_mirror row_mask:0xf bank_mask:0xf
	s_nop 1
	v_add_f32_dpp v192, v192, v192 row_bcast:15 row_mask:0xa bank_mask:0xf
	s_nop 1
	v_add_f32_dpp v192, v192, v192 row_bcast:31 row_mask:0xc bank_mask:0xf
	s_nop 1
	v_readlane_b32 s42, v192, 63
	s_nop 3
	s_mov_b32 s43, s42
	v_pk_fma_f32 v[160:161], s[42:43], v[196:197], v[160:161]
	v_pk_fma_f32 v[162:163], s[42:43], v[196:197], v[162:163]
	v_pk_fma_f32 v[164:165], s[42:43], v[196:197], v[164:165]
	v_pk_fma_f32 v[166:167], s[42:43], v[196:197], v[166:167]
	v_pk_fma_f32 v[168:169], s[42:43], v[196:197], v[168:169]
	v_pk_fma_f32 v[170:171], s[42:43], v[196:197], v[170:171]
	v_pk_fma_f32 v[172:173], s[42:43], v[196:197], v[172:173]
	v_pk_fma_f32 v[174:175], s[42:43], v[196:197], v[174:175]
	v_pk_mul_f32 v[176:177], v[160:161], v[160:161]
	v_pk_fma_f32 v[176:177], v[162:163], v[162:163], v[176:177]
	v_pk_fma_f32 v[176:177], v[164:165], v[164:165], v[176:177]
	v_pk_fma_f32 v[176:177], v[166:167], v[166:167], v[176:177]
	v_pk_fma_f32 v[176:177], v[168:169], v[168:169], v[176:177]
	v_pk_fma_f32 v[176:177], v[170:171], v[170:171], v[176:177]
	v_pk_fma_f32 v[176:177], v[172:173], v[172:173], v[176:177]
	v_pk_fma_f32 v[176:177], v[174:175], v[174:175], v[176:177]
	v_add_f32_e32 v194, v176, v177
	s_nop 1
	v_add_f32_dpp v192, v194, v194 quad_perm:[1,0,3,2] row_mask:0xf bank_mask:0xf
	s_nop 1
	v_add_f32_dpp v192, v192, v192 quad_perm:[2,3,0,1] row_mask:0xf bank_mask:0xf
	s_nop 1
	v_add_f32_dpp v192, v192, v192 row_half_mirror row_mask:0xf bank_mask:0xf
	s_nop 1
	v_add_f32_dpp v192, v192, v192 row_mirror row_mask:0xf bank_mask:0xf
	s_nop 1
	v_add_f32_dpp v192, v192, v192 row_bcast:15 row_mask:0xa bank_mask:0xf
	s_nop 1
	v_add_f32_dpp v192, v192, v192 row_bcast:31 row_mask:0xc bank_mask:0xf
	s_nop 1
	v_readlane_b32 s42, v192, 63
	s_nop 3
	v_fma_f32 v198, s42, v202, v203
	v_rsq_f32_e32 v198, v198
	s_nop 0
	v_pk_mul_f32 v[160:161], v[160:161], v[198:199] op_sel_hi:[1,0]
	v_pk_mul_f32 v[162:163], v[162:163], v[198:199] op_sel_hi:[1,0]
	v_pk_mul_f32 v[164:165], v[164:165], v[198:199] op_sel_hi:[1,0]
	v_pk_mul_f32 v[166:167], v[166:167], v[198:199] op_sel_hi:[1,0]
	v_pk_mul_f32 v[168:169], v[168:169], v[198:199] op_sel_hi:[1,0]
	v_pk_mul_f32 v[170:171], v[170:171], v[198:199] op_sel_hi:[1,0]
	v_pk_mul_f32 v[172:173], v[172:173], v[198:199] op_sel_hi:[1,0]
	v_pk_mul_f32 v[174:175], v[174:175], v[198:199] op_sel_hi:[1,0]
	v_pk_fma_f32 v[160:161], v[160:161], v[32:33], v[48:49]
	v_pk_fma_f32 v[162:163], v[162:163], v[34:35], v[50:51]
	v_pk_fma_f32 v[164:165], v[164:165], v[36:37], v[52:53]
	v_pk_fma_f32 v[166:167], v[166:167], v[38:39], v[54:55]
	v_pk_fma_f32 v[168:169], v[168:169], v[40:41], v[56:57]
	v_pk_fma_f32 v[170:171], v[170:171], v[42:43], v[58:59]
	v_pk_fma_f32 v[172:173], v[172:173], v[44:45], v[60:61]
	v_pk_fma_f32 v[174:175], v[174:175], v[46:47], v[62:63]
	v_cvt_pk_bf16_f32 v176, v160, v161
	v_cvt_pk_bf16_f32 v177, v162, v163
	v_cvt_pk_bf16_f32 v178, v164, v165
	v_cvt_pk_bf16_f32 v179, v166, v167
	v_cvt_pk_bf16_f32 v180, v168, v169
	v_cvt_pk_bf16_f32 v181, v170, v171
	v_cvt_pk_bf16_f32 v182, v172, v173
	v_cvt_pk_bf16_f32 v183, v174, v175
	global_store_dwordx2 v201, v[176:177], s[12:13] offset:0
	global_store_dwordx2 v201, v[178:179], s[12:13] offset:512
	global_store_dwordx2 v201, v[180:181], s[12:13] offset:1024
	global_store_dwordx2 v201, v[182:183], s[12:13] offset:1536
	s_add_u32 s8, s8, 0x1000
	s_addc_u32 s9, s9, 0
	s_add_u32 s12, s12, 0x800
	s_addc_u32 s13, s13, 0
	global_load_dwordx4 v[80:83], v200, s[2:3] offset:0
	global_load_dwordx4 v[84:87], v200, s[2:3] offset:1024
	global_load_dwordx4 v[88:91], v200, s[2:3] offset:2048
	global_load_dwordx4 v[92:95], v200, s[2:3] offset:3072
	global_load_dwordx2 v[136:137], v201, s[6:7] offset:0
	global_load_dwordx2 v[138:139], v201, s[6:7] offset:512
	global_load_dwordx2 v[140:141], v201, s[6:7] offset:1024
	global_load_dwordx2 v[142:143], v201, s[6:7] offset:1536
	s_add_u32 s2, s2, 0x1000
	s_addc_u32 s3, s3, 0
	s_add_u32 s6, s6, 0x800
	s_addc_u32 s7, s7, 0
	s_waitcnt vmcnt(40)
	v_lshlrev_b32_e32 v160, 16, v144
	v_and_b32_e32 v161, 0xffff0000, v144
	v_lshlrev_b32_e32 v162, 16, v145
	v_and_b32_e32 v163, 0xffff0000, v145
	v_lshlrev_b32_e32 v164, 16, v146
	v_and_b32_e32 v165, 0xffff0000, v146
	v_lshlrev_b32_e32 v166, 16, v147
	v_and_b32_e32 v167, 0xffff0000, v147
	v_lshlrev_b32_e32 v168, 16, v148
	v_and_b32_e32 v169, 0xffff0000, v148
	v_lshlrev_b32_e32 v170, 16, v149
	v_and_b32_e32 v171, 0xffff0000, v149
	v_lshlrev_b32_e32 v172, 16, v150
	v_and_b32_e32 v173, 0xffff0000, v150
	v_lshlrev_b32_e32 v174, 16, v151
	v_and_b32_e32 v175, 0xffff0000, v151
	v_pk_fma_f32 v[160:161], v[96:97], s[44:45], v[160:161]
	v_pk_fma_f32 v[162:163], v[98:99], s[44:45], v[162:163]
	v_pk_fma_f32 v[164:165], v[100:101], s[44:45], v[164:165]
	v_pk_fma_f32 v[166:167], v[102:103], s[44:45], v[166:167]
	v_pk_fma_f32 v[168:169], v[104:105], s[44:45], v[168:169]
	v_pk_fma_f32 v[170:171], v[106:107], s[44:45], v[170:171]
	v_pk_fma_f32 v[172:173], v[108:109], s[44:45], v[172:173]
	v_pk_fma_f32 v[174:175], v[110:111], s[44:45], v[174:175]
	v_pk_add_f32 v[176:177], v[160:161], v[162:163]
	v_pk_add_f32 v[176:177], v[176:177], v[164:165]
	v_pk_add_f32 v[176:177], v[176:177], v[166:167]
	v_pk_add_f32 v[176:177], v[176:177], v[168:169]
	v_pk_add_f32 v[176:177], v[176:177], v[170:171]
	v_pk_add_f32 v[176:177], v[176:177], v[172:173]
	v_pk_add_f32 v[176:177], v[176:177], v[174:175]
	v_add_f32_e32 v194, v176, v177
	s_nop 1
	v_add_f32_dpp v192, v194, v194 quad_perm:[1,0,3,2] row_mask:0xf bank_mask:0xf
	s_nop 1
	v_add_f32_dpp v192, v192, v192 quad_perm:[2,3,0,1] row_mask:0xf bank_mask:0xf
	s_nop 1
	v_add_f32_dpp v192, v192, v192 row_half_mirror row_mask:0xf bank_mask:0xf
	s_nop 1
	v_add_f32_dpp v192, v192, v192 row_mirror row_mask:0xf bank_mask:0xf
	s_nop 1
	v_add_f32_dpp v192, v192, v192 row_bcast:15 row_mask:0xa bank_mask:0xf
	s_nop 1
	v_add_f32_dpp v192, v192, v192 row_bcast:31 row_mask:0xc bank_mask:0xf
	s_nop 1
	v_readlane_b32 s42, v192, 63
	s_nop 3
	s_mov_b32 s43, s42
	v_pk_fma_f32 v[160:161], s[42:43], v[196:197], v[160:161]
	v_pk_fma_f32 v[162:163], s[42:43], v[196:197], v[162:163]
	v_pk_fma_f32 v[164:165], s[42:43], v[196:197], v[164:165]
	v_pk_fma_f32 v[166:167], s[42:43], v[196:197], v[166:167]
	v_pk_fma_f32 v[168:169], s[42:43], v[196:197], v[168:169]
	v_pk_fma_f32 v[170:171], s[42:43], v[196:197], v[170:171]
	v_pk_fma_f32 v[172:173], s[42:43], v[196:197], v[172:173]
	v_pk_fma_f32 v[174:175], s[42:43], v[196:197], v[174:175]
	v_pk_mul_f32 v[176:177], v[160:161], v[160:161]
	v_pk_fma_f32 v[176:177], v[162:163], v[162:163], v[176:177]
	v_pk_fma_f32 v[176:177], v[164:165], v[164:165], v[176:177]
	v_pk_fma_f32 v[176:177], v[166:167], v[166:167], v[176:177]
	v_pk_fma_f32 v[176:177], v[168:169], v[168:169], v[176:177]
	v_pk_fma_f32 v[176:177], v[170:171], v[170:171], v[176:177]
	v_pk_fma_f32 v[176:177], v[172:173], v[172:173], v[176:177]
	v_pk_fma_f32 v[176:177], v[174:175], v[174:175], v[176:177]
	v_add_f32_e32 v194, v176, v177
	s_nop 1
	v_add_f32_dpp v192, v194, v194 quad_perm:[1,0,3,2] row_mask:0xf bank_mask:0xf
	s_nop 1
	v_add_f32_dpp v192, v192, v192 quad_perm:[2,3,0,1] row_mask:0xf bank_mask:0xf
	s_nop 1
	v_add_f32_dpp v192, v192, v192 row_half_mirror row_mask:0xf bank_mask:0xf
	s_nop 1
	v_add_f32_dpp v192, v192, v192 row_mirror row_mask:0xf bank_mask:0xf
	s_nop 1
	v_add_f32_dpp v192, v192, v192 row_bcast:15 row_mask:0xa bank_mask:0xf
	s_nop 1
	v_add_f32_dpp v192, v192, v192 row_bcast:31 row_mask:0xc bank_mask:0xf
	s_nop 1
	v_readlane_b32 s42, v192, 63
	s_nop 3
	v_fma_f32 v198, s42, v202, v203
	v_rsq_f32_e32 v198, v198
	s_nop 0
	v_pk_mul_f32 v[160:161], v[160:161], v[198:199] op_sel_hi:[1,0]
	v_pk_mul_f32 v[162:163], v[162:163], v[198:199] op_sel_hi:[1,0]
	v_pk_mul_f32 v[164:165], v[164:165], v[198:199] op_sel_hi:[1,0]
	v_pk_mul_f32 v[166:167], v[166:167], v[198:199] op_sel_hi:[1,0]
	v_pk_mul_f32 v[168:169], v[168:169], v[198:199] op_sel_hi:[1,0]
	v_pk_mul_f32 v[170:171], v[170:171], v[198:199] op_sel_hi:[1,0]
	v_pk_mul_f32 v[172:173], v[172:173], v[198:199] op_sel_hi:[1,0]
	v_pk_mul_f32 v[174:175], v[174:175], v[198:199] op_sel_hi:[1,0]
	v_pk_fma_f32 v[160:161], v[160:161], v[0:1], v[16:17]
	v_pk_fma_f32 v[162:163], v[162:163], v[2:3], v[18:19]
	v_pk_fma_f32 v[164:165], v[164:165], v[4:5], v[20:21]
	v_pk_fma_f32 v[166:167], v[166:167], v[6:7], v[22:23]
	v_pk_fma_f32 v[168:169], v[168:169], v[8:9], v[24:25]
	v_pk_fma_f32 v[170:171], v[170:171], v[10:11], v[26:27]
	v_pk_fma_f32 v[172:173], v[172:173], v[12:13], v[28:29]
	v_pk_fma_f32 v[174:175], v[174:175], v[14:15], v[30:31]
	global_store_dwordx4 v200, v[160:163], s[8:9] offset:0
	global_store_dwordx4 v200, v[164:167], s[8:9] offset:1024
	global_store_dwordx4 v200, v[168:171], s[8:9] offset:2048
	global_store_dwordx4 v200, v[172:175], s[8:9] offset:3072
	v_pk_add_f32 v[176:177], v[160:161], v[162:163]
	v_pk_add_f32 v[176:177], v[176:177], v[164:165]
	v_pk_add_f32 v[176:177], v[176:177], v[166:167]
	v_pk_add_f32 v[176:177], v[176:177], v[168:169]
	v_pk_add_f32 v[176:177], v[176:177], v[170:171]
	v_pk_add_f32 v[176:177], v[176:177], v[172:173]
	v_pk_add_f32 v[176:177], v[176:177], v[174:175]
	v_add_f32_e32 v194, v176, v177
	s_nop 1
	v_add_f32_dpp v192, v194, v194 quad_perm:[1,0,3,2] row_mask:0xf bank_mask:0xf
	s_nop 1
	v_add_f32_dpp v192, v192, v192 quad_perm:[2,3,0,1] row_mask:0xf bank_mask:0xf
	s_nop 1
	v_add_f32_dpp v192, v192, v192 row_half_mirror row_mask:0xf bank_mask:0xf
	s_nop 1
	v_add_f32_dpp v192, v192, v192 row_mirror row_mask:0xf bank_mask:0xf
	s_nop 1
	v_add_f32_dpp v192, v192, v192 row_bcast:15 row_mask:0xa bank_mask:0xf
	s_nop 1
	v_add_f32_dpp v192, v192, v192 row_bcast:31 row_mask:0xc bank_mask:0xf
	s_nop 1
	v_readlane_b32 s42, v192, 63
	s_nop 3
	s_mov_b32 s43, s42
	v_pk_fma_f32 v[160:161], s[42:43], v[196:197], v[160:161]
	v_pk_fma_f32 v[162:163], s[42:43], v[196:197], v[162:163]
	v_pk_fma_f32 v[164:165], s[42:43], v[196:197], v[164:165]
	v_pk_fma_f32 v[166:167], s[42:43], v[196:197], v[166:167]
	v_pk_fma_f32 v[168:169], s[42:43], v[196:197], v[168:169]
	v_pk_fma_f32 v[170:171], s[42:43], v[196:197], v[170:171]
	v_pk_fma_f32 v[172:173], s[42:43], v[196:197], v[172:173]
	v_pk_fma_f32 v[174:175], s[42:43], v[196:197], v[174:175]
	v_pk_mul_f32 v[176:177], v[160:161], v[160:161]
	v_pk_fma_f32 v[176:177], v[162:163], v[162:163], v[176:177]
	v_pk_fma_f32 v[176:177], v[164:165], v[164:165], v[176:177]
	v_pk_fma_f32 v[176:177], v[166:167], v[166:167], v[176:177]
	v_pk_fma_f32 v[176:177], v[168:169], v[168:169], v[176:177]
	v_pk_fma_f32 v[176:177], v[170:171], v[170:171], v[176:177]
	v_pk_fma_f32 v[176:177], v[172:173], v[172:173], v[176:177]
	v_pk_fma_f32 v[176:177], v[174:175], v[174:175], v[176:177]
	v_add_f32_e32 v194, v176, v177
	s_nop 1
	v_add_f32_dpp v192, v194, v194 quad_perm:[1,0,3,2] row_mask:0xf bank_mask:0xf
	s_nop 1
	v_add_f32_dpp v192, v192, v192 quad_perm:[2,3,0,1] row_mask:0xf bank_mask:0xf
	s_nop 1
	v_add_f32_dpp v192, v192, v192 row_half_mirror row_mask:0xf bank_mask:0xf
	s_nop 1
	v_add_f32_dpp v192, v192, v192 row_mirror row_mask:0xf bank_mask:0xf
	s_nop 1
	v_add_f32_dpp v192, v192, v192 row_bcast:15 row_mask:0xa bank_mask:0xf
	s_nop 1
	v_add_f32_dpp v192, v192, v192 row_bcast:31 row_mask:0xc bank_mask:0xf
	s_nop 1
	v_readlane_b32 s42, v192, 63
	s_nop 3
	v_fma_f32 v198, s42, v202, v203
	v_rsq_f32_e32 v198, v198
	s_nop 0
	v_pk_mul_f32 v[160:161], v[160:161], v[198:199] op_sel_hi:[1,0]
	v_pk_mul_f32 v[162:163], v[162:163], v[198:199] op_sel_hi:[1,0]
	v_pk_mul_f32 v[164:165], v[164:165], v[198:199] op_sel_hi:[1,0]
	v_pk_mul_f32 v[166:167], v[166:167], v[198:199] op_sel_hi:[1,0]
	v_pk_mul_f32 v[168:169], v[168:169], v[198:199] op_sel_hi:[1,0]
	v_pk_mul_f32 v[170:171], v[170:171], v[198:199] op_sel_hi:[1,0]
	v_pk_mul_f32 v[172:173], v[172:173], v[198:199] op_sel_hi:[1,0]
	v_pk_mul_f32 v[174:175], v[174:175], v[198:199] op_sel_hi:[1,0]
	v_pk_fma_f32 v[160:161], v[160:161], v[32:33], v[48:49]
	v_pk_fma_f32 v[162:163], v[162:163], v[34:35], v[50:51]
	v_pk_fma_f32 v[164:165], v[164:165], v[36:37], v[52:53]
	v_pk_fma_f32 v[166:167], v[166:167], v[38:39], v[54:55]
	v_pk_fma_f32 v[168:169], v[168:169], v[40:41], v[56:57]
	v_pk_fma_f32 v[170:171], v[170:171], v[42:43], v[58:59]
	v_pk_fma_f32 v[172:173], v[172:173], v[44:45], v[60:61]
	v_pk_fma_f32 v[174:175], v[174:175], v[46:47], v[62:63]
	v_cvt_pk_bf16_f32 v176, v160, v161
	v_cvt_pk_bf16_f32 v177, v162, v163
	v_cvt_pk_bf16_f32 v178, v164, v165
	v_cvt_pk_bf16_f32 v179, v166, v167
	v_cvt_pk_bf16_f32 v180, v168, v169
	v_cvt_pk_bf16_f32 v181, v170, v171
	v_cvt_pk_bf16_f32 v182, v172, v173
	v_cvt_pk_bf16_f32 v183, v174, v175
	global_store_dwordx2 v201, v[176:177], s[12:13] offset:0
	global_store_dwordx2 v201, v[178:179], s[12:13] offset:512
	global_store_dwordx2 v201, v[180:181], s[12:13] offset:1024
	global_store_dwordx2 v201, v[182:183], s[12:13] offset:1536
	s_add_u32 s8, s8, 0x1000
	s_addc_u32 s9, s9, 0
	s_add_u32 s12, s12, 0x800
	s_addc_u32 s13, s13, 0
	global_load_dwordx4 v[96:99], v200, s[2:3] offset:0
	global_load_dwordx4 v[100:103], v200, s[2:3] offset:1024
	global_load_dwordx4 v[104:107], v200, s[2:3] offset:2048
	global_load_dwordx4 v[108:111], v200, s[2:3] offset:3072
	global_load_dwordx2 v[144:145], v201, s[6:7] offset:0
	global_load_dwordx2 v[146:147], v201, s[6:7] offset:512
	global_load_dwordx2 v[148:149], v201, s[6:7] offset:1024
	global_load_dwordx2 v[150:151], v201, s[6:7] offset:1536
	s_add_u32 s2, s2, 0x1000
	s_addc_u32 s3, s3, 0
	s_add_u32 s6, s6, 0x800
	s_addc_u32 s7, s7, 0
	s_waitcnt vmcnt(48)
	v_lshlrev_b32_e32 v160, 16, v152
	v_and_b32_e32 v161, 0xffff0000, v152
	v_lshlrev_b32_e32 v162, 16, v153
	v_and_b32_e32 v163, 0xffff0000, v153
	v_lshlrev_b32_e32 v164, 16, v154
	v_and_b32_e32 v165, 0xffff0000, v154
	v_lshlrev_b32_e32 v166, 16, v155
	v_and_b32_e32 v167, 0xffff0000, v155
	v_lshlrev_b32_e32 v168, 16, v156
	v_and_b32_e32 v169, 0xffff0000, v156
	v_lshlrev_b32_e32 v170, 16, v157
	v_and_b32_e32 v171, 0xffff0000, v157
	v_lshlrev_b32_e32 v172, 16, v158
	v_and_b32_e32 v173, 0xffff0000, v158
	v_lshlrev_b32_e32 v174, 16, v159
	v_and_b32_e32 v175, 0xffff0000, v159
	v_pk_fma_f32 v[160:161], v[112:113], s[44:45], v[160:161]
	v_pk_fma_f32 v[162:163], v[114:115], s[44:45], v[162:163]
	v_pk_fma_f32 v[164:165], v[116:117], s[44:45], v[164:165]
	v_pk_fma_f32 v[166:167], v[118:119], s[44:45], v[166:167]
	v_pk_fma_f32 v[168:169], v[120:121], s[44:45], v[168:169]
	v_pk_fma_f32 v[170:171], v[122:123], s[44:45], v[170:171]
	v_pk_fma_f32 v[172:173], v[124:125], s[44:45], v[172:173]
	v_pk_fma_f32 v[174:175], v[126:127], s[44:45], v[174:175]
	v_pk_add_f32 v[176:177], v[160:161], v[162:163]
	v_pk_add_f32 v[176:177], v[176:177], v[164:165]
	v_pk_add_f32 v[176:177], v[176:177], v[166:167]
	v_pk_add_f32 v[176:177], v[176:177], v[168:169]
	v_pk_add_f32 v[176:177], v[176:177], v[170:171]
	v_pk_add_f32 v[176:177], v[176:177], v[172:173]
	v_pk_add_f32 v[176:177], v[176:177], v[174:175]
	v_add_f32_e32 v194, v176, v177
	s_nop 1
	v_add_f32_dpp v192, v194, v194 quad_perm:[1,0,3,2] row_mask:0xf bank_mask:0xf
	s_nop 1
	v_add_f32_dpp v192, v192, v192 quad_perm:[2,3,0,1] row_mask:0xf bank_mask:0xf
	s_nop 1
	v_add_f32_dpp v192, v192, v192 row_half_mirror row_mask:0xf bank_mask:0xf
	s_nop 1
	v_add_f32_dpp v192, v192, v192 row_mirror row_mask:0xf bank_mask:0xf
	s_nop 1
	v_add_f32_dpp v192, v192, v192 row_bcast:15 row_mask:0xa bank_mask:0xf
	s_nop 1
	v_add_f32_dpp v192, v192, v192 row_bcast:31 row_mask:0xc bank_mask:0xf
	s_nop 1
	v_readlane_b32 s42, v192, 63
	s_nop 3
	s_mov_b32 s43, s42
	v_pk_fma_f32 v[160:161], s[42:43], v[196:197], v[160:161]
	v_pk_fma_f32 v[162:163], s[42:43], v[196:197], v[162:163]
	v_pk_fma_f32 v[164:165], s[42:43], v[196:197], v[164:165]
	v_pk_fma_f32 v[166:167], s[42:43], v[196:197], v[166:167]
	v_pk_fma_f32 v[168:169], s[42:43], v[196:197], v[168:169]
	v_pk_fma_f32 v[170:171], s[42:43], v[196:197], v[170:171]
	v_pk_fma_f32 v[172:173], s[42:43], v[196:197], v[172:173]
	v_pk_fma_f32 v[174:175], s[42:43], v[196:197], v[174:175]
	v_pk_mul_f32 v[176:177], v[160:161], v[160:161]
	v_pk_fma_f32 v[176:177], v[162:163], v[162:163], v[176:177]
	v_pk_fma_f32 v[176:177], v[164:165], v[164:165], v[176:177]
	v_pk_fma_f32 v[176:177], v[166:167], v[166:167], v[176:177]
	v_pk_fma_f32 v[176:177], v[168:169], v[168:169], v[176:177]
	v_pk_fma_f32 v[176:177], v[170:171], v[170:171], v[176:177]
	v_pk_fma_f32 v[176:177], v[172:173], v[172:173], v[176:177]
	v_pk_fma_f32 v[176:177], v[174:175], v[174:175], v[176:177]
	v_add_f32_e32 v194, v176, v177
	s_nop 1
	v_add_f32_dpp v192, v194, v194 quad_perm:[1,0,3,2] row_mask:0xf bank_mask:0xf
	s_nop 1
	v_add_f32_dpp v192, v192, v192 quad_perm:[2,3,0,1] row_mask:0xf bank_mask:0xf
	s_nop 1
	v_add_f32_dpp v192, v192, v192 row_half_mirror row_mask:0xf bank_mask:0xf
	s_nop 1
	v_add_f32_dpp v192, v192, v192 row_mirror row_mask:0xf bank_mask:0xf
	s_nop 1
	v_add_f32_dpp v192, v192, v192 row_bcast:15 row_mask:0xa bank_mask:0xf
	s_nop 1
	v_add_f32_dpp v192, v192, v192 row_bcast:31 row_mask:0xc bank_mask:0xf
	s_nop 1
	v_readlane_b32 s42, v192, 63
	s_nop 3
	v_fma_f32 v198, s42, v202, v203
	v_rsq_f32_e32 v198, v198
	s_nop 0
	v_pk_mul_f32 v[160:161], v[160:161], v[198:199] op_sel_hi:[1,0]
	v_pk_mul_f32 v[162:163], v[162:163], v[198:199] op_sel_hi:[1,0]
	v_pk_mul_f32 v[164:165], v[164:165], v[198:199] op_sel_hi:[1,0]
	v_pk_mul_f32 v[166:167], v[166:167], v[198:199] op_sel_hi:[1,0]
	v_pk_mul_f32 v[168:169], v[168:169], v[198:199] op_sel_hi:[1,0]
	v_pk_mul_f32 v[170:171], v[170:171], v[198:199] op_sel_hi:[1,0]
	v_pk_mul_f32 v[172:173], v[172:173], v[198:199] op_sel_hi:[1,0]
	v_pk_mul_f32 v[174:175], v[174:175], v[198:199] op_sel_hi:[1,0]
	v_pk_fma_f32 v[160:161], v[160:161], v[0:1], v[16:17]
	v_pk_fma_f32 v[162:163], v[162:163], v[2:3], v[18:19]
	v_pk_fma_f32 v[164:165], v[164:165], v[4:5], v[20:21]
	v_pk_fma_f32 v[166:167], v[166:167], v[6:7], v[22:23]
	v_pk_fma_f32 v[168:169], v[168:169], v[8:9], v[24:25]
	v_pk_fma_f32 v[170:171], v[170:171], v[10:11], v[26:27]
	v_pk_fma_f32 v[172:173], v[172:173], v[12:13], v[28:29]
	v_pk_fma_f32 v[174:175], v[174:175], v[14:15], v[30:31]
	global_store_dwordx4 v200, v[160:163], s[8:9] offset:0
	global_store_dwordx4 v200, v[164:167], s[8:9] offset:1024
	global_store_dwordx4 v200, v[168:171], s[8:9] offset:2048
	global_store_dwordx4 v200, v[172:175], s[8:9] offset:3072
	v_pk_add_f32 v[176:177], v[160:161], v[162:163]
	v_pk_add_f32 v[176:177], v[176:177], v[164:165]
	v_pk_add_f32 v[176:177], v[176:177], v[166:167]
	v_pk_add_f32 v[176:177], v[176:177], v[168:169]
	v_pk_add_f32 v[176:177], v[176:177], v[170:171]
	v_pk_add_f32 v[176:177], v[176:177], v[172:173]
	v_pk_add_f32 v[176:177], v[176:177], v[174:175]
	v_add_f32_e32 v194, v176, v177
	s_nop 1
	v_add_f32_dpp v192, v194, v194 quad_perm:[1,0,3,2] row_mask:0xf bank_mask:0xf
	s_nop 1
	v_add_f32_dpp v192, v192, v192 quad_perm:[2,3,0,1] row_mask:0xf bank_mask:0xf
	s_nop 1
	v_add_f32_dpp v192, v192, v192 row_half_mirror row_mask:0xf bank_mask:0xf
	s_nop 1
	v_add_f32_dpp v192, v192, v192 row_mirror row_mask:0xf bank_mask:0xf
	s_nop 1
	v_add_f32_dpp v192, v192, v192 row_bcast:15 row_mask:0xa bank_mask:0xf
	s_nop 1
	v_add_f32_dpp v192, v192, v192 row_bcast:31 row_mask:0xc bank_mask:0xf
	s_nop 1
	v_readlane_b32 s42, v192, 63
	s_nop 3
	s_mov_b32 s43, s42
	v_pk_fma_f32 v[160:161], s[42:43], v[196:197], v[160:161]
	v_pk_fma_f32 v[162:163], s[42:43], v[196:197], v[162:163]
	v_pk_fma_f32 v[164:165], s[42:43], v[196:197], v[164:165]
	v_pk_fma_f32 v[166:167], s[42:43], v[196:197], v[166:167]
	v_pk_fma_f32 v[168:169], s[42:43], v[196:197], v[168:169]
	v_pk_fma_f32 v[170:171], s[42:43], v[196:197], v[170:171]
	v_pk_fma_f32 v[172:173], s[42:43], v[196:197], v[172:173]
	v_pk_fma_f32 v[174:175], s[42:43], v[196:197], v[174:175]
	v_pk_mul_f32 v[176:177], v[160:161], v[160:161]
	v_pk_fma_f32 v[176:177], v[162:163], v[162:163], v[176:177]
	v_pk_fma_f32 v[176:177], v[164:165], v[164:165], v[176:177]
	v_pk_fma_f32 v[176:177], v[166:167], v[166:167], v[176:177]
	v_pk_fma_f32 v[176:177], v[168:169], v[168:169], v[176:177]
	v_pk_fma_f32 v[176:177], v[170:171], v[170:171], v[176:177]
	v_pk_fma_f32 v[176:177], v[172:173], v[172:173], v[176:177]
	v_pk_fma_f32 v[176:177], v[174:175], v[174:175], v[176:177]
	v_add_f32_e32 v194, v176, v177
	s_nop 1
	v_add_f32_dpp v192, v194, v194 quad_perm:[1,0,3,2] row_mask:0xf bank_mask:0xf
	s_nop 1
	v_add_f32_dpp v192, v192, v192 quad_perm:[2,3,0,1] row_mask:0xf bank_mask:0xf
	s_nop 1
	v_add_f32_dpp v192, v192, v192 row_half_mirror row_mask:0xf bank_mask:0xf
	s_nop 1
	v_add_f32_dpp v192, v192, v192 row_mirror row_mask:0xf bank_mask:0xf
	s_nop 1
	v_add_f32_dpp v192, v192, v192 row_bcast:15 row_mask:0xa bank_mask:0xf
	s_nop 1
	v_add_f32_dpp v192, v192, v192 row_bcast:31 row_mask:0xc bank_mask:0xf
	s_nop 1
	v_readlane_b32 s42, v192, 63
	s_nop 3
	v_fma_f32 v198, s42, v202, v203
	v_rsq_f32_e32 v198, v198
	s_nop 0
	v_pk_mul_f32 v[160:161], v[160:161], v[198:199] op_sel_hi:[1,0]
	v_pk_mul_f32 v[162:163], v[162:163], v[198:199] op_sel_hi:[1,0]
	v_pk_mul_f32 v[164:165], v[164:165], v[198:199] op_sel_hi:[1,0]
	v_pk_mul_f32 v[166:167], v[166:167], v[198:199] op_sel_hi:[1,0]
	v_pk_mul_f32 v[168:169], v[168:169], v[198:199] op_sel_hi:[1,0]
	v_pk_mul_f32 v[170:171], v[170:171], v[198:199] op_sel_hi:[1,0]
	v_pk_mul_f32 v[172:173], v[172:173], v[198:199] op_sel_hi:[1,0]
	v_pk_mul_f32 v[174:175], v[174:175], v[198:199] op_sel_hi:[1,0]
	v_pk_fma_f32 v[160:161], v[160:161], v[32:33], v[48:49]
	v_pk_fma_f32 v[162:163], v[162:163], v[34:35], v[50:51]
	v_pk_fma_f32 v[164:165], v[164:165], v[36:37], v[52:53]
	v_pk_fma_f32 v[166:167], v[166:167], v[38:39], v[54:55]
	v_pk_fma_f32 v[168:169], v[168:169], v[40:41], v[56:57]
	v_pk_fma_f32 v[170:171], v[170:171], v[42:43], v[58:59]
	v_pk_fma_f32 v[172:173], v[172:173], v[44:45], v[60:61]
	v_pk_fma_f32 v[174:175], v[174:175], v[46:47], v[62:63]
	v_cvt_pk_bf16_f32 v176, v160, v161
	v_cvt_pk_bf16_f32 v177, v162, v163
	v_cvt_pk_bf16_f32 v178, v164, v165
	v_cvt_pk_bf16_f32 v179, v166, v167
	v_cvt_pk_bf16_f32 v180, v168, v169
	v_cvt_pk_bf16_f32 v181, v170, v171
	v_cvt_pk_bf16_f32 v182, v172, v173
	v_cvt_pk_bf16_f32 v183, v174, v175
	global_store_dwordx2 v201, v[176:177], s[12:13] offset:0
	global_store_dwordx2 v201, v[178:179], s[12:13] offset:512
	global_store_dwordx2 v201, v[180:181], s[12:13] offset:1024
	global_store_dwordx2 v201, v[182:183], s[12:13] offset:1536
	s_add_u32 s8, s8, 0x1000
	s_addc_u32 s9, s9, 0
	s_add_u32 s12, s12, 0x800
	s_addc_u32 s13, s13, 0
	global_load_dwordx4 v[112:115], v200, s[2:3] offset:0
	global_load_dwordx4 v[116:119], v200, s[2:3] offset:1024
	global_load_dwordx4 v[120:123], v200, s[2:3] offset:2048
	global_load_dwordx4 v[124:127], v200, s[2:3] offset:3072
	global_load_dwordx2 v[152:153], v201, s[6:7] offset:0
	global_load_dwordx2 v[154:155], v201, s[6:7] offset:512
	global_load_dwordx2 v[156:157], v201, s[6:7] offset:1024
	global_load_dwordx2 v[158:159], v201, s[6:7] offset:1536
	s_add_u32 s2, s2, 0x1000
	s_addc_u32 s3, s3, 0
	s_add_u32 s6, s6, 0x800
	s_addc_u32 s7, s7, 0
	s_waitcnt vmcnt(48)
	v_lshlrev_b32_e32 v160, 16, v128
	v_and_b32_e32 v161, 0xffff0000, v128
	v_lshlrev_b32_e32 v162, 16, v129
	v_and_b32_e32 v163, 0xffff0000, v129
	v_lshlrev_b32_e32 v164, 16, v130
	v_and_b32_e32 v165, 0xffff0000, v130
	v_lshlrev_b32_e32 v166, 16, v131
	v_and_b32_e32 v167, 0xffff0000, v131
	v_lshlrev_b32_e32 v168, 16, v132
	v_and_b32_e32 v169, 0xffff0000, v132
	v_lshlrev_b32_e32 v170, 16, v133
	v_and_b32_e32 v171, 0xffff0000, v133
	v_lshlrev_b32_e32 v172, 16, v134
	v_and_b32_e32 v173, 0xffff0000, v134
	v_lshlrev_b32_e32 v174, 16, v135
	v_and_b32_e32 v175, 0xffff0000, v135
	v_pk_fma_f32 v[160:161], v[64:65], s[44:45], v[160:161]
	v_pk_fma_f32 v[162:163], v[66:67], s[44:45], v[162:163]
	v_pk_fma_f32 v[164:165], v[68:69], s[44:45], v[164:165]
	v_pk_fma_f32 v[166:167], v[70:71], s[44:45], v[166:167]
	v_pk_fma_f32 v[168:169], v[72:73], s[44:45], v[168:169]
	v_pk_fma_f32 v[170:171], v[74:75], s[44:45], v[170:171]
	v_pk_fma_f32 v[172:173], v[76:77], s[44:45], v[172:173]
	v_pk_fma_f32 v[174:175], v[78:79], s[44:45], v[174:175]
	v_pk_add_f32 v[176:177], v[160:161], v[162:163]
	v_pk_add_f32 v[176:177], v[176:177], v[164:165]
	v_pk_add_f32 v[176:177], v[176:177], v[166:167]
	v_pk_add_f32 v[176:177], v[176:177], v[168:169]
	v_pk_add_f32 v[176:177], v[176:177], v[170:171]
	v_pk_add_f32 v[176:177], v[176:177], v[172:173]
	v_pk_add_f32 v[176:177], v[176:177], v[174:175]
	v_add_f32_e32 v194, v176, v177
	s_nop 1
	v_add_f32_dpp v192, v194, v194 quad_perm:[1,0,3,2] row_mask:0xf bank_mask:0xf
	s_nop 1
	v_add_f32_dpp v192, v192, v192 quad_perm:[2,3,0,1] row_mask:0xf bank_mask:0xf
	s_nop 1
	v_add_f32_dpp v192, v192, v192 row_half_mirror row_mask:0xf bank_mask:0xf
	s_nop 1
	v_add_f32_dpp v192, v192, v192 row_mirror row_mask:0xf bank_mask:0xf
	s_nop 1
	v_add_f32_dpp v192, v192, v192 row_bcast:15 row_mask:0xa bank_mask:0xf
	s_nop 1
	v_add_f32_dpp v192, v192, v192 row_bcast:31 row_mask:0xc bank_mask:0xf
	s_nop 1
	v_readlane_b32 s42, v192, 63
	s_nop 3
	s_mov_b32 s43, s42
	v_pk_fma_f32 v[160:161], s[42:43], v[196:197], v[160:161]
	v_pk_fma_f32 v[162:163], s[42:43], v[196:197], v[162:163]
	v_pk_fma_f32 v[164:165], s[42:43], v[196:197], v[164:165]
	v_pk_fma_f32 v[166:167], s[42:43], v[196:197], v[166:167]
	v_pk_fma_f32 v[168:169], s[42:43], v[196:197], v[168:169]
	v_pk_fma_f32 v[170:171], s[42:43], v[196:197], v[170:171]
	v_pk_fma_f32 v[172:173], s[42:43], v[196:197], v[172:173]
	v_pk_fma_f32 v[174:175], s[42:43], v[196:197], v[174:175]
	v_pk_mul_f32 v[176:177], v[160:161], v[160:161]
	v_pk_fma_f32 v[176:177], v[162:163], v[162:163], v[176:177]
	v_pk_fma_f32 v[176:177], v[164:165], v[164:165], v[176:177]
	v_pk_fma_f32 v[176:177], v[166:167], v[166:167], v[176:177]
	v_pk_fma_f32 v[176:177], v[168:169], v[168:169], v[176:177]
	v_pk_fma_f32 v[176:177], v[170:171], v[170:171], v[176:177]
	v_pk_fma_f32 v[176:177], v[172:173], v[172:173], v[176:177]
	v_pk_fma_f32 v[176:177], v[174:175], v[174:175], v[176:177]
	v_add_f32_e32 v194, v176, v177
	s_nop 1
	v_add_f32_dpp v192, v194, v194 quad_perm:[1,0,3,2] row_mask:0xf bank_mask:0xf
	s_nop 1
	v_add_f32_dpp v192, v192, v192 quad_perm:[2,3,0,1] row_mask:0xf bank_mask:0xf
	s_nop 1
	v_add_f32_dpp v192, v192, v192 row_half_mirror row_mask:0xf bank_mask:0xf
	s_nop 1
	v_add_f32_dpp v192, v192, v192 row_mirror row_mask:0xf bank_mask:0xf
	s_nop 1
	v_add_f32_dpp v192, v192, v192 row_bcast:15 row_mask:0xa bank_mask:0xf
	s_nop 1
	v_add_f32_dpp v192, v192, v192 row_bcast:31 row_mask:0xc bank_mask:0xf
	s_nop 1
	v_readlane_b32 s42, v192, 63
	s_nop 3
	v_fma_f32 v198, s42, v202, v203
	v_rsq_f32_e32 v198, v198
	s_nop 0
	v_pk_mul_f32 v[160:161], v[160:161], v[198:199] op_sel_hi:[1,0]
	v_pk_mul_f32 v[162:163], v[162:163], v[198:199] op_sel_hi:[1,0]
	v_pk_mul_f32 v[164:165], v[164:165], v[198:199] op_sel_hi:[1,0]
	v_pk_mul_f32 v[166:167], v[166:167], v[198:199] op_sel_hi:[1,0]
	v_pk_mul_f32 v[168:169], v[168:169], v[198:199] op_sel_hi:[1,0]
	v_pk_mul_f32 v[170:171], v[170:171], v[198:199] op_sel_hi:[1,0]
	v_pk_mul_f32 v[172:173], v[172:173], v[198:199] op_sel_hi:[1,0]
	v_pk_mul_f32 v[174:175], v[174:175], v[198:199] op_sel_hi:[1,0]
	v_pk_fma_f32 v[160:161], v[160:161], v[0:1], v[16:17]
	v_pk_fma_f32 v[162:163], v[162:163], v[2:3], v[18:19]
	v_pk_fma_f32 v[164:165], v[164:165], v[4:5], v[20:21]
	v_pk_fma_f32 v[166:167], v[166:167], v[6:7], v[22:23]
	v_pk_fma_f32 v[168:169], v[168:169], v[8:9], v[24:25]
	v_pk_fma_f32 v[170:171], v[170:171], v[10:11], v[26:27]
	v_pk_fma_f32 v[172:173], v[172:173], v[12:13], v[28:29]
	v_pk_fma_f32 v[174:175], v[174:175], v[14:15], v[30:31]
	global_store_dwordx4 v200, v[160:163], s[8:9] offset:0
	global_store_dwordx4 v200, v[164:167], s[8:9] offset:1024
	global_store_dwordx4 v200, v[168:171], s[8:9] offset:2048
	global_store_dwordx4 v200, v[172:175], s[8:9] offset:3072
	v_pk_add_f32 v[176:177], v[160:161], v[162:163]
	v_pk_add_f32 v[176:177], v[176:177], v[164:165]
	v_pk_add_f32 v[176:177], v[176:177], v[166:167]
	v_pk_add_f32 v[176:177], v[176:177], v[168:169]
	v_pk_add_f32 v[176:177], v[176:177], v[170:171]
	v_pk_add_f32 v[176:177], v[176:177], v[172:173]
	v_pk_add_f32 v[176:177], v[176:177], v[174:175]
	v_add_f32_e32 v194, v176, v177
	s_nop 1
	v_add_f32_dpp v192, v194, v194 quad_perm:[1,0,3,2] row_mask:0xf bank_mask:0xf
	s_nop 1
	v_add_f32_dpp v192, v192, v192 quad_perm:[2,3,0,1] row_mask:0xf bank_mask:0xf
	s_nop 1
	v_add_f32_dpp v192, v192, v192 row_half_mirror row_mask:0xf bank_mask:0xf
	s_nop 1
	v_add_f32_dpp v192, v192, v192 row_mirror row_mask:0xf bank_mask:0xf
	s_nop 1
	v_add_f32_dpp v192, v192, v192 row_bcast:15 row_mask:0xa bank_mask:0xf
	s_nop 1
	v_add_f32_dpp v192, v192, v192 row_bcast:31 row_mask:0xc bank_mask:0xf
	s_nop 1
	v_readlane_b32 s42, v192, 63
	s_nop 3
	s_mov_b32 s43, s42
	v_pk_fma_f32 v[160:161], s[42:43], v[196:197], v[160:161]
	v_pk_fma_f32 v[162:163], s[42:43], v[196:197], v[162:163]
	v_pk_fma_f32 v[164:165], s[42:43], v[196:197], v[164:165]
	v_pk_fma_f32 v[166:167], s[42:43], v[196:197], v[166:167]
	v_pk_fma_f32 v[168:169], s[42:43], v[196:197], v[168:169]
	v_pk_fma_f32 v[170:171], s[42:43], v[196:197], v[170:171]
	v_pk_fma_f32 v[172:173], s[42:43], v[196:197], v[172:173]
	v_pk_fma_f32 v[174:175], s[42:43], v[196:197], v[174:175]
	v_pk_mul_f32 v[176:177], v[160:161], v[160:161]
	v_pk_fma_f32 v[176:177], v[162:163], v[162:163], v[176:177]
	v_pk_fma_f32 v[176:177], v[164:165], v[164:165], v[176:177]
	v_pk_fma_f32 v[176:177], v[166:167], v[166:167], v[176:177]
	v_pk_fma_f32 v[176:177], v[168:169], v[168:169], v[176:177]
	v_pk_fma_f32 v[176:177], v[170:171], v[170:171], v[176:177]
	v_pk_fma_f32 v[176:177], v[172:173], v[172:173], v[176:177]
	v_pk_fma_f32 v[176:177], v[174:175], v[174:175], v[176:177]
	v_add_f32_e32 v194, v176, v177
	s_nop 1
	v_add_f32_dpp v192, v194, v194 quad_perm:[1,0,3,2] row_mask:0xf bank_mask:0xf
	s_nop 1
	v_add_f32_dpp v192, v192, v192 quad_perm:[2,3,0,1] row_mask:0xf bank_mask:0xf
	s_nop 1
	v_add_f32_dpp v192, v192, v192 row_half_mirror row_mask:0xf bank_mask:0xf
	s_nop 1
	v_add_f32_dpp v192, v192, v192 row_mirror row_mask:0xf bank_mask:0xf
	s_nop 1
	v_add_f32_dpp v192, v192, v192 row_bcast:15 row_mask:0xa bank_mask:0xf
	s_nop 1
	v_add_f32_dpp v192, v192, v192 row_bcast:31 row_mask:0xc bank_mask:0xf
	s_nop 1
	v_readlane_b32 s42, v192, 63
	s_nop 3
	v_fma_f32 v198, s42, v202, v203
	v_rsq_f32_e32 v198, v198
	s_nop 0
	v_pk_mul_f32 v[160:161], v[160:161], v[198:199] op_sel_hi:[1,0]
	v_pk_mul_f32 v[162:163], v[162:163], v[198:199] op_sel_hi:[1,0]
	v_pk_mul_f32 v[164:165], v[164:165], v[198:199] op_sel_hi:[1,0]
	v_pk_mul_f32 v[166:167], v[166:167], v[198:199] op_sel_hi:[1,0]
	v_pk_mul_f32 v[168:169], v[168:169], v[198:199] op_sel_hi:[1,0]
	v_pk_mul_f32 v[170:171], v[170:171], v[198:199] op_sel_hi:[1,0]
	v_pk_mul_f32 v[172:173], v[172:173], v[198:199] op_sel_hi:[1,0]
	v_pk_mul_f32 v[174:175], v[174:175], v[198:199] op_sel_hi:[1,0]
	v_pk_fma_f32 v[160:161], v[160:161], v[32:33], v[48:49]
	v_pk_fma_f32 v[162:163], v[162:163], v[34:35], v[50:51]
	v_pk_fma_f32 v[164:165], v[164:165], v[36:37], v[52:53]
	v_pk_fma_f32 v[166:167], v[166:167], v[38:39], v[54:55]
	v_pk_fma_f32 v[168:169], v[168:169], v[40:41], v[56:57]
	v_pk_fma_f32 v[170:171], v[170:171], v[42:43], v[58:59]
	v_pk_fma_f32 v[172:173], v[172:173], v[44:45], v[60:61]
	v_pk_fma_f32 v[174:175], v[174:175], v[46:47], v[62:63]
	v_cvt_pk_bf16_f32 v176, v160, v161
	v_cvt_pk_bf16_f32 v177, v162, v163
	v_cvt_pk_bf16_f32 v178, v164, v165
	v_cvt_pk_bf16_f32 v179, v166, v167
	v_cvt_pk_bf16_f32 v180, v168, v169
	v_cvt_pk_bf16_f32 v181, v170, v171
	v_cvt_pk_bf16_f32 v182, v172, v173
	v_cvt_pk_bf16_f32 v183, v174, v175
	global_store_dwordx2 v201, v[176:177], s[12:13] offset:0
	global_store_dwordx2 v201, v[178:179], s[12:13] offset:512
	global_store_dwordx2 v201, v[180:181], s[12:13] offset:1024
	global_store_dwordx2 v201, v[182:183], s[12:13] offset:1536
	s_add_u32 s8, s8, 0x1000
	s_addc_u32 s9, s9, 0
	s_add_u32 s12, s12, 0x800
	s_addc_u32 s13, s13, 0
	global_load_dwordx4 v[64:67], v200, s[2:3] offset:0
	global_load_dwordx4 v[68:71], v200, s[2:3] offset:1024
	global_load_dwordx4 v[72:75], v200, s[2:3] offset:2048
	global_load_dwordx4 v[76:79], v200, s[2:3] offset:3072
	global_load_dwordx2 v[128:129], v201, s[6:7] offset:0
	global_load_dwordx2 v[130:131], v201, s[6:7] offset:512
	global_load_dwordx2 v[132:133], v201, s[6:7] offset:1024
	global_load_dwordx2 v[134:135], v201, s[6:7] offset:1536
	s_add_u32 s2, s2, 0x1000
	s_addc_u32 s3, s3, 0
	s_add_u32 s6, s6, 0x800
	s_addc_u32 s7, s7, 0
	s_waitcnt vmcnt(48)
	v_lshlrev_b32_e32 v160, 16, v136
	v_and_b32_e32 v161, 0xffff0000, v136
	v_lshlrev_b32_e32 v162, 16, v137
	v_and_b32_e32 v163, 0xffff0000, v137
	v_lshlrev_b32_e32 v164, 16, v138
	v_and_b32_e32 v165, 0xffff0000, v138
	v_lshlrev_b32_e32 v166, 16, v139
	v_and_b32_e32 v167, 0xffff0000, v139
	v_lshlrev_b32_e32 v168, 16, v140
	v_and_b32_e32 v169, 0xffff0000, v140
	v_lshlrev_b32_e32 v170, 16, v141
	v_and_b32_e32 v171, 0xffff0000, v141
	v_lshlrev_b32_e32 v172, 16, v142
	v_and_b32_e32 v173, 0xffff0000, v142
	v_lshlrev_b32_e32 v174, 16, v143
	v_and_b32_e32 v175, 0xffff0000, v143
	v_pk_fma_f32 v[160:161], v[80:81], s[44:45], v[160:161]
	v_pk_fma_f32 v[162:163], v[82:83], s[44:45], v[162:163]
	v_pk_fma_f32 v[164:165], v[84:85], s[44:45], v[164:165]
	v_pk_fma_f32 v[166:167], v[86:87], s[44:45], v[166:167]
	v_pk_fma_f32 v[168:169], v[88:89], s[44:45], v[168:169]
	v_pk_fma_f32 v[170:171], v[90:91], s[44:45], v[170:171]
	v_pk_fma_f32 v[172:173], v[92:93], s[44:45], v[172:173]
	v_pk_fma_f32 v[174:175], v[94:95], s[44:45], v[174:175]
	v_pk_add_f32 v[176:177], v[160:161], v[162:163]
	v_pk_add_f32 v[176:177], v[176:177], v[164:165]
	v_pk_add_f32 v[176:177], v[176:177], v[166:167]
	v_pk_add_f32 v[176:177], v[176:177], v[168:169]
	v_pk_add_f32 v[176:177], v[176:177], v[170:171]
	v_pk_add_f32 v[176:177], v[176:177], v[172:173]
	v_pk_add_f32 v[176:177], v[176:177], v[174:175]
	v_add_f32_e32 v194, v176, v177
	s_nop 1
	v_add_f32_dpp v192, v194, v194 quad_perm:[1,0,3,2] row_mask:0xf bank_mask:0xf
	s_nop 1
	v_add_f32_dpp v192, v192, v192 quad_perm:[2,3,0,1] row_mask:0xf bank_mask:0xf
	s_nop 1
	v_add_f32_dpp v192, v192, v192 row_half_mirror row_mask:0xf bank_mask:0xf
	s_nop 1
	v_add_f32_dpp v192, v192, v192 row_mirror row_mask:0xf bank_mask:0xf
	s_nop 1
	v_add_f32_dpp v192, v192, v192 row_bcast:15 row_mask:0xa bank_mask:0xf
	s_nop 1
	v_add_f32_dpp v192, v192, v192 row_bcast:31 row_mask:0xc bank_mask:0xf
	s_nop 1
	v_readlane_b32 s42, v192, 63
	s_nop 3
	s_mov_b32 s43, s42
	v_pk_fma_f32 v[160:161], s[42:43], v[196:197], v[160:161]
	v_pk_fma_f32 v[162:163], s[42:43], v[196:197], v[162:163]
	v_pk_fma_f32 v[164:165], s[42:43], v[196:197], v[164:165]
	v_pk_fma_f32 v[166:167], s[42:43], v[196:197], v[166:167]
	v_pk_fma_f32 v[168:169], s[42:43], v[196:197], v[168:169]
	v_pk_fma_f32 v[170:171], s[42:43], v[196:197], v[170:171]
	v_pk_fma_f32 v[172:173], s[42:43], v[196:197], v[172:173]
	v_pk_fma_f32 v[174:175], s[42:43], v[196:197], v[174:175]
	v_pk_mul_f32 v[176:177], v[160:161], v[160:161]
	v_pk_fma_f32 v[176:177], v[162:163], v[162:163], v[176:177]
	v_pk_fma_f32 v[176:177], v[164:165], v[164:165], v[176:177]
	v_pk_fma_f32 v[176:177], v[166:167], v[166:167], v[176:177]
	v_pk_fma_f32 v[176:177], v[168:169], v[168:169], v[176:177]
	v_pk_fma_f32 v[176:177], v[170:171], v[170:171], v[176:177]
	v_pk_fma_f32 v[176:177], v[172:173], v[172:173], v[176:177]
	v_pk_fma_f32 v[176:177], v[174:175], v[174:175], v[176:177]
	v_add_f32_e32 v194, v176, v177
	s_nop 1
	v_add_f32_dpp v192, v194, v194 quad_perm:[1,0,3,2] row_mask:0xf bank_mask:0xf
	s_nop 1
	v_add_f32_dpp v192, v192, v192 quad_perm:[2,3,0,1] row_mask:0xf bank_mask:0xf
	s_nop 1
	v_add_f32_dpp v192, v192, v192 row_half_mirror row_mask:0xf bank_mask:0xf
	s_nop 1
	v_add_f32_dpp v192, v192, v192 row_mirror row_mask:0xf bank_mask:0xf
	s_nop 1
	v_add_f32_dpp v192, v192, v192 row_bcast:15 row_mask:0xa bank_mask:0xf
	s_nop 1
	v_add_f32_dpp v192, v192, v192 row_bcast:31 row_mask:0xc bank_mask:0xf
	s_nop 1
	v_readlane_b32 s42, v192, 63
	s_nop 3
	v_fma_f32 v198, s42, v202, v203
	v_rsq_f32_e32 v198, v198
	s_nop 0
	v_pk_mul_f32 v[160:161], v[160:161], v[198:199] op_sel_hi:[1,0]
	v_pk_mul_f32 v[162:163], v[162:163], v[198:199] op_sel_hi:[1,0]
	v_pk_mul_f32 v[164:165], v[164:165], v[198:199] op_sel_hi:[1,0]
	v_pk_mul_f32 v[166:167], v[166:167], v[198:199] op_sel_hi:[1,0]
	v_pk_mul_f32 v[168:169], v[168:169], v[198:199] op_sel_hi:[1,0]
	v_pk_mul_f32 v[170:171], v[170:171], v[198:199] op_sel_hi:[1,0]
	v_pk_mul_f32 v[172:173], v[172:173], v[198:199] op_sel_hi:[1,0]
	v_pk_mul_f32 v[174:175], v[174:175], v[198:199] op_sel_hi:[1,0]
	v_pk_fma_f32 v[160:161], v[160:161], v[0:1], v[16:17]
	v_pk_fma_f32 v[162:163], v[162:163], v[2:3], v[18:19]
	v_pk_fma_f32 v[164:165], v[164:165], v[4:5], v[20:21]
	v_pk_fma_f32 v[166:167], v[166:167], v[6:7], v[22:23]
	v_pk_fma_f32 v[168:169], v[168:169], v[8:9], v[24:25]
	v_pk_fma_f32 v[170:171], v[170:171], v[10:11], v[26:27]
	v_pk_fma_f32 v[172:173], v[172:173], v[12:13], v[28:29]
	v_pk_fma_f32 v[174:175], v[174:175], v[14:15], v[30:31]
	global_store_dwordx4 v200, v[160:163], s[8:9] offset:0
	global_store_dwordx4 v200, v[164:167], s[8:9] offset:1024
	global_store_dwordx4 v200, v[168:171], s[8:9] offset:2048
	global_store_dwordx4 v200, v[172:175], s[8:9] offset:3072
	v_pk_add_f32 v[176:177], v[160:161], v[162:163]
	v_pk_add_f32 v[176:177], v[176:177], v[164:165]
	v_pk_add_f32 v[176:177], v[176:177], v[166:167]
	v_pk_add_f32 v[176:177], v[176:177], v[168:169]
	v_pk_add_f32 v[176:177], v[176:177], v[170:171]
	v_pk_add_f32 v[176:177], v[176:177], v[172:173]
	v_pk_add_f32 v[176:177], v[176:177], v[174:175]
	v_add_f32_e32 v194, v176, v177
	s_nop 1
	v_add_f32_dpp v192, v194, v194 quad_perm:[1,0,3,2] row_mask:0xf bank_mask:0xf
	s_nop 1
	v_add_f32_dpp v192, v192, v192 quad_perm:[2,3,0,1] row_mask:0xf bank_mask:0xf
	s_nop 1
	v_add_f32_dpp v192, v192, v192 row_half_mirror row_mask:0xf bank_mask:0xf
	s_nop 1
	v_add_f32_dpp v192, v192, v192 row_mirror row_mask:0xf bank_mask:0xf
	s_nop 1
	v_add_f32_dpp v192, v192, v192 row_bcast:15 row_mask:0xa bank_mask:0xf
	s_nop 1
	v_add_f32_dpp v192, v192, v192 row_bcast:31 row_mask:0xc bank_mask:0xf
	s_nop 1
	v_readlane_b32 s42, v192, 63
	s_nop 3
	s_mov_b32 s43, s42
	v_pk_fma_f32 v[160:161], s[42:43], v[196:197], v[160:161]
	v_pk_fma_f32 v[162:163], s[42:43], v[196:197], v[162:163]
	v_pk_fma_f32 v[164:165], s[42:43], v[196:197], v[164:165]
	v_pk_fma_f32 v[166:167], s[42:43], v[196:197], v[166:167]
	v_pk_fma_f32 v[168:169], s[42:43], v[196:197], v[168:169]
	v_pk_fma_f32 v[170:171], s[42:43], v[196:197], v[170:171]
	v_pk_fma_f32 v[172:173], s[42:43], v[196:197], v[172:173]
	v_pk_fma_f32 v[174:175], s[42:43], v[196:197], v[174:175]
	v_pk_mul_f32 v[176:177], v[160:161], v[160:161]
	v_pk_fma_f32 v[176:177], v[162:163], v[162:163], v[176:177]
	v_pk_fma_f32 v[176:177], v[164:165], v[164:165], v[176:177]
	v_pk_fma_f32 v[176:177], v[166:167], v[166:167], v[176:177]
	v_pk_fma_f32 v[176:177], v[168:169], v[168:169], v[176:177]
	v_pk_fma_f32 v[176:177], v[170:171], v[170:171], v[176:177]
	v_pk_fma_f32 v[176:177], v[172:173], v[172:173], v[176:177]
	v_pk_fma_f32 v[176:177], v[174:175], v[174:175], v[176:177]
	v_add_f32_e32 v194, v176, v177
	s_nop 1
	v_add_f32_dpp v192, v194, v194 quad_perm:[1,0,3,2] row_mask:0xf bank_mask:0xf
	s_nop 1
	v_add_f32_dpp v192, v192, v192 quad_perm:[2,3,0,1] row_mask:0xf bank_mask:0xf
	s_nop 1
	v_add_f32_dpp v192, v192, v192 row_half_mirror row_mask:0xf bank_mask:0xf
	s_nop 1
	v_add_f32_dpp v192, v192, v192 row_mirror row_mask:0xf bank_mask:0xf
	s_nop 1
	v_add_f32_dpp v192, v192, v192 row_bcast:15 row_mask:0xa bank_mask:0xf
	s_nop 1
	v_add_f32_dpp v192, v192, v192 row_bcast:31 row_mask:0xc bank_mask:0xf
	s_nop 1
	v_readlane_b32 s42, v192, 63
	s_nop 3
	v_fma_f32 v198, s42, v202, v203
	v_rsq_f32_e32 v198, v198
	s_nop 0
	v_pk_mul_f32 v[160:161], v[160:161], v[198:199] op_sel_hi:[1,0]
	v_pk_mul_f32 v[162:163], v[162:163], v[198:199] op_sel_hi:[1,0]
	v_pk_mul_f32 v[164:165], v[164:165], v[198:199] op_sel_hi:[1,0]
	v_pk_mul_f32 v[166:167], v[166:167], v[198:199] op_sel_hi:[1,0]
	v_pk_mul_f32 v[168:169], v[168:169], v[198:199] op_sel_hi:[1,0]
	v_pk_mul_f32 v[170:171], v[170:171], v[198:199] op_sel_hi:[1,0]
	v_pk_mul_f32 v[172:173], v[172:173], v[198:199] op_sel_hi:[1,0]
	v_pk_mul_f32 v[174:175], v[174:175], v[198:199] op_sel_hi:[1,0]
	v_pk_fma_f32 v[160:161], v[160:161], v[32:33], v[48:49]
	v_pk_fma_f32 v[162:163], v[162:163], v[34:35], v[50:51]
	v_pk_fma_f32 v[164:165], v[164:165], v[36:37], v[52:53]
	v_pk_fma_f32 v[166:167], v[166:167], v[38:39], v[54:55]
	v_pk_fma_f32 v[168:169], v[168:169], v[40:41], v[56:57]
	v_pk_fma_f32 v[170:171], v[170:171], v[42:43], v[58:59]
	v_pk_fma_f32 v[172:173], v[172:173], v[44:45], v[60:61]
	v_pk_fma_f32 v[174:175], v[174:175], v[46:47], v[62:63]
	v_cvt_pk_bf16_f32 v176, v160, v161
	v_cvt_pk_bf16_f32 v177, v162, v163
	v_cvt_pk_bf16_f32 v178, v164, v165
	v_cvt_pk_bf16_f32 v179, v166, v167
	v_cvt_pk_bf16_f32 v180, v168, v169
	v_cvt_pk_bf16_f32 v181, v170, v171
	v_cvt_pk_bf16_f32 v182, v172, v173
	v_cvt_pk_bf16_f32 v183, v174, v175
	global_store_dwordx2 v201, v[176:177], s[12:13] offset:0
	global_store_dwordx2 v201, v[178:179], s[12:13] offset:512
	global_store_dwordx2 v201, v[180:181], s[12:13] offset:1024
	global_store_dwordx2 v201, v[182:183], s[12:13] offset:1536
	s_add_u32 s8, s8, 0x1000
	s_addc_u32 s9, s9, 0
	s_add_u32 s12, s12, 0x800
	s_addc_u32 s13, s13, 0
	global_load_dwordx4 v[80:83], v200, s[2:3] offset:0
	global_load_dwordx4 v[84:87], v200, s[2:3] offset:1024
	global_load_dwordx4 v[88:91], v200, s[2:3] offset:2048
	global_load_dwordx4 v[92:95], v200, s[2:3] offset:3072
	global_load_dwordx2 v[136:137], v201, s[6:7] offset:0
	global_load_dwordx2 v[138:139], v201, s[6:7] offset:512
	global_load_dwordx2 v[140:141], v201, s[6:7] offset:1024
	global_load_dwordx2 v[142:143], v201, s[6:7] offset:1536
	s_add_u32 s2, s2, 0x1000
	s_addc_u32 s3, s3, 0
	s_add_u32 s6, s6, 0x800
	s_addc_u32 s7, s7, 0
	s_waitcnt vmcnt(48)
	v_lshlrev_b32_e32 v160, 16, v144
	v_and_b32_e32 v161, 0xffff0000, v144
	v_lshlrev_b32_e32 v162, 16, v145
	v_and_b32_e32 v163, 0xffff0000, v145
	v_lshlrev_b32_e32 v164, 16, v146
	v_and_b32_e32 v165, 0xffff0000, v146
	v_lshlrev_b32_e32 v166, 16, v147
	v_and_b32_e32 v167, 0xffff0000, v147
	v_lshlrev_b32_e32 v168, 16, v148
	v_and_b32_e32 v169, 0xffff0000, v148
	v_lshlrev_b32_e32 v170, 16, v149
	v_and_b32_e32 v171, 0xffff0000, v149
	v_lshlrev_b32_e32 v172, 16, v150
	v_and_b32_e32 v173, 0xffff0000, v150
	v_lshlrev_b32_e32 v174, 16, v151
	v_and_b32_e32 v175, 0xffff0000, v151
	v_pk_fma_f32 v[160:161], v[96:97], s[44:45], v[160:161]
	v_pk_fma_f32 v[162:163], v[98:99], s[44:45], v[162:163]
	v_pk_fma_f32 v[164:165], v[100:101], s[44:45], v[164:165]
	v_pk_fma_f32 v[166:167], v[102:103], s[44:45], v[166:167]
	v_pk_fma_f32 v[168:169], v[104:105], s[44:45], v[168:169]
	v_pk_fma_f32 v[170:171], v[106:107], s[44:45], v[170:171]
	v_pk_fma_f32 v[172:173], v[108:109], s[44:45], v[172:173]
	v_pk_fma_f32 v[174:175], v[110:111], s[44:45], v[174:175]
	v_pk_add_f32 v[176:177], v[160:161], v[162:163]
	v_pk_add_f32 v[176:177], v[176:177], v[164:165]
	v_pk_add_f32 v[176:177], v[176:177], v[166:167]
	v_pk_add_f32 v[176:177], v[176:177], v[168:169]
	v_pk_add_f32 v[176:177], v[176:177], v[170:171]
	v_pk_add_f32 v[176:177], v[176:177], v[172:173]
	v_pk_add_f32 v[176:177], v[176:177], v[174:175]
	v_add_f32_e32 v194, v176, v177
	s_nop 1
	v_add_f32_dpp v192, v194, v194 quad_perm:[1,0,3,2] row_mask:0xf bank_mask:0xf
	s_nop 1
	v_add_f32_dpp v192, v192, v192 quad_perm:[2,3,0,1] row_mask:0xf bank_mask:0xf
	s_nop 1
	v_add_f32_dpp v192, v192, v192 row_half_mirror row_mask:0xf bank_mask:0xf
	s_nop 1
	v_add_f32_dpp v192, v192, v192 row_mirror row_mask:0xf bank_mask:0xf
	s_nop 1
	v_add_f32_dpp v192, v192, v192 row_bcast:15 row_mask:0xa bank_mask:0xf
	s_nop 1
	v_add_f32_dpp v192, v192, v192 row_bcast:31 row_mask:0xc bank_mask:0xf
	s_nop 1
	v_readlane_b32 s42, v192, 63
	s_nop 3
	s_mov_b32 s43, s42
	v_pk_fma_f32 v[160:161], s[42:43], v[196:197], v[160:161]
	v_pk_fma_f32 v[162:163], s[42:43], v[196:197], v[162:163]
	v_pk_fma_f32 v[164:165], s[42:43], v[196:197], v[164:165]
	v_pk_fma_f32 v[166:167], s[42:43], v[196:197], v[166:167]
	v_pk_fma_f32 v[168:169], s[42:43], v[196:197], v[168:169]
	v_pk_fma_f32 v[170:171], s[42:43], v[196:197], v[170:171]
	v_pk_fma_f32 v[172:173], s[42:43], v[196:197], v[172:173]
	v_pk_fma_f32 v[174:175], s[42:43], v[196:197], v[174:175]
	v_pk_mul_f32 v[176:177], v[160:161], v[160:161]
	v_pk_fma_f32 v[176:177], v[162:163], v[162:163], v[176:177]
	v_pk_fma_f32 v[176:177], v[164:165], v[164:165], v[176:177]
	v_pk_fma_f32 v[176:177], v[166:167], v[166:167], v[176:177]
	v_pk_fma_f32 v[176:177], v[168:169], v[168:169], v[176:177]
	v_pk_fma_f32 v[176:177], v[170:171], v[170:171], v[176:177]
	v_pk_fma_f32 v[176:177], v[172:173], v[172:173], v[176:177]
	v_pk_fma_f32 v[176:177], v[174:175], v[174:175], v[176:177]
	v_add_f32_e32 v194, v176, v177
	s_nop 1
	v_add_f32_dpp v192, v194, v194 quad_perm:[1,0,3,2] row_mask:0xf bank_mask:0xf
	s_nop 1
	v_add_f32_dpp v192, v192, v192 quad_perm:[2,3,0,1] row_mask:0xf bank_mask:0xf
	s_nop 1
	v_add_f32_dpp v192, v192, v192 row_half_mirror row_mask:0xf bank_mask:0xf
	s_nop 1
	v_add_f32_dpp v192, v192, v192 row_mirror row_mask:0xf bank_mask:0xf
	s_nop 1
	v_add_f32_dpp v192, v192, v192 row_bcast:15 row_mask:0xa bank_mask:0xf
	s_nop 1
	v_add_f32_dpp v192, v192, v192 row_bcast:31 row_mask:0xc bank_mask:0xf
	s_nop 1
	v_readlane_b32 s42, v192, 63
	s_nop 3
	v_fma_f32 v198, s42, v202, v203
	v_rsq_f32_e32 v198, v198
	s_nop 0
	v_pk_mul_f32 v[160:161], v[160:161], v[198:199] op_sel_hi:[1,0]
	v_pk_mul_f32 v[162:163], v[162:163], v[198:199] op_sel_hi:[1,0]
	v_pk_mul_f32 v[164:165], v[164:165], v[198:199] op_sel_hi:[1,0]
	v_pk_mul_f32 v[166:167], v[166:167], v[198:199] op_sel_hi:[1,0]
	v_pk_mul_f32 v[168:169], v[168:169], v[198:199] op_sel_hi:[1,0]
	v_pk_mul_f32 v[170:171], v[170:171], v[198:199] op_sel_hi:[1,0]
	v_pk_mul_f32 v[172:173], v[172:173], v[198:199] op_sel_hi:[1,0]
	v_pk_mul_f32 v[174:175], v[174:175], v[198:199] op_sel_hi:[1,0]
	v_pk_fma_f32 v[160:161], v[160:161], v[0:1], v[16:17]
	v_pk_fma_f32 v[162:163], v[162:163], v[2:3], v[18:19]
	v_pk_fma_f32 v[164:165], v[164:165], v[4:5], v[20:21]
	v_pk_fma_f32 v[166:167], v[166:167], v[6:7], v[22:23]
	v_pk_fma_f32 v[168:169], v[168:169], v[8:9], v[24:25]
	v_pk_fma_f32 v[170:171], v[170:171], v[10:11], v[26:27]
	v_pk_fma_f32 v[172:173], v[172:173], v[12:13], v[28:29]
	v_pk_fma_f32 v[174:175], v[174:175], v[14:15], v[30:31]
	global_store_dwordx4 v200, v[160:163], s[8:9] offset:0
	global_store_dwordx4 v200, v[164:167], s[8:9] offset:1024
	global_store_dwordx4 v200, v[168:171], s[8:9] offset:2048
	global_store_dwordx4 v200, v[172:175], s[8:9] offset:3072
	v_pk_add_f32 v[176:177], v[160:161], v[162:163]
	v_pk_add_f32 v[176:177], v[176:177], v[164:165]
	v_pk_add_f32 v[176:177], v[176:177], v[166:167]
	v_pk_add_f32 v[176:177], v[176:177], v[168:169]
	v_pk_add_f32 v[176:177], v[176:177], v[170:171]
	v_pk_add_f32 v[176:177], v[176:177], v[172:173]
	v_pk_add_f32 v[176:177], v[176:177], v[174:175]
	v_add_f32_e32 v194, v176, v177
	s_nop 1
	v_add_f32_dpp v192, v194, v194 quad_perm:[1,0,3,2] row_mask:0xf bank_mask:0xf
	s_nop 1
	v_add_f32_dpp v192, v192, v192 quad_perm:[2,3,0,1] row_mask:0xf bank_mask:0xf
	s_nop 1
	v_add_f32_dpp v192, v192, v192 row_half_mirror row_mask:0xf bank_mask:0xf
	s_nop 1
	v_add_f32_dpp v192, v192, v192 row_mirror row_mask:0xf bank_mask:0xf
	s_nop 1
	v_add_f32_dpp v192, v192, v192 row_bcast:15 row_mask:0xa bank_mask:0xf
	s_nop 1
	v_add_f32_dpp v192, v192, v192 row_bcast:31 row_mask:0xc bank_mask:0xf
	s_nop 1
	v_readlane_b32 s42, v192, 63
	s_nop 3
	s_mov_b32 s43, s42
	v_pk_fma_f32 v[160:161], s[42:43], v[196:197], v[160:161]
	v_pk_fma_f32 v[162:163], s[42:43], v[196:197], v[162:163]
	v_pk_fma_f32 v[164:165], s[42:43], v[196:197], v[164:165]
	v_pk_fma_f32 v[166:167], s[42:43], v[196:197], v[166:167]
	v_pk_fma_f32 v[168:169], s[42:43], v[196:197], v[168:169]
	v_pk_fma_f32 v[170:171], s[42:43], v[196:197], v[170:171]
	v_pk_fma_f32 v[172:173], s[42:43], v[196:197], v[172:173]
	v_pk_fma_f32 v[174:175], s[42:43], v[196:197], v[174:175]
	v_pk_mul_f32 v[176:177], v[160:161], v[160:161]
	v_pk_fma_f32 v[176:177], v[162:163], v[162:163], v[176:177]
	v_pk_fma_f32 v[176:177], v[164:165], v[164:165], v[176:177]
	v_pk_fma_f32 v[176:177], v[166:167], v[166:167], v[176:177]
	v_pk_fma_f32 v[176:177], v[168:169], v[168:169], v[176:177]
	v_pk_fma_f32 v[176:177], v[170:171], v[170:171], v[176:177]
	v_pk_fma_f32 v[176:177], v[172:173], v[172:173], v[176:177]
	v_pk_fma_f32 v[176:177], v[174:175], v[174:175], v[176:177]
	v_add_f32_e32 v194, v176, v177
	s_nop 1
	v_add_f32_dpp v192, v194, v194 quad_perm:[1,0,3,2] row_mask:0xf bank_mask:0xf
	s_nop 1
	v_add_f32_dpp v192, v192, v192 quad_perm:[2,3,0,1] row_mask:0xf bank_mask:0xf
	s_nop 1
	v_add_f32_dpp v192, v192, v192 row_half_mirror row_mask:0xf bank_mask:0xf
	s_nop 1
	v_add_f32_dpp v192, v192, v192 row_mirror row_mask:0xf bank_mask:0xf
	s_nop 1
	v_add_f32_dpp v192, v192, v192 row_bcast:15 row_mask:0xa bank_mask:0xf
	s_nop 1
	v_add_f32_dpp v192, v192, v192 row_bcast:31 row_mask:0xc bank_mask:0xf
	s_nop 1
	v_readlane_b32 s42, v192, 63
	s_nop 3
	v_fma_f32 v198, s42, v202, v203
	v_rsq_f32_e32 v198, v198
	s_nop 0
	v_pk_mul_f32 v[160:161], v[160:161], v[198:199] op_sel_hi:[1,0]
	v_pk_mul_f32 v[162:163], v[162:163], v[198:199] op_sel_hi:[1,0]
	v_pk_mul_f32 v[164:165], v[164:165], v[198:199] op_sel_hi:[1,0]
	v_pk_mul_f32 v[166:167], v[166:167], v[198:199] op_sel_hi:[1,0]
	v_pk_mul_f32 v[168:169], v[168:169], v[198:199] op_sel_hi:[1,0]
	v_pk_mul_f32 v[170:171], v[170:171], v[198:199] op_sel_hi:[1,0]
	v_pk_mul_f32 v[172:173], v[172:173], v[198:199] op_sel_hi:[1,0]
	v_pk_mul_f32 v[174:175], v[174:175], v[198:199] op_sel_hi:[1,0]
	v_pk_fma_f32 v[160:161], v[160:161], v[32:33], v[48:49]
	v_pk_fma_f32 v[162:163], v[162:163], v[34:35], v[50:51]
	v_pk_fma_f32 v[164:165], v[164:165], v[36:37], v[52:53]
	v_pk_fma_f32 v[166:167], v[166:167], v[38:39], v[54:55]
	v_pk_fma_f32 v[168:169], v[168:169], v[40:41], v[56:57]
	v_pk_fma_f32 v[170:171], v[170:171], v[42:43], v[58:59]
	v_pk_fma_f32 v[172:173], v[172:173], v[44:45], v[60:61]
	v_pk_fma_f32 v[174:175], v[174:175], v[46:47], v[62:63]
	v_cvt_pk_bf16_f32 v176, v160, v161
	v_cvt_pk_bf16_f32 v177, v162, v163
	v_cvt_pk_bf16_f32 v178, v164, v165
	v_cvt_pk_bf16_f32 v179, v166, v167
	v_cvt_pk_bf16_f32 v180, v168, v169
	v_cvt_pk_bf16_f32 v181, v170, v171
	v_cvt_pk_bf16_f32 v182, v172, v173
	v_cvt_pk_bf16_f32 v183, v174, v175
	global_store_dwordx2 v201, v[176:177], s[12:13] offset:0
	global_store_dwordx2 v201, v[178:179], s[12:13] offset:512
	global_store_dwordx2 v201, v[180:181], s[12:13] offset:1024
	global_store_dwordx2 v201, v[182:183], s[12:13] offset:1536
	s_add_u32 s8, s8, 0x1000
	s_addc_u32 s9, s9, 0
	s_add_u32 s12, s12, 0x800
	s_addc_u32 s13, s13, 0
	global_load_dwordx4 v[96:99], v200, s[2:3] offset:0
	global_load_dwordx4 v[100:103], v200, s[2:3] offset:1024
	global_load_dwordx4 v[104:107], v200, s[2:3] offset:2048
	global_load_dwordx4 v[108:111], v200, s[2:3] offset:3072
	global_load_dwordx2 v[144:145], v201, s[6:7] offset:0
	global_load_dwordx2 v[146:147], v201, s[6:7] offset:512
	global_load_dwordx2 v[148:149], v201, s[6:7] offset:1024
	global_load_dwordx2 v[150:151], v201, s[6:7] offset:1536
	s_add_u32 s2, s2, 0x1000
	s_addc_u32 s3, s3, 0
	s_add_u32 s6, s6, 0x800
	s_addc_u32 s7, s7, 0
	s_waitcnt vmcnt(48)
	v_lshlrev_b32_e32 v160, 16, v152
	v_and_b32_e32 v161, 0xffff0000, v152
	v_lshlrev_b32_e32 v162, 16, v153
	v_and_b32_e32 v163, 0xffff0000, v153
	v_lshlrev_b32_e32 v164, 16, v154
	v_and_b32_e32 v165, 0xffff0000, v154
	v_lshlrev_b32_e32 v166, 16, v155
	v_and_b32_e32 v167, 0xffff0000, v155
	v_lshlrev_b32_e32 v168, 16, v156
	v_and_b32_e32 v169, 0xffff0000, v156
	v_lshlrev_b32_e32 v170, 16, v157
	v_and_b32_e32 v171, 0xffff0000, v157
	v_lshlrev_b32_e32 v172, 16, v158
	v_and_b32_e32 v173, 0xffff0000, v158
	v_lshlrev_b32_e32 v174, 16, v159
	v_and_b32_e32 v175, 0xffff0000, v159
	v_pk_fma_f32 v[160:161], v[112:113], s[44:45], v[160:161]
	v_pk_fma_f32 v[162:163], v[114:115], s[44:45], v[162:163]
	v_pk_fma_f32 v[164:165], v[116:117], s[44:45], v[164:165]
	v_pk_fma_f32 v[166:167], v[118:119], s[44:45], v[166:167]
	v_pk_fma_f32 v[168:169], v[120:121], s[44:45], v[168:169]
	v_pk_fma_f32 v[170:171], v[122:123], s[44:45], v[170:171]
	v_pk_fma_f32 v[172:173], v[124:125], s[44:45], v[172:173]
	v_pk_fma_f32 v[174:175], v[126:127], s[44:45], v[174:175]
	v_pk_add_f32 v[176:177], v[160:161], v[162:163]
	v_pk_add_f32 v[176:177], v[176:177], v[164:165]
	v_pk_add_f32 v[176:177], v[176:177], v[166:167]
	v_pk_add_f32 v[176:177], v[176:177], v[168:169]
	v_pk_add_f32 v[176:177], v[176:177], v[170:171]
	v_pk_add_f32 v[176:177], v[176:177], v[172:173]
	v_pk_add_f32 v[176:177], v[176:177], v[174:175]
	v_add_f32_e32 v194, v176, v177
	s_nop 1
	v_add_f32_dpp v192, v194, v194 quad_perm:[1,0,3,2] row_mask:0xf bank_mask:0xf
	s_nop 1
	v_add_f32_dpp v192, v192, v192 quad_perm:[2,3,0,1] row_mask:0xf bank_mask:0xf
	s_nop 1
	v_add_f32_dpp v192, v192, v192 row_half_mirror row_mask:0xf bank_mask:0xf
	s_nop 1
	v_add_f32_dpp v192, v192, v192 row_mirror row_mask:0xf bank_mask:0xf
	s_nop 1
	v_add_f32_dpp v192, v192, v192 row_bcast:15 row_mask:0xa bank_mask:0xf
	s_nop 1
	v_add_f32_dpp v192, v192, v192 row_bcast:31 row_mask:0xc bank_mask:0xf
	s_nop 1
	v_readlane_b32 s42, v192, 63
	s_nop 3
	s_mov_b32 s43, s42
	v_pk_fma_f32 v[160:161], s[42:43], v[196:197], v[160:161]
	v_pk_fma_f32 v[162:163], s[42:43], v[196:197], v[162:163]
	v_pk_fma_f32 v[164:165], s[42:43], v[196:197], v[164:165]
	v_pk_fma_f32 v[166:167], s[42:43], v[196:197], v[166:167]
	v_pk_fma_f32 v[168:169], s[42:43], v[196:197], v[168:169]
	v_pk_fma_f32 v[170:171], s[42:43], v[196:197], v[170:171]
	v_pk_fma_f32 v[172:173], s[42:43], v[196:197], v[172:173]
	v_pk_fma_f32 v[174:175], s[42:43], v[196:197], v[174:175]
	v_pk_mul_f32 v[176:177], v[160:161], v[160:161]
	v_pk_fma_f32 v[176:177], v[162:163], v[162:163], v[176:177]
	v_pk_fma_f32 v[176:177], v[164:165], v[164:165], v[176:177]
	v_pk_fma_f32 v[176:177], v[166:167], v[166:167], v[176:177]
	v_pk_fma_f32 v[176:177], v[168:169], v[168:169], v[176:177]
	v_pk_fma_f32 v[176:177], v[170:171], v[170:171], v[176:177]
	v_pk_fma_f32 v[176:177], v[172:173], v[172:173], v[176:177]
	v_pk_fma_f32 v[176:177], v[174:175], v[174:175], v[176:177]
	v_add_f32_e32 v194, v176, v177
	s_nop 1
	v_add_f32_dpp v192, v194, v194 quad_perm:[1,0,3,2] row_mask:0xf bank_mask:0xf
	s_nop 1
	v_add_f32_dpp v192, v192, v192 quad_perm:[2,3,0,1] row_mask:0xf bank_mask:0xf
	s_nop 1
	v_add_f32_dpp v192, v192, v192 row_half_mirror row_mask:0xf bank_mask:0xf
	s_nop 1
	v_add_f32_dpp v192, v192, v192 row_mirror row_mask:0xf bank_mask:0xf
	s_nop 1
	v_add_f32_dpp v192, v192, v192 row_bcast:15 row_mask:0xa bank_mask:0xf
	s_nop 1
	v_add_f32_dpp v192, v192, v192 row_bcast:31 row_mask:0xc bank_mask:0xf
	s_nop 1
	v_readlane_b32 s42, v192, 63
	s_nop 3
	v_fma_f32 v198, s42, v202, v203
	v_rsq_f32_e32 v198, v198
	s_nop 0
	v_pk_mul_f32 v[160:161], v[160:161], v[198:199] op_sel_hi:[1,0]
	v_pk_mul_f32 v[162:163], v[162:163], v[198:199] op_sel_hi:[1,0]
	v_pk_mul_f32 v[164:165], v[164:165], v[198:199] op_sel_hi:[1,0]
	v_pk_mul_f32 v[166:167], v[166:167], v[198:199] op_sel_hi:[1,0]
	v_pk_mul_f32 v[168:169], v[168:169], v[198:199] op_sel_hi:[1,0]
	v_pk_mul_f32 v[170:171], v[170:171], v[198:199] op_sel_hi:[1,0]
	v_pk_mul_f32 v[172:173], v[172:173], v[198:199] op_sel_hi:[1,0]
	v_pk_mul_f32 v[174:175], v[174:175], v[198:199] op_sel_hi:[1,0]
	v_pk_fma_f32 v[160:161], v[160:161], v[0:1], v[16:17]
	v_pk_fma_f32 v[162:163], v[162:163], v[2:3], v[18:19]
	v_pk_fma_f32 v[164:165], v[164:165], v[4:5], v[20:21]
	v_pk_fma_f32 v[166:167], v[166:167], v[6:7], v[22:23]
	v_pk_fma_f32 v[168:169], v[168:169], v[8:9], v[24:25]
	v_pk_fma_f32 v[170:171], v[170:171], v[10:11], v[26:27]
	v_pk_fma_f32 v[172:173], v[172:173], v[12:13], v[28:29]
	v_pk_fma_f32 v[174:175], v[174:175], v[14:15], v[30:31]
	global_store_dwordx4 v200, v[160:163], s[8:9] offset:0
	global_store_dwordx4 v200, v[164:167], s[8:9] offset:1024
	global_store_dwordx4 v200, v[168:171], s[8:9] offset:2048
	global_store_dwordx4 v200, v[172:175], s[8:9] offset:3072
	v_pk_add_f32 v[176:177], v[160:161], v[162:163]
	v_pk_add_f32 v[176:177], v[176:177], v[164:165]
	v_pk_add_f32 v[176:177], v[176:177], v[166:167]
	v_pk_add_f32 v[176:177], v[176:177], v[168:169]
	v_pk_add_f32 v[176:177], v[176:177], v[170:171]
	v_pk_add_f32 v[176:177], v[176:177], v[172:173]
	v_pk_add_f32 v[176:177], v[176:177], v[174:175]
	v_add_f32_e32 v194, v176, v177
	s_nop 1
	v_add_f32_dpp v192, v194, v194 quad_perm:[1,0,3,2] row_mask:0xf bank_mask:0xf
	s_nop 1
	v_add_f32_dpp v192, v192, v192 quad_perm:[2,3,0,1] row_mask:0xf bank_mask:0xf
	s_nop 1
	v_add_f32_dpp v192, v192, v192 row_half_mirror row_mask:0xf bank_mask:0xf
	s_nop 1
	v_add_f32_dpp v192, v192, v192 row_mirror row_mask:0xf bank_mask:0xf
	s_nop 1
	v_add_f32_dpp v192, v192, v192 row_bcast:15 row_mask:0xa bank_mask:0xf
	s_nop 1
	v_add_f32_dpp v192, v192, v192 row_bcast:31 row_mask:0xc bank_mask:0xf
	s_nop 1
	v_readlane_b32 s42, v192, 63
	s_nop 3
	s_mov_b32 s43, s42
	v_pk_fma_f32 v[160:161], s[42:43], v[196:197], v[160:161]
	v_pk_fma_f32 v[162:163], s[42:43], v[196:197], v[162:163]
	v_pk_fma_f32 v[164:165], s[42:43], v[196:197], v[164:165]
	v_pk_fma_f32 v[166:167], s[42:43], v[196:197], v[166:167]
	v_pk_fma_f32 v[168:169], s[42:43], v[196:197], v[168:169]
	v_pk_fma_f32 v[170:171], s[42:43], v[196:197], v[170:171]
	v_pk_fma_f32 v[172:173], s[42:43], v[196:197], v[172:173]
	v_pk_fma_f32 v[174:175], s[42:43], v[196:197], v[174:175]
	v_pk_mul_f32 v[176:177], v[160:161], v[160:161]
	v_pk_fma_f32 v[176:177], v[162:163], v[162:163], v[176:177]
	v_pk_fma_f32 v[176:177], v[164:165], v[164:165], v[176:177]
	v_pk_fma_f32 v[176:177], v[166:167], v[166:167], v[176:177]
	v_pk_fma_f32 v[176:177], v[168:169], v[168:169], v[176:177]
	v_pk_fma_f32 v[176:177], v[170:171], v[170:171], v[176:177]
	v_pk_fma_f32 v[176:177], v[172:173], v[172:173], v[176:177]
	v_pk_fma_f32 v[176:177], v[174:175], v[174:175], v[176:177]
	v_add_f32_e32 v194, v176, v177
	s_nop 1
	v_add_f32_dpp v192, v194, v194 quad_perm:[1,0,3,2] row_mask:0xf bank_mask:0xf
	s_nop 1
	v_add_f32_dpp v192, v192, v192 quad_perm:[2,3,0,1] row_mask:0xf bank_mask:0xf
	s_nop 1
	v_add_f32_dpp v192, v192, v192 row_half_mirror row_mask:0xf bank_mask:0xf
	s_nop 1
	v_add_f32_dpp v192, v192, v192 row_mirror row_mask:0xf bank_mask:0xf
	s_nop 1
	v_add_f32_dpp v192, v192, v192 row_bcast:15 row_mask:0xa bank_mask:0xf
	s_nop 1
	v_add_f32_dpp v192, v192, v192 row_bcast:31 row_mask:0xc bank_mask:0xf
	s_nop 1
	v_readlane_b32 s42, v192, 63
	s_nop 3
	v_fma_f32 v198, s42, v202, v203
	v_rsq_f32_e32 v198, v198
	s_nop 0
	v_pk_mul_f32 v[160:161], v[160:161], v[198:199] op_sel_hi:[1,0]
	v_pk_mul_f32 v[162:163], v[162:163], v[198:199] op_sel_hi:[1,0]
	v_pk_mul_f32 v[164:165], v[164:165], v[198:199] op_sel_hi:[1,0]
	v_pk_mul_f32 v[166:167], v[166:167], v[198:199] op_sel_hi:[1,0]
	v_pk_mul_f32 v[168:169], v[168:169], v[198:199] op_sel_hi:[1,0]
	v_pk_mul_f32 v[170:171], v[170:171], v[198:199] op_sel_hi:[1,0]
	v_pk_mul_f32 v[172:173], v[172:173], v[198:199] op_sel_hi:[1,0]
	v_pk_mul_f32 v[174:175], v[174:175], v[198:199] op_sel_hi:[1,0]
	v_pk_fma_f32 v[160:161], v[160:161], v[32:33], v[48:49]
	v_pk_fma_f32 v[162:163], v[162:163], v[34:35], v[50:51]
	v_pk_fma_f32 v[164:165], v[164:165], v[36:37], v[52:53]
	v_pk_fma_f32 v[166:167], v[166:167], v[38:39], v[54:55]
	v_pk_fma_f32 v[168:169], v[168:169], v[40:41], v[56:57]
	v_pk_fma_f32 v[170:171], v[170:171], v[42:43], v[58:59]
	v_pk_fma_f32 v[172:173], v[172:173], v[44:45], v[60:61]
	v_pk_fma_f32 v[174:175], v[174:175], v[46:47], v[62:63]
	v_cvt_pk_bf16_f32 v176, v160, v161
	v_cvt_pk_bf16_f32 v177, v162, v163
	v_cvt_pk_bf16_f32 v178, v164, v165
	v_cvt_pk_bf16_f32 v179, v166, v167
	v_cvt_pk_bf16_f32 v180, v168, v169
	v_cvt_pk_bf16_f32 v181, v170, v171
	v_cvt_pk_bf16_f32 v182, v172, v173
	v_cvt_pk_bf16_f32 v183, v174, v175
	global_store_dwordx2 v201, v[176:177], s[12:13] offset:0
	global_store_dwordx2 v201, v[178:179], s[12:13] offset:512
	global_store_dwordx2 v201, v[180:181], s[12:13] offset:1024
	global_store_dwordx2 v201, v[182:183], s[12:13] offset:1536
	s_add_u32 s8, s8, 0x1000
	s_addc_u32 s9, s9, 0
	s_add_u32 s12, s12, 0x800
	s_addc_u32 s13, s13, 0
	global_load_dwordx4 v[112:115], v200, s[2:3] offset:0
	global_load_dwordx4 v[116:119], v200, s[2:3] offset:1024
	global_load_dwordx4 v[120:123], v200, s[2:3] offset:2048
	global_load_dwordx4 v[124:127], v200, s[2:3] offset:3072
	global_load_dwordx2 v[152:153], v201, s[6:7] offset:0
	global_load_dwordx2 v[154:155], v201, s[6:7] offset:512
	global_load_dwordx2 v[156:157], v201, s[6:7] offset:1024
	global_load_dwordx2 v[158:159], v201, s[6:7] offset:1536
	s_add_u32 s2, s2, 0x1000
	s_addc_u32 s3, s3, 0
	s_add_u32 s6, s6, 0x800
	s_addc_u32 s7, s7, 0
	s_waitcnt vmcnt(48)
	v_lshlrev_b32_e32 v160, 16, v128
	v_and_b32_e32 v161, 0xffff0000, v128
	v_lshlrev_b32_e32 v162, 16, v129
	v_and_b32_e32 v163, 0xffff0000, v129
	v_lshlrev_b32_e32 v164, 16, v130
	v_and_b32_e32 v165, 0xffff0000, v130
	v_lshlrev_b32_e32 v166, 16, v131
	v_and_b32_e32 v167, 0xffff0000, v131
	v_lshlrev_b32_e32 v168, 16, v132
	v_and_b32_e32 v169, 0xffff0000, v132
	v_lshlrev_b32_e32 v170, 16, v133
	v_and_b32_e32 v171, 0xffff0000, v133
	v_lshlrev_b32_e32 v172, 16, v134
	v_and_b32_e32 v173, 0xffff0000, v134
	v_lshlrev_b32_e32 v174, 16, v135
	v_and_b32_e32 v175, 0xffff0000, v135
	v_pk_fma_f32 v[160:161], v[64:65], s[44:45], v[160:161]
	v_pk_fma_f32 v[162:163], v[66:67], s[44:45], v[162:163]
	v_pk_fma_f32 v[164:165], v[68:69], s[44:45], v[164:165]
	v_pk_fma_f32 v[166:167], v[70:71], s[44:45], v[166:167]
	v_pk_fma_f32 v[168:169], v[72:73], s[44:45], v[168:169]
	v_pk_fma_f32 v[170:171], v[74:75], s[44:45], v[170:171]
	v_pk_fma_f32 v[172:173], v[76:77], s[44:45], v[172:173]
	v_pk_fma_f32 v[174:175], v[78:79], s[44:45], v[174:175]
	v_pk_add_f32 v[176:177], v[160:161], v[162:163]
	v_pk_add_f32 v[176:177], v[176:177], v[164:165]
	v_pk_add_f32 v[176:177], v[176:177], v[166:167]
	v_pk_add_f32 v[176:177], v[176:177], v[168:169]
	v_pk_add_f32 v[176:177], v[176:177], v[170:171]
	v_pk_add_f32 v[176:177], v[176:177], v[172:173]
	v_pk_add_f32 v[176:177], v[176:177], v[174:175]
	v_add_f32_e32 v194, v176, v177
	s_nop 1
	v_add_f32_dpp v192, v194, v194 quad_perm:[1,0,3,2] row_mask:0xf bank_mask:0xf
	s_nop 1
	v_add_f32_dpp v192, v192, v192 quad_perm:[2,3,0,1] row_mask:0xf bank_mask:0xf
	s_nop 1
	v_add_f32_dpp v192, v192, v192 row_half_mirror row_mask:0xf bank_mask:0xf
	s_nop 1
	v_add_f32_dpp v192, v192, v192 row_mirror row_mask:0xf bank_mask:0xf
	s_nop 1
	v_add_f32_dpp v192, v192, v192 row_bcast:15 row_mask:0xa bank_mask:0xf
	s_nop 1
	v_add_f32_dpp v192, v192, v192 row_bcast:31 row_mask:0xc bank_mask:0xf
	s_nop 1
	v_readlane_b32 s42, v192, 63
	s_nop 3
	s_mov_b32 s43, s42
	v_pk_fma_f32 v[160:161], s[42:43], v[196:197], v[160:161]
	v_pk_fma_f32 v[162:163], s[42:43], v[196:197], v[162:163]
	v_pk_fma_f32 v[164:165], s[42:43], v[196:197], v[164:165]
	v_pk_fma_f32 v[166:167], s[42:43], v[196:197], v[166:167]
	v_pk_fma_f32 v[168:169], s[42:43], v[196:197], v[168:169]
	v_pk_fma_f32 v[170:171], s[42:43], v[196:197], v[170:171]
	v_pk_fma_f32 v[172:173], s[42:43], v[196:197], v[172:173]
	v_pk_fma_f32 v[174:175], s[42:43], v[196:197], v[174:175]
	v_pk_mul_f32 v[176:177], v[160:161], v[160:161]
	v_pk_fma_f32 v[176:177], v[162:163], v[162:163], v[176:177]
	v_pk_fma_f32 v[176:177], v[164:165], v[164:165], v[176:177]
	v_pk_fma_f32 v[176:177], v[166:167], v[166:167], v[176:177]
	v_pk_fma_f32 v[176:177], v[168:169], v[168:169], v[176:177]
	v_pk_fma_f32 v[176:177], v[170:171], v[170:171], v[176:177]
	v_pk_fma_f32 v[176:177], v[172:173], v[172:173], v[176:177]
	v_pk_fma_f32 v[176:177], v[174:175], v[174:175], v[176:177]
	v_add_f32_e32 v194, v176, v177
	s_nop 1
	v_add_f32_dpp v192, v194, v194 quad_perm:[1,0,3,2] row_mask:0xf bank_mask:0xf
	s_nop 1
	v_add_f32_dpp v192, v192, v192 quad_perm:[2,3,0,1] row_mask:0xf bank_mask:0xf
	s_nop 1
	v_add_f32_dpp v192, v192, v192 row_half_mirror row_mask:0xf bank_mask:0xf
	s_nop 1
	v_add_f32_dpp v192, v192, v192 row_mirror row_mask:0xf bank_mask:0xf
	s_nop 1
	v_add_f32_dpp v192, v192, v192 row_bcast:15 row_mask:0xa bank_mask:0xf
	s_nop 1
	v_add_f32_dpp v192, v192, v192 row_bcast:31 row_mask:0xc bank_mask:0xf
	s_nop 1
	v_readlane_b32 s42, v192, 63
	s_nop 3
	v_fma_f32 v198, s42, v202, v203
	v_rsq_f32_e32 v198, v198
	s_nop 0
	v_pk_mul_f32 v[160:161], v[160:161], v[198:199] op_sel_hi:[1,0]
	v_pk_mul_f32 v[162:163], v[162:163], v[198:199] op_sel_hi:[1,0]
	v_pk_mul_f32 v[164:165], v[164:165], v[198:199] op_sel_hi:[1,0]
	v_pk_mul_f32 v[166:167], v[166:167], v[198:199] op_sel_hi:[1,0]
	v_pk_mul_f32 v[168:169], v[168:169], v[198:199] op_sel_hi:[1,0]
	v_pk_mul_f32 v[170:171], v[170:171], v[198:199] op_sel_hi:[1,0]
	v_pk_mul_f32 v[172:173], v[172:173], v[198:199] op_sel_hi:[1,0]
	v_pk_mul_f32 v[174:175], v[174:175], v[198:199] op_sel_hi:[1,0]
	v_pk_fma_f32 v[160:161], v[160:161], v[0:1], v[16:17]
	v_pk_fma_f32 v[162:163], v[162:163], v[2:3], v[18:19]
	v_pk_fma_f32 v[164:165], v[164:165], v[4:5], v[20:21]
	v_pk_fma_f32 v[166:167], v[166:167], v[6:7], v[22:23]
	v_pk_fma_f32 v[168:169], v[168:169], v[8:9], v[24:25]
	v_pk_fma_f32 v[170:171], v[170:171], v[10:11], v[26:27]
	v_pk_fma_f32 v[172:173], v[172:173], v[12:13], v[28:29]
	v_pk_fma_f32 v[174:175], v[174:175], v[14:15], v[30:31]
	global_store_dwordx4 v200, v[160:163], s[8:9] offset:0
	global_store_dwordx4 v200, v[164:167], s[8:9] offset:1024
	global_store_dwordx4 v200, v[168:171], s[8:9] offset:2048
	global_store_dwordx4 v200, v[172:175], s[8:9] offset:3072
	v_pk_add_f32 v[176:177], v[160:161], v[162:163]
	v_pk_add_f32 v[176:177], v[176:177], v[164:165]
	v_pk_add_f32 v[176:177], v[176:177], v[166:167]
	v_pk_add_f32 v[176:177], v[176:177], v[168:169]
	v_pk_add_f32 v[176:177], v[176:177], v[170:171]
	v_pk_add_f32 v[176:177], v[176:177], v[172:173]
	v_pk_add_f32 v[176:177], v[176:177], v[174:175]
	v_add_f32_e32 v194, v176, v177
	s_nop 1
	v_add_f32_dpp v192, v194, v194 quad_perm:[1,0,3,2] row_mask:0xf bank_mask:0xf
	s_nop 1
	v_add_f32_dpp v192, v192, v192 quad_perm:[2,3,0,1] row_mask:0xf bank_mask:0xf
	s_nop 1
	v_add_f32_dpp v192, v192, v192 row_half_mirror row_mask:0xf bank_mask:0xf
	s_nop 1
	v_add_f32_dpp v192, v192, v192 row_mirror row_mask:0xf bank_mask:0xf
	s_nop 1
	v_add_f32_dpp v192, v192, v192 row_bcast:15 row_mask:0xa bank_mask:0xf
	s_nop 1
	v_add_f32_dpp v192, v192, v192 row_bcast:31 row_mask:0xc bank_mask:0xf
	s_nop 1
	v_readlane_b32 s42, v192, 63
	s_nop 3
	s_mov_b32 s43, s42
	v_pk_fma_f32 v[160:161], s[42:43], v[196:197], v[160:161]
	v_pk_fma_f32 v[162:163], s[42:43], v[196:197], v[162:163]
	v_pk_fma_f32 v[164:165], s[42:43], v[196:197], v[164:165]
	v_pk_fma_f32 v[166:167], s[42:43], v[196:197], v[166:167]
	v_pk_fma_f32 v[168:169], s[42:43], v[196:197], v[168:169]
	v_pk_fma_f32 v[170:171], s[42:43], v[196:197], v[170:171]
	v_pk_fma_f32 v[172:173], s[42:43], v[196:197], v[172:173]
	v_pk_fma_f32 v[174:175], s[42:43], v[196:197], v[174:175]
	v_pk_mul_f32 v[176:177], v[160:161], v[160:161]
	v_pk_fma_f32 v[176:177], v[162:163], v[162:163], v[176:177]
	v_pk_fma_f32 v[176:177], v[164:165], v[164:165], v[176:177]
	v_pk_fma_f32 v[176:177], v[166:167], v[166:167], v[176:177]
	v_pk_fma_f32 v[176:177], v[168:169], v[168:169], v[176:177]
	v_pk_fma_f32 v[176:177], v[170:171], v[170:171], v[176:177]
	v_pk_fma_f32 v[176:177], v[172:173], v[172:173], v[176:177]
	v_pk_fma_f32 v[176:177], v[174:175], v[174:175], v[176:177]
	v_add_f32_e32 v194, v176, v177
	s_nop 1
	v_add_f32_dpp v192, v194, v194 quad_perm:[1,0,3,2] row_mask:0xf bank_mask:0xf
	s_nop 1
	v_add_f32_dpp v192, v192, v192 quad_perm:[2,3,0,1] row_mask:0xf bank_mask:0xf
	s_nop 1
	v_add_f32_dpp v192, v192, v192 row_half_mirror row_mask:0xf bank_mask:0xf
	s_nop 1
	v_add_f32_dpp v192, v192, v192 row_mirror row_mask:0xf bank_mask:0xf
	s_nop 1
	v_add_f32_dpp v192, v192, v192 row_bcast:15 row_mask:0xa bank_mask:0xf
	s_nop 1
	v_add_f32_dpp v192, v192, v192 row_bcast:31 row_mask:0xc bank_mask:0xf
	s_nop 1
	v_readlane_b32 s42, v192, 63
	s_nop 3
	v_fma_f32 v198, s42, v202, v203
	v_rsq_f32_e32 v198, v198
	s_nop 0
	v_pk_mul_f32 v[160:161], v[160:161], v[198:199] op_sel_hi:[1,0]
	v_pk_mul_f32 v[162:163], v[162:163], v[198:199] op_sel_hi:[1,0]
	v_pk_mul_f32 v[164:165], v[164:165], v[198:199] op_sel_hi:[1,0]
	v_pk_mul_f32 v[166:167], v[166:167], v[198:199] op_sel_hi:[1,0]
	v_pk_mul_f32 v[168:169], v[168:169], v[198:199] op_sel_hi:[1,0]
	v_pk_mul_f32 v[170:171], v[170:171], v[198:199] op_sel_hi:[1,0]
	v_pk_mul_f32 v[172:173], v[172:173], v[198:199] op_sel_hi:[1,0]
	v_pk_mul_f32 v[174:175], v[174:175], v[198:199] op_sel_hi:[1,0]
	v_pk_fma_f32 v[160:161], v[160:161], v[32:33], v[48:49]
	v_pk_fma_f32 v[162:163], v[162:163], v[34:35], v[50:51]
	v_pk_fma_f32 v[164:165], v[164:165], v[36:37], v[52:53]
	v_pk_fma_f32 v[166:167], v[166:167], v[38:39], v[54:55]
	v_pk_fma_f32 v[168:169], v[168:169], v[40:41], v[56:57]
	v_pk_fma_f32 v[170:171], v[170:171], v[42:43], v[58:59]
	v_pk_fma_f32 v[172:173], v[172:173], v[44:45], v[60:61]
	v_pk_fma_f32 v[174:175], v[174:175], v[46:47], v[62:63]
	v_cvt_pk_bf16_f32 v176, v160, v161
	v_cvt_pk_bf16_f32 v177, v162, v163
	v_cvt_pk_bf16_f32 v178, v164, v165
	v_cvt_pk_bf16_f32 v179, v166, v167
	v_cvt_pk_bf16_f32 v180, v168, v169
	v_cvt_pk_bf16_f32 v181, v170, v171
	v_cvt_pk_bf16_f32 v182, v172, v173
	v_cvt_pk_bf16_f32 v183, v174, v175
	global_store_dwordx2 v201, v[176:177], s[12:13] offset:0
	global_store_dwordx2 v201, v[178:179], s[12:13] offset:512
	global_store_dwordx2 v201, v[180:181], s[12:13] offset:1024
	global_store_dwordx2 v201, v[182:183], s[12:13] offset:1536
	s_add_u32 s8, s8, 0x1000
	s_addc_u32 s9, s9, 0
	s_add_u32 s12, s12, 0x800
	s_addc_u32 s13, s13, 0
	global_load_dwordx4 v[64:67], v200, s[2:3] offset:0
	global_load_dwordx4 v[68:71], v200, s[2:3] offset:1024
	global_load_dwordx4 v[72:75], v200, s[2:3] offset:2048
	global_load_dwordx4 v[76:79], v200, s[2:3] offset:3072
	global_load_dwordx2 v[128:129], v201, s[6:7] offset:0
	global_load_dwordx2 v[130:131], v201, s[6:7] offset:512
	global_load_dwordx2 v[132:133], v201, s[6:7] offset:1024
	global_load_dwordx2 v[134:135], v201, s[6:7] offset:1536
	s_add_u32 s2, s2, 0x1000
	s_addc_u32 s3, s3, 0
	s_add_u32 s6, s6, 0x800
	s_addc_u32 s7, s7, 0
	s_waitcnt vmcnt(48)
	v_lshlrev_b32_e32 v160, 16, v136
	v_and_b32_e32 v161, 0xffff0000, v136
	v_lshlrev_b32_e32 v162, 16, v137
	v_and_b32_e32 v163, 0xffff0000, v137
	v_lshlrev_b32_e32 v164, 16, v138
	v_and_b32_e32 v165, 0xffff0000, v138
	v_lshlrev_b32_e32 v166, 16, v139
	v_and_b32_e32 v167, 0xffff0000, v139
	v_lshlrev_b32_e32 v168, 16, v140
	v_and_b32_e32 v169, 0xffff0000, v140
	v_lshlrev_b32_e32 v170, 16, v141
	v_and_b32_e32 v171, 0xffff0000, v141
	v_lshlrev_b32_e32 v172, 16, v142
	v_and_b32_e32 v173, 0xffff0000, v142
	v_lshlrev_b32_e32 v174, 16, v143
	v_and_b32_e32 v175, 0xffff0000, v143
	v_pk_fma_f32 v[160:161], v[80:81], s[44:45], v[160:161]
	v_pk_fma_f32 v[162:163], v[82:83], s[44:45], v[162:163]
	v_pk_fma_f32 v[164:165], v[84:85], s[44:45], v[164:165]
	v_pk_fma_f32 v[166:167], v[86:87], s[44:45], v[166:167]
	v_pk_fma_f32 v[168:169], v[88:89], s[44:45], v[168:169]
	v_pk_fma_f32 v[170:171], v[90:91], s[44:45], v[170:171]
	v_pk_fma_f32 v[172:173], v[92:93], s[44:45], v[172:173]
	v_pk_fma_f32 v[174:175], v[94:95], s[44:45], v[174:175]
	v_pk_add_f32 v[176:177], v[160:161], v[162:163]
	v_pk_add_f32 v[176:177], v[176:177], v[164:165]
	v_pk_add_f32 v[176:177], v[176:177], v[166:167]
	v_pk_add_f32 v[176:177], v[176:177], v[168:169]
	v_pk_add_f32 v[176:177], v[176:177], v[170:171]
	v_pk_add_f32 v[176:177], v[176:177], v[172:173]
	v_pk_add_f32 v[176:177], v[176:177], v[174:175]
	v_add_f32_e32 v194, v176, v177
	s_nop 1
	v_add_f32_dpp v192, v194, v194 quad_perm:[1,0,3,2] row_mask:0xf bank_mask:0xf
	s_nop 1
	v_add_f32_dpp v192, v192, v192 quad_perm:[2,3,0,1] row_mask:0xf bank_mask:0xf
	s_nop 1
	v_add_f32_dpp v192, v192, v192 row_half_mirror row_mask:0xf bank_mask:0xf
	s_nop 1
	v_add_f32_dpp v192, v192, v192 row_mirror row_mask:0xf bank_mask:0xf
	s_nop 1
	v_add_f32_dpp v192, v192, v192 row_bcast:15 row_mask:0xa bank_mask:0xf
	s_nop 1
	v_add_f32_dpp v192, v192, v192 row_bcast:31 row_mask:0xc bank_mask:0xf
	s_nop 1
	v_readlane_b32 s42, v192, 63
	s_nop 3
	s_mov_b32 s43, s42
	v_pk_fma_f32 v[160:161], s[42:43], v[196:197], v[160:161]
	v_pk_fma_f32 v[162:163], s[42:43], v[196:197], v[162:163]
	v_pk_fma_f32 v[164:165], s[42:43], v[196:197], v[164:165]
	v_pk_fma_f32 v[166:167], s[42:43], v[196:197], v[166:167]
	v_pk_fma_f32 v[168:169], s[42:43], v[196:197], v[168:169]
	v_pk_fma_f32 v[170:171], s[42:43], v[196:197], v[170:171]
	v_pk_fma_f32 v[172:173], s[42:43], v[196:197], v[172:173]
	v_pk_fma_f32 v[174:175], s[42:43], v[196:197], v[174:175]
	v_pk_mul_f32 v[176:177], v[160:161], v[160:161]
	v_pk_fma_f32 v[176:177], v[162:163], v[162:163], v[176:177]
	v_pk_fma_f32 v[176:177], v[164:165], v[164:165], v[176:177]
	v_pk_fma_f32 v[176:177], v[166:167], v[166:167], v[176:177]
	v_pk_fma_f32 v[176:177], v[168:169], v[168:169], v[176:177]
	v_pk_fma_f32 v[176:177], v[170:171], v[170:171], v[176:177]
	v_pk_fma_f32 v[176:177], v[172:173], v[172:173], v[176:177]
	v_pk_fma_f32 v[176:177], v[174:175], v[174:175], v[176:177]
	v_add_f32_e32 v194, v176, v177
	s_nop 1
	v_add_f32_dpp v192, v194, v194 quad_perm:[1,0,3,2] row_mask:0xf bank_mask:0xf
	s_nop 1
	v_add_f32_dpp v192, v192, v192 quad_perm:[2,3,0,1] row_mask:0xf bank_mask:0xf
	s_nop 1
	v_add_f32_dpp v192, v192, v192 row_half_mirror row_mask:0xf bank_mask:0xf
	s_nop 1
	v_add_f32_dpp v192, v192, v192 row_mirror row_mask:0xf bank_mask:0xf
	s_nop 1
	v_add_f32_dpp v192, v192, v192 row_bcast:15 row_mask:0xa bank_mask:0xf
	s_nop 1
	v_add_f32_dpp v192, v192, v192 row_bcast:31 row_mask:0xc bank_mask:0xf
	s_nop 1
	v_readlane_b32 s42, v192, 63
	s_nop 3
	v_fma_f32 v198, s42, v202, v203
	v_rsq_f32_e32 v198, v198
	s_nop 0
	v_pk_mul_f32 v[160:161], v[160:161], v[198:199] op_sel_hi:[1,0]
	v_pk_mul_f32 v[162:163], v[162:163], v[198:199] op_sel_hi:[1,0]
	v_pk_mul_f32 v[164:165], v[164:165], v[198:199] op_sel_hi:[1,0]
	v_pk_mul_f32 v[166:167], v[166:167], v[198:199] op_sel_hi:[1,0]
	v_pk_mul_f32 v[168:169], v[168:169], v[198:199] op_sel_hi:[1,0]
	v_pk_mul_f32 v[170:171], v[170:171], v[198:199] op_sel_hi:[1,0]
	v_pk_mul_f32 v[172:173], v[172:173], v[198:199] op_sel_hi:[1,0]
	v_pk_mul_f32 v[174:175], v[174:175], v[198:199] op_sel_hi:[1,0]
	v_pk_fma_f32 v[160:161], v[160:161], v[0:1], v[16:17]
	v_pk_fma_f32 v[162:163], v[162:163], v[2:3], v[18:19]
	v_pk_fma_f32 v[164:165], v[164:165], v[4:5], v[20:21]
	v_pk_fma_f32 v[166:167], v[166:167], v[6:7], v[22:23]
	v_pk_fma_f32 v[168:169], v[168:169], v[8:9], v[24:25]
	v_pk_fma_f32 v[170:171], v[170:171], v[10:11], v[26:27]
	v_pk_fma_f32 v[172:173], v[172:173], v[12:13], v[28:29]
	v_pk_fma_f32 v[174:175], v[174:175], v[14:15], v[30:31]
	global_store_dwordx4 v200, v[160:163], s[8:9] offset:0
	global_store_dwordx4 v200, v[164:167], s[8:9] offset:1024
	global_store_dwordx4 v200, v[168:171], s[8:9] offset:2048
	global_store_dwordx4 v200, v[172:175], s[8:9] offset:3072
	v_pk_add_f32 v[176:177], v[160:161], v[162:163]
	v_pk_add_f32 v[176:177], v[176:177], v[164:165]
	v_pk_add_f32 v[176:177], v[176:177], v[166:167]
	v_pk_add_f32 v[176:177], v[176:177], v[168:169]
	v_pk_add_f32 v[176:177], v[176:177], v[170:171]
	v_pk_add_f32 v[176:177], v[176:177], v[172:173]
	v_pk_add_f32 v[176:177], v[176:177], v[174:175]
	v_add_f32_e32 v194, v176, v177
	s_nop 1
	v_add_f32_dpp v192, v194, v194 quad_perm:[1,0,3,2] row_mask:0xf bank_mask:0xf
	s_nop 1
	v_add_f32_dpp v192, v192, v192 quad_perm:[2,3,0,1] row_mask:0xf bank_mask:0xf
	s_nop 1
	v_add_f32_dpp v192, v192, v192 row_half_mirror row_mask:0xf bank_mask:0xf
	s_nop 1
	v_add_f32_dpp v192, v192, v192 row_mirror row_mask:0xf bank_mask:0xf
	s_nop 1
	v_add_f32_dpp v192, v192, v192 row_bcast:15 row_mask:0xa bank_mask:0xf
	s_nop 1
	v_add_f32_dpp v192, v192, v192 row_bcast:31 row_mask:0xc bank_mask:0xf
	s_nop 1
	v_readlane_b32 s42, v192, 63
	s_nop 3
	s_mov_b32 s43, s42
	v_pk_fma_f32 v[160:161], s[42:43], v[196:197], v[160:161]
	v_pk_fma_f32 v[162:163], s[42:43], v[196:197], v[162:163]
	v_pk_fma_f32 v[164:165], s[42:43], v[196:197], v[164:165]
	v_pk_fma_f32 v[166:167], s[42:43], v[196:197], v[166:167]
	v_pk_fma_f32 v[168:169], s[42:43], v[196:197], v[168:169]
	v_pk_fma_f32 v[170:171], s[42:43], v[196:197], v[170:171]
	v_pk_fma_f32 v[172:173], s[42:43], v[196:197], v[172:173]
	v_pk_fma_f32 v[174:175], s[42:43], v[196:197], v[174:175]
	v_pk_mul_f32 v[176:177], v[160:161], v[160:161]
	v_pk_fma_f32 v[176:177], v[162:163], v[162:163], v[176:177]
	v_pk_fma_f32 v[176:177], v[164:165], v[164:165], v[176:177]
	v_pk_fma_f32 v[176:177], v[166:167], v[166:167], v[176:177]
	v_pk_fma_f32 v[176:177], v[168:169], v[168:169], v[176:177]
	v_pk_fma_f32 v[176:177], v[170:171], v[170:171], v[176:177]
	v_pk_fma_f32 v[176:177], v[172:173], v[172:173], v[176:177]
	v_pk_fma_f32 v[176:177], v[174:175], v[174:175], v[176:177]
	v_add_f32_e32 v194, v176, v177
	s_nop 1
	v_add_f32_dpp v192, v194, v194 quad_perm:[1,0,3,2] row_mask:0xf bank_mask:0xf
	s_nop 1
	v_add_f32_dpp v192, v192, v192 quad_perm:[2,3,0,1] row_mask:0xf bank_mask:0xf
	s_nop 1
	v_add_f32_dpp v192, v192, v192 row_half_mirror row_mask:0xf bank_mask:0xf
	s_nop 1
	v_add_f32_dpp v192, v192, v192 row_mirror row_mask:0xf bank_mask:0xf
	s_nop 1
	v_add_f32_dpp v192, v192, v192 row_bcast:15 row_mask:0xa bank_mask:0xf
	s_nop 1
	v_add_f32_dpp v192, v192, v192 row_bcast:31 row_mask:0xc bank_mask:0xf
	s_nop 1
	v_readlane_b32 s42, v192, 63
	s_nop 3
	v_fma_f32 v198, s42, v202, v203
	v_rsq_f32_e32 v198, v198
	s_nop 0
	v_pk_mul_f32 v[160:161], v[160:161], v[198:199] op_sel_hi:[1,0]
	v_pk_mul_f32 v[162:163], v[162:163], v[198:199] op_sel_hi:[1,0]
	v_pk_mul_f32 v[164:165], v[164:165], v[198:199] op_sel_hi:[1,0]
	v_pk_mul_f32 v[166:167], v[166:167], v[198:199] op_sel_hi:[1,0]
	v_pk_mul_f32 v[168:169], v[168:169], v[198:199] op_sel_hi:[1,0]
	v_pk_mul_f32 v[170:171], v[170:171], v[198:199] op_sel_hi:[1,0]
	v_pk_mul_f32 v[172:173], v[172:173], v[198:199] op_sel_hi:[1,0]
	v_pk_mul_f32 v[174:175], v[174:175], v[198:199] op_sel_hi:[1,0]
	v_pk_fma_f32 v[160:161], v[160:161], v[32:33], v[48:49]
	v_pk_fma_f32 v[162:163], v[162:163], v[34:35], v[50:51]
	v_pk_fma_f32 v[164:165], v[164:165], v[36:37], v[52:53]
	v_pk_fma_f32 v[166:167], v[166:167], v[38:39], v[54:55]
	v_pk_fma_f32 v[168:169], v[168:169], v[40:41], v[56:57]
	v_pk_fma_f32 v[170:171], v[170:171], v[42:43], v[58:59]
	v_pk_fma_f32 v[172:173], v[172:173], v[44:45], v[60:61]
	v_pk_fma_f32 v[174:175], v[174:175], v[46:47], v[62:63]
	v_cvt_pk_bf16_f32 v176, v160, v161
	v_cvt_pk_bf16_f32 v177, v162, v163
	v_cvt_pk_bf16_f32 v178, v164, v165
	v_cvt_pk_bf16_f32 v179, v166, v167
	v_cvt_pk_bf16_f32 v180, v168, v169
	v_cvt_pk_bf16_f32 v181, v170, v171
	v_cvt_pk_bf16_f32 v182, v172, v173
	v_cvt_pk_bf16_f32 v183, v174, v175
	global_store_dwordx2 v201, v[176:177], s[12:13] offset:0
	global_store_dwordx2 v201, v[178:179], s[12:13] offset:512
	global_store_dwordx2 v201, v[180:181], s[12:13] offset:1024
	global_store_dwordx2 v201, v[182:183], s[12:13] offset:1536
	s_add_u32 s8, s8, 0x1000
	s_addc_u32 s9, s9, 0
	s_add_u32 s12, s12, 0x800
	s_addc_u32 s13, s13, 0
	global_load_dwordx4 v[80:83], v200, s[2:3] offset:0
	global_load_dwordx4 v[84:87], v200, s[2:3] offset:1024
	global_load_dwordx4 v[88:91], v200, s[2:3] offset:2048
	global_load_dwordx4 v[92:95], v200, s[2:3] offset:3072
	global_load_dwordx2 v[136:137], v201, s[6:7] offset:0
	global_load_dwordx2 v[138:139], v201, s[6:7] offset:512
	global_load_dwordx2 v[140:141], v201, s[6:7] offset:1024
	global_load_dwordx2 v[142:143], v201, s[6:7] offset:1536
	s_add_u32 s2, s2, 0x1000
	s_addc_u32 s3, s3, 0
	s_add_u32 s6, s6, 0x800
	s_addc_u32 s7, s7, 0
	s_waitcnt vmcnt(48)
	v_lshlrev_b32_e32 v160, 16, v144
	v_and_b32_e32 v161, 0xffff0000, v144
	v_lshlrev_b32_e32 v162, 16, v145
	v_and_b32_e32 v163, 0xffff0000, v145
	v_lshlrev_b32_e32 v164, 16, v146
	v_and_b32_e32 v165, 0xffff0000, v146
	v_lshlrev_b32_e32 v166, 16, v147
	v_and_b32_e32 v167, 0xffff0000, v147
	v_lshlrev_b32_e32 v168, 16, v148
	v_and_b32_e32 v169, 0xffff0000, v148
	v_lshlrev_b32_e32 v170, 16, v149
	v_and_b32_e32 v171, 0xffff0000, v149
	v_lshlrev_b32_e32 v172, 16, v150
	v_and_b32_e32 v173, 0xffff0000, v150
	v_lshlrev_b32_e32 v174, 16, v151
	v_and_b32_e32 v175, 0xffff0000, v151
	v_pk_fma_f32 v[160:161], v[96:97], s[44:45], v[160:161]
	v_pk_fma_f32 v[162:163], v[98:99], s[44:45], v[162:163]
	v_pk_fma_f32 v[164:165], v[100:101], s[44:45], v[164:165]
	v_pk_fma_f32 v[166:167], v[102:103], s[44:45], v[166:167]
	v_pk_fma_f32 v[168:169], v[104:105], s[44:45], v[168:169]
	v_pk_fma_f32 v[170:171], v[106:107], s[44:45], v[170:171]
	v_pk_fma_f32 v[172:173], v[108:109], s[44:45], v[172:173]
	v_pk_fma_f32 v[174:175], v[110:111], s[44:45], v[174:175]
	v_pk_add_f32 v[176:177], v[160:161], v[162:163]
	v_pk_add_f32 v[176:177], v[176:177], v[164:165]
	v_pk_add_f32 v[176:177], v[176:177], v[166:167]
	v_pk_add_f32 v[176:177], v[176:177], v[168:169]
	v_pk_add_f32 v[176:177], v[176:177], v[170:171]
	v_pk_add_f32 v[176:177], v[176:177], v[172:173]
	v_pk_add_f32 v[176:177], v[176:177], v[174:175]
	v_add_f32_e32 v194, v176, v177
	s_nop 1
	v_add_f32_dpp v192, v194, v194 quad_perm:[1,0,3,2] row_mask:0xf bank_mask:0xf
	s_nop 1
	v_add_f32_dpp v192, v192, v192 quad_perm:[2,3,0,1] row_mask:0xf bank_mask:0xf
	s_nop 1
	v_add_f32_dpp v192, v192, v192 row_half_mirror row_mask:0xf bank_mask:0xf
	s_nop 1
	v_add_f32_dpp v192, v192, v192 row_mirror row_mask:0xf bank_mask:0xf
	s_nop 1
	v_add_f32_dpp v192, v192, v192 row_bcast:15 row_mask:0xa bank_mask:0xf
	s_nop 1
	v_add_f32_dpp v192, v192, v192 row_bcast:31 row_mask:0xc bank_mask:0xf
	s_nop 1
	v_readlane_b32 s42, v192, 63
	s_nop 3
	s_mov_b32 s43, s42
	v_pk_fma_f32 v[160:161], s[42:43], v[196:197], v[160:161]
	v_pk_fma_f32 v[162:163], s[42:43], v[196:197], v[162:163]
	v_pk_fma_f32 v[164:165], s[42:43], v[196:197], v[164:165]
	v_pk_fma_f32 v[166:167], s[42:43], v[196:197], v[166:167]
	v_pk_fma_f32 v[168:169], s[42:43], v[196:197], v[168:169]
	v_pk_fma_f32 v[170:171], s[42:43], v[196:197], v[170:171]
	v_pk_fma_f32 v[172:173], s[42:43], v[196:197], v[172:173]
	v_pk_fma_f32 v[174:175], s[42:43], v[196:197], v[174:175]
	v_pk_mul_f32 v[176:177], v[160:161], v[160:161]
	v_pk_fma_f32 v[176:177], v[162:163], v[162:163], v[176:177]
	v_pk_fma_f32 v[176:177], v[164:165], v[164:165], v[176:177]
	v_pk_fma_f32 v[176:177], v[166:167], v[166:167], v[176:177]
	v_pk_fma_f32 v[176:177], v[168:169], v[168:169], v[176:177]
	v_pk_fma_f32 v[176:177], v[170:171], v[170:171], v[176:177]
	v_pk_fma_f32 v[176:177], v[172:173], v[172:173], v[176:177]
	v_pk_fma_f32 v[176:177], v[174:175], v[174:175], v[176:177]
	v_add_f32_e32 v194, v176, v177
	s_nop 1
	v_add_f32_dpp v192, v194, v194 quad_perm:[1,0,3,2] row_mask:0xf bank_mask:0xf
	s_nop 1
	v_add_f32_dpp v192, v192, v192 quad_perm:[2,3,0,1] row_mask:0xf bank_mask:0xf
	s_nop 1
	v_add_f32_dpp v192, v192, v192 row_half_mirror row_mask:0xf bank_mask:0xf
	s_nop 1
	v_add_f32_dpp v192, v192, v192 row_mirror row_mask:0xf bank_mask:0xf
	s_nop 1
	v_add_f32_dpp v192, v192, v192 row_bcast:15 row_mask:0xa bank_mask:0xf
	s_nop 1
	v_add_f32_dpp v192, v192, v192 row_bcast:31 row_mask:0xc bank_mask:0xf
	s_nop 1
	v_readlane_b32 s42, v192, 63
	s_nop 3
	v_fma_f32 v198, s42, v202, v203
	v_rsq_f32_e32 v198, v198
	s_nop 0
	v_pk_mul_f32 v[160:161], v[160:161], v[198:199] op_sel_hi:[1,0]
	v_pk_mul_f32 v[162:163], v[162:163], v[198:199] op_sel_hi:[1,0]
	v_pk_mul_f32 v[164:165], v[164:165], v[198:199] op_sel_hi:[1,0]
	v_pk_mul_f32 v[166:167], v[166:167], v[198:199] op_sel_hi:[1,0]
	v_pk_mul_f32 v[168:169], v[168:169], v[198:199] op_sel_hi:[1,0]
	v_pk_mul_f32 v[170:171], v[170:171], v[198:199] op_sel_hi:[1,0]
	v_pk_mul_f32 v[172:173], v[172:173], v[198:199] op_sel_hi:[1,0]
	v_pk_mul_f32 v[174:175], v[174:175], v[198:199] op_sel_hi:[1,0]
	v_pk_fma_f32 v[160:161], v[160:161], v[0:1], v[16:17]
	v_pk_fma_f32 v[162:163], v[162:163], v[2:3], v[18:19]
	v_pk_fma_f32 v[164:165], v[164:165], v[4:5], v[20:21]
	v_pk_fma_f32 v[166:167], v[166:167], v[6:7], v[22:23]
	v_pk_fma_f32 v[168:169], v[168:169], v[8:9], v[24:25]
	v_pk_fma_f32 v[170:171], v[170:171], v[10:11], v[26:27]
	v_pk_fma_f32 v[172:173], v[172:173], v[12:13], v[28:29]
	v_pk_fma_f32 v[174:175], v[174:175], v[14:15], v[30:31]
	global_store_dwordx4 v200, v[160:163], s[8:9] offset:0
	global_store_dwordx4 v200, v[164:167], s[8:9] offset:1024
	global_store_dwordx4 v200, v[168:171], s[8:9] offset:2048
	global_store_dwordx4 v200, v[172:175], s[8:9] offset:3072
	v_pk_add_f32 v[176:177], v[160:161], v[162:163]
	v_pk_add_f32 v[176:177], v[176:177], v[164:165]
	v_pk_add_f32 v[176:177], v[176:177], v[166:167]
	v_pk_add_f32 v[176:177], v[176:177], v[168:169]
	v_pk_add_f32 v[176:177], v[176:177], v[170:171]
	v_pk_add_f32 v[176:177], v[176:177], v[172:173]
	v_pk_add_f32 v[176:177], v[176:177], v[174:175]
	v_add_f32_e32 v194, v176, v177
	s_nop 1
	v_add_f32_dpp v192, v194, v194 quad_perm:[1,0,3,2] row_mask:0xf bank_mask:0xf
	s_nop 1
	v_add_f32_dpp v192, v192, v192 quad_perm:[2,3,0,1] row_mask:0xf bank_mask:0xf
	s_nop 1
	v_add_f32_dpp v192, v192, v192 row_half_mirror row_mask:0xf bank_mask:0xf
	s_nop 1
	v_add_f32_dpp v192, v192, v192 row_mirror row_mask:0xf bank_mask:0xf
	s_nop 1
	v_add_f32_dpp v192, v192, v192 row_bcast:15 row_mask:0xa bank_mask:0xf
	s_nop 1
	v_add_f32_dpp v192, v192, v192 row_bcast:31 row_mask:0xc bank_mask:0xf
	s_nop 1
	v_readlane_b32 s42, v192, 63
	s_nop 3
	s_mov_b32 s43, s42
	v_pk_fma_f32 v[160:161], s[42:43], v[196:197], v[160:161]
	v_pk_fma_f32 v[162:163], s[42:43], v[196:197], v[162:163]
	v_pk_fma_f32 v[164:165], s[42:43], v[196:197], v[164:165]
	v_pk_fma_f32 v[166:167], s[42:43], v[196:197], v[166:167]
	v_pk_fma_f32 v[168:169], s[42:43], v[196:197], v[168:169]
	v_pk_fma_f32 v[170:171], s[42:43], v[196:197], v[170:171]
	v_pk_fma_f32 v[172:173], s[42:43], v[196:197], v[172:173]
	v_pk_fma_f32 v[174:175], s[42:43], v[196:197], v[174:175]
	v_pk_mul_f32 v[176:177], v[160:161], v[160:161]
	v_pk_fma_f32 v[176:177], v[162:163], v[162:163], v[176:177]
	v_pk_fma_f32 v[176:177], v[164:165], v[164:165], v[176:177]
	v_pk_fma_f32 v[176:177], v[166:167], v[166:167], v[176:177]
	v_pk_fma_f32 v[176:177], v[168:169], v[168:169], v[176:177]
	v_pk_fma_f32 v[176:177], v[170:171], v[170:171], v[176:177]
	v_pk_fma_f32 v[176:177], v[172:173], v[172:173], v[176:177]
	v_pk_fma_f32 v[176:177], v[174:175], v[174:175], v[176:177]
	v_add_f32_e32 v194, v176, v177
	s_nop 1
	v_add_f32_dpp v192, v194, v194 quad_perm:[1,0,3,2] row_mask:0xf bank_mask:0xf
	s_nop 1
	v_add_f32_dpp v192, v192, v192 quad_perm:[2,3,0,1] row_mask:0xf bank_mask:0xf
	s_nop 1
	v_add_f32_dpp v192, v192, v192 row_half_mirror row_mask:0xf bank_mask:0xf
	s_nop 1
	v_add_f32_dpp v192, v192, v192 row_mirror row_mask:0xf bank_mask:0xf
	s_nop 1
	v_add_f32_dpp v192, v192, v192 row_bcast:15 row_mask:0xa bank_mask:0xf
	s_nop 1
	v_add_f32_dpp v192, v192, v192 row_bcast:31 row_mask:0xc bank_mask:0xf
	s_nop 1
	v_readlane_b32 s42, v192, 63
	s_nop 3
	v_fma_f32 v198, s42, v202, v203
	v_rsq_f32_e32 v198, v198
	s_nop 0
	v_pk_mul_f32 v[160:161], v[160:161], v[198:199] op_sel_hi:[1,0]
	v_pk_mul_f32 v[162:163], v[162:163], v[198:199] op_sel_hi:[1,0]
	v_pk_mul_f32 v[164:165], v[164:165], v[198:199] op_sel_hi:[1,0]
	v_pk_mul_f32 v[166:167], v[166:167], v[198:199] op_sel_hi:[1,0]
	v_pk_mul_f32 v[168:169], v[168:169], v[198:199] op_sel_hi:[1,0]
	v_pk_mul_f32 v[170:171], v[170:171], v[198:199] op_sel_hi:[1,0]
	v_pk_mul_f32 v[172:173], v[172:173], v[198:199] op_sel_hi:[1,0]
	v_pk_mul_f32 v[174:175], v[174:175], v[198:199] op_sel_hi:[1,0]
	v_pk_fma_f32 v[160:161], v[160:161], v[32:33], v[48:49]
	v_pk_fma_f32 v[162:163], v[162:163], v[34:35], v[50:51]
	v_pk_fma_f32 v[164:165], v[164:165], v[36:37], v[52:53]
	v_pk_fma_f32 v[166:167], v[166:167], v[38:39], v[54:55]
	v_pk_fma_f32 v[168:169], v[168:169], v[40:41], v[56:57]
	v_pk_fma_f32 v[170:171], v[170:171], v[42:43], v[58:59]
	v_pk_fma_f32 v[172:173], v[172:173], v[44:45], v[60:61]
	v_pk_fma_f32 v[174:175], v[174:175], v[46:47], v[62:63]
	v_cvt_pk_bf16_f32 v176, v160, v161
	v_cvt_pk_bf16_f32 v177, v162, v163
	v_cvt_pk_bf16_f32 v178, v164, v165
	v_cvt_pk_bf16_f32 v179, v166, v167
	v_cvt_pk_bf16_f32 v180, v168, v169
	v_cvt_pk_bf16_f32 v181, v170, v171
	v_cvt_pk_bf16_f32 v182, v172, v173
	v_cvt_pk_bf16_f32 v183, v174, v175
	global_store_dwordx2 v201, v[176:177], s[12:13] offset:0
	global_store_dwordx2 v201, v[178:179], s[12:13] offset:512
	global_store_dwordx2 v201, v[180:181], s[12:13] offset:1024
	global_store_dwordx2 v201, v[182:183], s[12:13] offset:1536
	s_add_u32 s8, s8, 0x1000
	s_addc_u32 s9, s9, 0
	s_add_u32 s12, s12, 0x800
	s_addc_u32 s13, s13, 0
	global_load_dwordx4 v[96:99], v200, s[2:3] offset:0
	global_load_dwordx4 v[100:103], v200, s[2:3] offset:1024
	global_load_dwordx4 v[104:107], v200, s[2:3] offset:2048
	global_load_dwordx4 v[108:111], v200, s[2:3] offset:3072
	global_load_dwordx2 v[144:145], v201, s[6:7] offset:0
	global_load_dwordx2 v[146:147], v201, s[6:7] offset:512
	global_load_dwordx2 v[148:149], v201, s[6:7] offset:1024
	global_load_dwordx2 v[150:151], v201, s[6:7] offset:1536
	s_add_u32 s2, s2, 0x1000
	s_addc_u32 s3, s3, 0
	s_add_u32 s6, s6, 0x800
	s_addc_u32 s7, s7, 0
	s_waitcnt vmcnt(48)
	v_lshlrev_b32_e32 v160, 16, v152
	v_and_b32_e32 v161, 0xffff0000, v152
	v_lshlrev_b32_e32 v162, 16, v153
	v_and_b32_e32 v163, 0xffff0000, v153
	v_lshlrev_b32_e32 v164, 16, v154
	v_and_b32_e32 v165, 0xffff0000, v154
	v_lshlrev_b32_e32 v166, 16, v155
	v_and_b32_e32 v167, 0xffff0000, v155
	v_lshlrev_b32_e32 v168, 16, v156
	v_and_b32_e32 v169, 0xffff0000, v156
	v_lshlrev_b32_e32 v170, 16, v157
	v_and_b32_e32 v171, 0xffff0000, v157
	v_lshlrev_b32_e32 v172, 16, v158
	v_and_b32_e32 v173, 0xffff0000, v158
	v_lshlrev_b32_e32 v174, 16, v159
	v_and_b32_e32 v175, 0xffff0000, v159
	v_pk_fma_f32 v[160:161], v[112:113], s[44:45], v[160:161]
	v_pk_fma_f32 v[162:163], v[114:115], s[44:45], v[162:163]
	v_pk_fma_f32 v[164:165], v[116:117], s[44:45], v[164:165]
	v_pk_fma_f32 v[166:167], v[118:119], s[44:45], v[166:167]
	v_pk_fma_f32 v[168:169], v[120:121], s[44:45], v[168:169]
	v_pk_fma_f32 v[170:171], v[122:123], s[44:45], v[170:171]
	v_pk_fma_f32 v[172:173], v[124:125], s[44:45], v[172:173]
	v_pk_fma_f32 v[174:175], v[126:127], s[44:45], v[174:175]
	v_pk_add_f32 v[176:177], v[160:161], v[162:163]
	v_pk_add_f32 v[176:177], v[176:177], v[164:165]
	v_pk_add_f32 v[176:177], v[176:177], v[166:167]
	v_pk_add_f32 v[176:177], v[176:177], v[168:169]
	v_pk_add_f32 v[176:177], v[176:177], v[170:171]
	v_pk_add_f32 v[176:177], v[176:177], v[172:173]
	v_pk_add_f32 v[176:177], v[176:177], v[174:175]
	v_add_f32_e32 v194, v176, v177
	s_nop 1
	v_add_f32_dpp v192, v194, v194 quad_perm:[1,0,3,2] row_mask:0xf bank_mask:0xf
	s_nop 1
	v_add_f32_dpp v192, v192, v192 quad_perm:[2,3,0,1] row_mask:0xf bank_mask:0xf
	s_nop 1
	v_add_f32_dpp v192, v192, v192 row_half_mirror row_mask:0xf bank_mask:0xf
	s_nop 1
	v_add_f32_dpp v192, v192, v192 row_mirror row_mask:0xf bank_mask:0xf
	s_nop 1
	v_add_f32_dpp v192, v192, v192 row_bcast:15 row_mask:0xa bank_mask:0xf
	s_nop 1
	v_add_f32_dpp v192, v192, v192 row_bcast:31 row_mask:0xc bank_mask:0xf
	s_nop 1
	v_readlane_b32 s42, v192, 63
	s_nop 3
	s_mov_b32 s43, s42
	v_pk_fma_f32 v[160:161], s[42:43], v[196:197], v[160:161]
	v_pk_fma_f32 v[162:163], s[42:43], v[196:197], v[162:163]
	v_pk_fma_f32 v[164:165], s[42:43], v[196:197], v[164:165]
	v_pk_fma_f32 v[166:167], s[42:43], v[196:197], v[166:167]
	v_pk_fma_f32 v[168:169], s[42:43], v[196:197], v[168:169]
	v_pk_fma_f32 v[170:171], s[42:43], v[196:197], v[170:171]
	v_pk_fma_f32 v[172:173], s[42:43], v[196:197], v[172:173]
	v_pk_fma_f32 v[174:175], s[42:43], v[196:197], v[174:175]
	v_pk_mul_f32 v[176:177], v[160:161], v[160:161]
	v_pk_fma_f32 v[176:177], v[162:163], v[162:163], v[176:177]
	v_pk_fma_f32 v[176:177], v[164:165], v[164:165], v[176:177]
	v_pk_fma_f32 v[176:177], v[166:167], v[166:167], v[176:177]
	v_pk_fma_f32 v[176:177], v[168:169], v[168:169], v[176:177]
	v_pk_fma_f32 v[176:177], v[170:171], v[170:171], v[176:177]
	v_pk_fma_f32 v[176:177], v[172:173], v[172:173], v[176:177]
	v_pk_fma_f32 v[176:177], v[174:175], v[174:175], v[176:177]
	v_add_f32_e32 v194, v176, v177
	s_nop 1
	v_add_f32_dpp v192, v194, v194 quad_perm:[1,0,3,2] row_mask:0xf bank_mask:0xf
	s_nop 1
	v_add_f32_dpp v192, v192, v192 quad_perm:[2,3,0,1] row_mask:0xf bank_mask:0xf
	s_nop 1
	v_add_f32_dpp v192, v192, v192 row_half_mirror row_mask:0xf bank_mask:0xf
	s_nop 1
	v_add_f32_dpp v192, v192, v192 row_mirror row_mask:0xf bank_mask:0xf
	s_nop 1
	v_add_f32_dpp v192, v192, v192 row_bcast:15 row_mask:0xa bank_mask:0xf
	s_nop 1
	v_add_f32_dpp v192, v192, v192 row_bcast:31 row_mask:0xc bank_mask:0xf
	s_nop 1
	v_readlane_b32 s42, v192, 63
	s_nop 3
	v_fma_f32 v198, s42, v202, v203
	v_rsq_f32_e32 v198, v198
	s_nop 0
	v_pk_mul_f32 v[160:161], v[160:161], v[198:199] op_sel_hi:[1,0]
	v_pk_mul_f32 v[162:163], v[162:163], v[198:199] op_sel_hi:[1,0]
	v_pk_mul_f32 v[164:165], v[164:165], v[198:199] op_sel_hi:[1,0]
	v_pk_mul_f32 v[166:167], v[166:167], v[198:199] op_sel_hi:[1,0]
	v_pk_mul_f32 v[168:169], v[168:169], v[198:199] op_sel_hi:[1,0]
	v_pk_mul_f32 v[170:171], v[170:171], v[198:199] op_sel_hi:[1,0]
	v_pk_mul_f32 v[172:173], v[172:173], v[198:199] op_sel_hi:[1,0]
	v_pk_mul_f32 v[174:175], v[174:175], v[198:199] op_sel_hi:[1,0]
	v_pk_fma_f32 v[160:161], v[160:161], v[0:1], v[16:17]
	v_pk_fma_f32 v[162:163], v[162:163], v[2:3], v[18:19]
	v_pk_fma_f32 v[164:165], v[164:165], v[4:5], v[20:21]
	v_pk_fma_f32 v[166:167], v[166:167], v[6:7], v[22:23]
	v_pk_fma_f32 v[168:169], v[168:169], v[8:9], v[24:25]
	v_pk_fma_f32 v[170:171], v[170:171], v[10:11], v[26:27]
	v_pk_fma_f32 v[172:173], v[172:173], v[12:13], v[28:29]
	v_pk_fma_f32 v[174:175], v[174:175], v[14:15], v[30:31]
	global_store_dwordx4 v200, v[160:163], s[8:9] offset:0
	global_store_dwordx4 v200, v[164:167], s[8:9] offset:1024
	global_store_dwordx4 v200, v[168:171], s[8:9] offset:2048
	global_store_dwordx4 v200, v[172:175], s[8:9] offset:3072
	v_pk_add_f32 v[176:177], v[160:161], v[162:163]
	v_pk_add_f32 v[176:177], v[176:177], v[164:165]
	v_pk_add_f32 v[176:177], v[176:177], v[166:167]
	v_pk_add_f32 v[176:177], v[176:177], v[168:169]
	v_pk_add_f32 v[176:177], v[176:177], v[170:171]
	v_pk_add_f32 v[176:177], v[176:177], v[172:173]
	v_pk_add_f32 v[176:177], v[176:177], v[174:175]
	v_add_f32_e32 v194, v176, v177
	s_nop 1
	v_add_f32_dpp v192, v194, v194 quad_perm:[1,0,3,2] row_mask:0xf bank_mask:0xf
	s_nop 1
	v_add_f32_dpp v192, v192, v192 quad_perm:[2,3,0,1] row_mask:0xf bank_mask:0xf
	s_nop 1
	v_add_f32_dpp v192, v192, v192 row_half_mirror row_mask:0xf bank_mask:0xf
	s_nop 1
	v_add_f32_dpp v192, v192, v192 row_mirror row_mask:0xf bank_mask:0xf
	s_nop 1
	v_add_f32_dpp v192, v192, v192 row_bcast:15 row_mask:0xa bank_mask:0xf
	s_nop 1
	v_add_f32_dpp v192, v192, v192 row_bcast:31 row_mask:0xc bank_mask:0xf
	s_nop 1
	v_readlane_b32 s42, v192, 63
	s_nop 3
	s_mov_b32 s43, s42
	v_pk_fma_f32 v[160:161], s[42:43], v[196:197], v[160:161]
	v_pk_fma_f32 v[162:163], s[42:43], v[196:197], v[162:163]
	v_pk_fma_f32 v[164:165], s[42:43], v[196:197], v[164:165]
	v_pk_fma_f32 v[166:167], s[42:43], v[196:197], v[166:167]
	v_pk_fma_f32 v[168:169], s[42:43], v[196:197], v[168:169]
	v_pk_fma_f32 v[170:171], s[42:43], v[196:197], v[170:171]
	v_pk_fma_f32 v[172:173], s[42:43], v[196:197], v[172:173]
	v_pk_fma_f32 v[174:175], s[42:43], v[196:197], v[174:175]
	v_pk_mul_f32 v[176:177], v[160:161], v[160:161]
	v_pk_fma_f32 v[176:177], v[162:163], v[162:163], v[176:177]
	v_pk_fma_f32 v[176:177], v[164:165], v[164:165], v[176:177]
	v_pk_fma_f32 v[176:177], v[166:167], v[166:167], v[176:177]
	v_pk_fma_f32 v[176:177], v[168:169], v[168:169], v[176:177]
	v_pk_fma_f32 v[176:177], v[170:171], v[170:171], v[176:177]
	v_pk_fma_f32 v[176:177], v[172:173], v[172:173], v[176:177]
	v_pk_fma_f32 v[176:177], v[174:175], v[174:175], v[176:177]
	v_add_f32_e32 v194, v176, v177
	s_nop 1
	v_add_f32_dpp v192, v194, v194 quad_perm:[1,0,3,2] row_mask:0xf bank_mask:0xf
	s_nop 1
	v_add_f32_dpp v192, v192, v192 quad_perm:[2,3,0,1] row_mask:0xf bank_mask:0xf
	s_nop 1
	v_add_f32_dpp v192, v192, v192 row_half_mirror row_mask:0xf bank_mask:0xf
	s_nop 1
	v_add_f32_dpp v192, v192, v192 row_mirror row_mask:0xf bank_mask:0xf
	s_nop 1
	v_add_f32_dpp v192, v192, v192 row_bcast:15 row_mask:0xa bank_mask:0xf
	s_nop 1
	v_add_f32_dpp v192, v192, v192 row_bcast:31 row_mask:0xc bank_mask:0xf
	s_nop 1
	v_readlane_b32 s42, v192, 63
	s_nop 3
	v_fma_f32 v198, s42, v202, v203
	v_rsq_f32_e32 v198, v198
	s_nop 0
	v_pk_mul_f32 v[160:161], v[160:161], v[198:199] op_sel_hi:[1,0]
	v_pk_mul_f32 v[162:163], v[162:163], v[198:199] op_sel_hi:[1,0]
	v_pk_mul_f32 v[164:165], v[164:165], v[198:199] op_sel_hi:[1,0]
	v_pk_mul_f32 v[166:167], v[166:167], v[198:199] op_sel_hi:[1,0]
	v_pk_mul_f32 v[168:169], v[168:169], v[198:199] op_sel_hi:[1,0]
	v_pk_mul_f32 v[170:171], v[170:171], v[198:199] op_sel_hi:[1,0]
	v_pk_mul_f32 v[172:173], v[172:173], v[198:199] op_sel_hi:[1,0]
	v_pk_mul_f32 v[174:175], v[174:175], v[198:199] op_sel_hi:[1,0]
	v_pk_fma_f32 v[160:161], v[160:161], v[32:33], v[48:49]
	v_pk_fma_f32 v[162:163], v[162:163], v[34:35], v[50:51]
	v_pk_fma_f32 v[164:165], v[164:165], v[36:37], v[52:53]
	v_pk_fma_f32 v[166:167], v[166:167], v[38:39], v[54:55]
	v_pk_fma_f32 v[168:169], v[168:169], v[40:41], v[56:57]
	v_pk_fma_f32 v[170:171], v[170:171], v[42:43], v[58:59]
	v_pk_fma_f32 v[172:173], v[172:173], v[44:45], v[60:61]
	v_pk_fma_f32 v[174:175], v[174:175], v[46:47], v[62:63]
	v_cvt_pk_bf16_f32 v176, v160, v161
	v_cvt_pk_bf16_f32 v177, v162, v163
	v_cvt_pk_bf16_f32 v178, v164, v165
	v_cvt_pk_bf16_f32 v179, v166, v167
	v_cvt_pk_bf16_f32 v180, v168, v169
	v_cvt_pk_bf16_f32 v181, v170, v171
	v_cvt_pk_bf16_f32 v182, v172, v173
	v_cvt_pk_bf16_f32 v183, v174, v175
	global_store_dwordx2 v201, v[176:177], s[12:13] offset:0
	global_store_dwordx2 v201, v[178:179], s[12:13] offset:512
	global_store_dwordx2 v201, v[180:181], s[12:13] offset:1024
	global_store_dwordx2 v201, v[182:183], s[12:13] offset:1536
	s_add_u32 s8, s8, 0x1000
	s_addc_u32 s9, s9, 0
	s_add_u32 s12, s12, 0x800
	s_addc_u32 s13, s13, 0
	global_load_dwordx4 v[112:115], v200, s[2:3] offset:0
	global_load_dwordx4 v[116:119], v200, s[2:3] offset:1024
	global_load_dwordx4 v[120:123], v200, s[2:3] offset:2048
	global_load_dwordx4 v[124:127], v200, s[2:3] offset:3072
	global_load_dwordx2 v[152:153], v201, s[6:7] offset:0
	global_load_dwordx2 v[154:155], v201, s[6:7] offset:512
	global_load_dwordx2 v[156:157], v201, s[6:7] offset:1024
	global_load_dwordx2 v[158:159], v201, s[6:7] offset:1536
	s_add_u32 s2, s2, 0x1000
	s_addc_u32 s3, s3, 0
	s_add_u32 s6, s6, 0x800
	s_addc_u32 s7, s7, 0
	s_waitcnt vmcnt(48)
	v_lshlrev_b32_e32 v160, 16, v128
	v_and_b32_e32 v161, 0xffff0000, v128
	v_lshlrev_b32_e32 v162, 16, v129
	v_and_b32_e32 v163, 0xffff0000, v129
	v_lshlrev_b32_e32 v164, 16, v130
	v_and_b32_e32 v165, 0xffff0000, v130
	v_lshlrev_b32_e32 v166, 16, v131
	v_and_b32_e32 v167, 0xffff0000, v131
	v_lshlrev_b32_e32 v168, 16, v132
	v_and_b32_e32 v169, 0xffff0000, v132
	v_lshlrev_b32_e32 v170, 16, v133
	v_and_b32_e32 v171, 0xffff0000, v133
	v_lshlrev_b32_e32 v172, 16, v134
	v_and_b32_e32 v173, 0xffff0000, v134
	v_lshlrev_b32_e32 v174, 16, v135
	v_and_b32_e32 v175, 0xffff0000, v135
	v_pk_fma_f32 v[160:161], v[64:65], s[44:45], v[160:161]
	v_pk_fma_f32 v[162:163], v[66:67], s[44:45], v[162:163]
	v_pk_fma_f32 v[164:165], v[68:69], s[44:45], v[164:165]
	v_pk_fma_f32 v[166:167], v[70:71], s[44:45], v[166:167]
	v_pk_fma_f32 v[168:169], v[72:73], s[44:45], v[168:169]
	v_pk_fma_f32 v[170:171], v[74:75], s[44:45], v[170:171]
	v_pk_fma_f32 v[172:173], v[76:77], s[44:45], v[172:173]
	v_pk_fma_f32 v[174:175], v[78:79], s[44:45], v[174:175]
	v_pk_add_f32 v[176:177], v[160:161], v[162:163]
	v_pk_add_f32 v[176:177], v[176:177], v[164:165]
	v_pk_add_f32 v[176:177], v[176:177], v[166:167]
	v_pk_add_f32 v[176:177], v[176:177], v[168:169]
	v_pk_add_f32 v[176:177], v[176:177], v[170:171]
	v_pk_add_f32 v[176:177], v[176:177], v[172:173]
	v_pk_add_f32 v[176:177], v[176:177], v[174:175]
	v_add_f32_e32 v194, v176, v177
	s_nop 1
	v_add_f32_dpp v192, v194, v194 quad_perm:[1,0,3,2] row_mask:0xf bank_mask:0xf
	s_nop 1
	v_add_f32_dpp v192, v192, v192 quad_perm:[2,3,0,1] row_mask:0xf bank_mask:0xf
	s_nop 1
	v_add_f32_dpp v192, v192, v192 row_half_mirror row_mask:0xf bank_mask:0xf
	s_nop 1
	v_add_f32_dpp v192, v192, v192 row_mirror row_mask:0xf bank_mask:0xf
	s_nop 1
	v_add_f32_dpp v192, v192, v192 row_bcast:15 row_mask:0xa bank_mask:0xf
	s_nop 1
	v_add_f32_dpp v192, v192, v192 row_bcast:31 row_mask:0xc bank_mask:0xf
	s_nop 1
	v_readlane_b32 s42, v192, 63
	s_nop 3
	s_mov_b32 s43, s42
	v_pk_fma_f32 v[160:161], s[42:43], v[196:197], v[160:161]
	v_pk_fma_f32 v[162:163], s[42:43], v[196:197], v[162:163]
	v_pk_fma_f32 v[164:165], s[42:43], v[196:197], v[164:165]
	v_pk_fma_f32 v[166:167], s[42:43], v[196:197], v[166:167]
	v_pk_fma_f32 v[168:169], s[42:43], v[196:197], v[168:169]
	v_pk_fma_f32 v[170:171], s[42:43], v[196:197], v[170:171]
	v_pk_fma_f32 v[172:173], s[42:43], v[196:197], v[172:173]
	v_pk_fma_f32 v[174:175], s[42:43], v[196:197], v[174:175]
	v_pk_mul_f32 v[176:177], v[160:161], v[160:161]
	v_pk_fma_f32 v[176:177], v[162:163], v[162:163], v[176:177]
	v_pk_fma_f32 v[176:177], v[164:165], v[164:165], v[176:177]
	v_pk_fma_f32 v[176:177], v[166:167], v[166:167], v[176:177]
	v_pk_fma_f32 v[176:177], v[168:169], v[168:169], v[176:177]
	v_pk_fma_f32 v[176:177], v[170:171], v[170:171], v[176:177]
	v_pk_fma_f32 v[176:177], v[172:173], v[172:173], v[176:177]
	v_pk_fma_f32 v[176:177], v[174:175], v[174:175], v[176:177]
	v_add_f32_e32 v194, v176, v177
	s_nop 1
	v_add_f32_dpp v192, v194, v194 quad_perm:[1,0,3,2] row_mask:0xf bank_mask:0xf
	s_nop 1
	v_add_f32_dpp v192, v192, v192 quad_perm:[2,3,0,1] row_mask:0xf bank_mask:0xf
	s_nop 1
	v_add_f32_dpp v192, v192, v192 row_half_mirror row_mask:0xf bank_mask:0xf
	s_nop 1
	v_add_f32_dpp v192, v192, v192 row_mirror row_mask:0xf bank_mask:0xf
	s_nop 1
	v_add_f32_dpp v192, v192, v192 row_bcast:15 row_mask:0xa bank_mask:0xf
	s_nop 1
	v_add_f32_dpp v192, v192, v192 row_bcast:31 row_mask:0xc bank_mask:0xf
	s_nop 1
	v_readlane_b32 s42, v192, 63
	s_nop 3
	v_fma_f32 v198, s42, v202, v203
	v_rsq_f32_e32 v198, v198
	s_nop 0
	v_pk_mul_f32 v[160:161], v[160:161], v[198:199] op_sel_hi:[1,0]
	v_pk_mul_f32 v[162:163], v[162:163], v[198:199] op_sel_hi:[1,0]
	v_pk_mul_f32 v[164:165], v[164:165], v[198:199] op_sel_hi:[1,0]
	v_pk_mul_f32 v[166:167], v[166:167], v[198:199] op_sel_hi:[1,0]
	v_pk_mul_f32 v[168:169], v[168:169], v[198:199] op_sel_hi:[1,0]
	v_pk_mul_f32 v[170:171], v[170:171], v[198:199] op_sel_hi:[1,0]
	v_pk_mul_f32 v[172:173], v[172:173], v[198:199] op_sel_hi:[1,0]
	v_pk_mul_f32 v[174:175], v[174:175], v[198:199] op_sel_hi:[1,0]
	v_pk_fma_f32 v[160:161], v[160:161], v[0:1], v[16:17]
	v_pk_fma_f32 v[162:163], v[162:163], v[2:3], v[18:19]
	v_pk_fma_f32 v[164:165], v[164:165], v[4:5], v[20:21]
	v_pk_fma_f32 v[166:167], v[166:167], v[6:7], v[22:23]
	v_pk_fma_f32 v[168:169], v[168:169], v[8:9], v[24:25]
	v_pk_fma_f32 v[170:171], v[170:171], v[10:11], v[26:27]
	v_pk_fma_f32 v[172:173], v[172:173], v[12:13], v[28:29]
	v_pk_fma_f32 v[174:175], v[174:175], v[14:15], v[30:31]
	global_store_dwordx4 v200, v[160:163], s[8:9] offset:0
	global_store_dwordx4 v200, v[164:167], s[8:9] offset:1024
	global_store_dwordx4 v200, v[168:171], s[8:9] offset:2048
	global_store_dwordx4 v200, v[172:175], s[8:9] offset:3072
	v_pk_add_f32 v[176:177], v[160:161], v[162:163]
	v_pk_add_f32 v[176:177], v[176:177], v[164:165]
	v_pk_add_f32 v[176:177], v[176:177], v[166:167]
	v_pk_add_f32 v[176:177], v[176:177], v[168:169]
	v_pk_add_f32 v[176:177], v[176:177], v[170:171]
	v_pk_add_f32 v[176:177], v[176:177], v[172:173]
	v_pk_add_f32 v[176:177], v[176:177], v[174:175]
	v_add_f32_e32 v194, v176, v177
	s_nop 1
	v_add_f32_dpp v192, v194, v194 quad_perm:[1,0,3,2] row_mask:0xf bank_mask:0xf
	s_nop 1
	v_add_f32_dpp v192, v192, v192 quad_perm:[2,3,0,1] row_mask:0xf bank_mask:0xf
	s_nop 1
	v_add_f32_dpp v192, v192, v192 row_half_mirror row_mask:0xf bank_mask:0xf
	s_nop 1
	v_add_f32_dpp v192, v192, v192 row_mirror row_mask:0xf bank_mask:0xf
	s_nop 1
	v_add_f32_dpp v192, v192, v192 row_bcast:15 row_mask:0xa bank_mask:0xf
	s_nop 1
	v_add_f32_dpp v192, v192, v192 row_bcast:31 row_mask:0xc bank_mask:0xf
	s_nop 1
	v_readlane_b32 s42, v192, 63
	s_nop 3
	s_mov_b32 s43, s42
	v_pk_fma_f32 v[160:161], s[42:43], v[196:197], v[160:161]
	v_pk_fma_f32 v[162:163], s[42:43], v[196:197], v[162:163]
	v_pk_fma_f32 v[164:165], s[42:43], v[196:197], v[164:165]
	v_pk_fma_f32 v[166:167], s[42:43], v[196:197], v[166:167]
	v_pk_fma_f32 v[168:169], s[42:43], v[196:197], v[168:169]
	v_pk_fma_f32 v[170:171], s[42:43], v[196:197], v[170:171]
	v_pk_fma_f32 v[172:173], s[42:43], v[196:197], v[172:173]
	v_pk_fma_f32 v[174:175], s[42:43], v[196:197], v[174:175]
	v_pk_mul_f32 v[176:177], v[160:161], v[160:161]
	v_pk_fma_f32 v[176:177], v[162:163], v[162:163], v[176:177]
	v_pk_fma_f32 v[176:177], v[164:165], v[164:165], v[176:177]
	v_pk_fma_f32 v[176:177], v[166:167], v[166:167], v[176:177]
	v_pk_fma_f32 v[176:177], v[168:169], v[168:169], v[176:177]
	v_pk_fma_f32 v[176:177], v[170:171], v[170:171], v[176:177]
	v_pk_fma_f32 v[176:177], v[172:173], v[172:173], v[176:177]
	v_pk_fma_f32 v[176:177], v[174:175], v[174:175], v[176:177]
	v_add_f32_e32 v194, v176, v177
	s_nop 1
	v_add_f32_dpp v192, v194, v194 quad_perm:[1,0,3,2] row_mask:0xf bank_mask:0xf
	s_nop 1
	v_add_f32_dpp v192, v192, v192 quad_perm:[2,3,0,1] row_mask:0xf bank_mask:0xf
	s_nop 1
	v_add_f32_dpp v192, v192, v192 row_half_mirror row_mask:0xf bank_mask:0xf
	s_nop 1
	v_add_f32_dpp v192, v192, v192 row_mirror row_mask:0xf bank_mask:0xf
	s_nop 1
	v_add_f32_dpp v192, v192, v192 row_bcast:15 row_mask:0xa bank_mask:0xf
	s_nop 1
	v_add_f32_dpp v192, v192, v192 row_bcast:31 row_mask:0xc bank_mask:0xf
	s_nop 1
	v_readlane_b32 s42, v192, 63
	s_nop 3
	v_fma_f32 v198, s42, v202, v203
	v_rsq_f32_e32 v198, v198
	s_nop 0
	v_pk_mul_f32 v[160:161], v[160:161], v[198:199] op_sel_hi:[1,0]
	v_pk_mul_f32 v[162:163], v[162:163], v[198:199] op_sel_hi:[1,0]
	v_pk_mul_f32 v[164:165], v[164:165], v[198:199] op_sel_hi:[1,0]
	v_pk_mul_f32 v[166:167], v[166:167], v[198:199] op_sel_hi:[1,0]
	v_pk_mul_f32 v[168:169], v[168:169], v[198:199] op_sel_hi:[1,0]
	v_pk_mul_f32 v[170:171], v[170:171], v[198:199] op_sel_hi:[1,0]
	v_pk_mul_f32 v[172:173], v[172:173], v[198:199] op_sel_hi:[1,0]
	v_pk_mul_f32 v[174:175], v[174:175], v[198:199] op_sel_hi:[1,0]
	v_pk_fma_f32 v[160:161], v[160:161], v[32:33], v[48:49]
	v_pk_fma_f32 v[162:163], v[162:163], v[34:35], v[50:51]
	v_pk_fma_f32 v[164:165], v[164:165], v[36:37], v[52:53]
	v_pk_fma_f32 v[166:167], v[166:167], v[38:39], v[54:55]
	v_pk_fma_f32 v[168:169], v[168:169], v[40:41], v[56:57]
	v_pk_fma_f32 v[170:171], v[170:171], v[42:43], v[58:59]
	v_pk_fma_f32 v[172:173], v[172:173], v[44:45], v[60:61]
	v_pk_fma_f32 v[174:175], v[174:175], v[46:47], v[62:63]
	v_cvt_pk_bf16_f32 v176, v160, v161
	v_cvt_pk_bf16_f32 v177, v162, v163
	v_cvt_pk_bf16_f32 v178, v164, v165
	v_cvt_pk_bf16_f32 v179, v166, v167
	v_cvt_pk_bf16_f32 v180, v168, v169
	v_cvt_pk_bf16_f32 v181, v170, v171
	v_cvt_pk_bf16_f32 v182, v172, v173
	v_cvt_pk_bf16_f32 v183, v174, v175
	global_store_dwordx2 v201, v[176:177], s[12:13] offset:0
	global_store_dwordx2 v201, v[178:179], s[12:13] offset:512
	global_store_dwordx2 v201, v[180:181], s[12:13] offset:1024
	global_store_dwordx2 v201, v[182:183], s[12:13] offset:1536
	s_add_u32 s8, s8, 0x1000
	s_addc_u32 s9, s9, 0
	s_add_u32 s12, s12, 0x800
	s_addc_u32 s13, s13, 0
	s_waitcnt vmcnt(40)
	v_lshlrev_b32_e32 v160, 16, v136
	v_and_b32_e32 v161, 0xffff0000, v136
	v_lshlrev_b32_e32 v162, 16, v137
	v_and_b32_e32 v163, 0xffff0000, v137
	v_lshlrev_b32_e32 v164, 16, v138
	v_and_b32_e32 v165, 0xffff0000, v138
	v_lshlrev_b32_e32 v166, 16, v139
	v_and_b32_e32 v167, 0xffff0000, v139
	v_lshlrev_b32_e32 v168, 16, v140
	v_and_b32_e32 v169, 0xffff0000, v140
	v_lshlrev_b32_e32 v170, 16, v141
	v_and_b32_e32 v171, 0xffff0000, v141
	v_lshlrev_b32_e32 v172, 16, v142
	v_and_b32_e32 v173, 0xffff0000, v142
	v_lshlrev_b32_e32 v174, 16, v143
	v_and_b32_e32 v175, 0xffff0000, v143
	v_pk_fma_f32 v[160:161], v[80:81], s[44:45], v[160:161]
	v_pk_fma_f32 v[162:163], v[82:83], s[44:45], v[162:163]
	v_pk_fma_f32 v[164:165], v[84:85], s[44:45], v[164:165]
	v_pk_fma_f32 v[166:167], v[86:87], s[44:45], v[166:167]
	v_pk_fma_f32 v[168:169], v[88:89], s[44:45], v[168:169]
	v_pk_fma_f32 v[170:171], v[90:91], s[44:45], v[170:171]
	v_pk_fma_f32 v[172:173], v[92:93], s[44:45], v[172:173]
	v_pk_fma_f32 v[174:175], v[94:95], s[44:45], v[174:175]
	v_pk_add_f32 v[176:177], v[160:161], v[162:163]
	v_pk_add_f32 v[176:177], v[176:177], v[164:165]
	v_pk_add_f32 v[176:177], v[176:177], v[166:167]
	v_pk_add_f32 v[176:177], v[176:177], v[168:169]
	v_pk_add_f32 v[176:177], v[176:177], v[170:171]
	v_pk_add_f32 v[176:177], v[176:177], v[172:173]
	v_pk_add_f32 v[176:177], v[176:177], v[174:175]
	v_add_f32_e32 v194, v176, v177
	s_nop 1
	v_add_f32_dpp v192, v194, v194 quad_perm:[1,0,3,2] row_mask:0xf bank_mask:0xf
	s_nop 1
	v_add_f32_dpp v192, v192, v192 quad_perm:[2,3,0,1] row_mask:0xf bank_mask:0xf
	s_nop 1
	v_add_f32_dpp v192, v192, v192 row_half_mirror row_mask:0xf bank_mask:0xf
	s_nop 1
	v_add_f32_dpp v192, v192, v192 row_mirror row_mask:0xf bank_mask:0xf
	s_nop 1
	v_add_f32_dpp v192, v192, v192 row_bcast:15 row_mask:0xa bank_mask:0xf
	s_nop 1
	v_add_f32_dpp v192, v192, v192 row_bcast:31 row_mask:0xc bank_mask:0xf
	s_nop 1
	v_readlane_b32 s42, v192, 63
	s_nop 3
	s_mov_b32 s43, s42
	v_pk_fma_f32 v[160:161], s[42:43], v[196:197], v[160:161]
	v_pk_fma_f32 v[162:163], s[42:43], v[196:197], v[162:163]
	v_pk_fma_f32 v[164:165], s[42:43], v[196:197], v[164:165]
	v_pk_fma_f32 v[166:167], s[42:43], v[196:197], v[166:167]
	v_pk_fma_f32 v[168:169], s[42:43], v[196:197], v[168:169]
	v_pk_fma_f32 v[170:171], s[42:43], v[196:197], v[170:171]
	v_pk_fma_f32 v[172:173], s[42:43], v[196:197], v[172:173]
	v_pk_fma_f32 v[174:175], s[42:43], v[196:197], v[174:175]
	v_pk_mul_f32 v[176:177], v[160:161], v[160:161]
	v_pk_fma_f32 v[176:177], v[162:163], v[162:163], v[176:177]
	v_pk_fma_f32 v[176:177], v[164:165], v[164:165], v[176:177]
	v_pk_fma_f32 v[176:177], v[166:167], v[166:167], v[176:177]
	v_pk_fma_f32 v[176:177], v[168:169], v[168:169], v[176:177]
	v_pk_fma_f32 v[176:177], v[170:171], v[170:171], v[176:177]
	v_pk_fma_f32 v[176:177], v[172:173], v[172:173], v[176:177]
	v_pk_fma_f32 v[176:177], v[174:175], v[174:175], v[176:177]
	v_add_f32_e32 v194, v176, v177
	s_nop 1
	v_add_f32_dpp v192, v194, v194 quad_perm:[1,0,3,2] row_mask:0xf bank_mask:0xf
	s_nop 1
	v_add_f32_dpp v192, v192, v192 quad_perm:[2,3,0,1] row_mask:0xf bank_mask:0xf
	s_nop 1
	v_add_f32_dpp v192, v192, v192 row_half_mirror row_mask:0xf bank_mask:0xf
	s_nop 1
	v_add_f32_dpp v192, v192, v192 row_mirror row_mask:0xf bank_mask:0xf
	s_nop 1
	v_add_f32_dpp v192, v192, v192 row_bcast:15 row_mask:0xa bank_mask:0xf
	s_nop 1
	v_add_f32_dpp v192, v192, v192 row_bcast:31 row_mask:0xc bank_mask:0xf
	s_nop 1
	v_readlane_b32 s42, v192, 63
	s_nop 3
	v_fma_f32 v198, s42, v202, v203
	v_rsq_f32_e32 v198, v198
	s_nop 0
	v_pk_mul_f32 v[160:161], v[160:161], v[198:199] op_sel_hi:[1,0]
	v_pk_mul_f32 v[162:163], v[162:163], v[198:199] op_sel_hi:[1,0]
	v_pk_mul_f32 v[164:165], v[164:165], v[198:199] op_sel_hi:[1,0]
	v_pk_mul_f32 v[166:167], v[166:167], v[198:199] op_sel_hi:[1,0]
	v_pk_mul_f32 v[168:169], v[168:169], v[198:199] op_sel_hi:[1,0]
	v_pk_mul_f32 v[170:171], v[170:171], v[198:199] op_sel_hi:[1,0]
	v_pk_mul_f32 v[172:173], v[172:173], v[198:199] op_sel_hi:[1,0]
	v_pk_mul_f32 v[174:175], v[174:175], v[198:199] op_sel_hi:[1,0]
	v_pk_fma_f32 v[160:161], v[160:161], v[0:1], v[16:17]
	v_pk_fma_f32 v[162:163], v[162:163], v[2:3], v[18:19]
	v_pk_fma_f32 v[164:165], v[164:165], v[4:5], v[20:21]
	v_pk_fma_f32 v[166:167], v[166:167], v[6:7], v[22:23]
	v_pk_fma_f32 v[168:169], v[168:169], v[8:9], v[24:25]
	v_pk_fma_f32 v[170:171], v[170:171], v[10:11], v[26:27]
	v_pk_fma_f32 v[172:173], v[172:173], v[12:13], v[28:29]
	v_pk_fma_f32 v[174:175], v[174:175], v[14:15], v[30:31]
	global_store_dwordx4 v200, v[160:163], s[8:9] offset:0
	global_store_dwordx4 v200, v[164:167], s[8:9] offset:1024
	global_store_dwordx4 v200, v[168:171], s[8:9] offset:2048
	global_store_dwordx4 v200, v[172:175], s[8:9] offset:3072
	v_pk_add_f32 v[176:177], v[160:161], v[162:163]
	v_pk_add_f32 v[176:177], v[176:177], v[164:165]
	v_pk_add_f32 v[176:177], v[176:177], v[166:167]
	v_pk_add_f32 v[176:177], v[176:177], v[168:169]
	v_pk_add_f32 v[176:177], v[176:177], v[170:171]
	v_pk_add_f32 v[176:177], v[176:177], v[172:173]
	v_pk_add_f32 v[176:177], v[176:177], v[174:175]
	v_add_f32_e32 v194, v176, v177
	s_nop 1
	v_add_f32_dpp v192, v194, v194 quad_perm:[1,0,3,2] row_mask:0xf bank_mask:0xf
	s_nop 1
	v_add_f32_dpp v192, v192, v192 quad_perm:[2,3,0,1] row_mask:0xf bank_mask:0xf
	s_nop 1
	v_add_f32_dpp v192, v192, v192 row_half_mirror row_mask:0xf bank_mask:0xf
	s_nop 1
	v_add_f32_dpp v192, v192, v192 row_mirror row_mask:0xf bank_mask:0xf
	s_nop 1
	v_add_f32_dpp v192, v192, v192 row_bcast:15 row_mask:0xa bank_mask:0xf
	s_nop 1
	v_add_f32_dpp v192, v192, v192 row_bcast:31 row_mask:0xc bank_mask:0xf
	s_nop 1
	v_readlane_b32 s42, v192, 63
	s_nop 3
	s_mov_b32 s43, s42
	v_pk_fma_f32 v[160:161], s[42:43], v[196:197], v[160:161]
	v_pk_fma_f32 v[162:163], s[42:43], v[196:197], v[162:163]
	v_pk_fma_f32 v[164:165], s[42:43], v[196:197], v[164:165]
	v_pk_fma_f32 v[166:167], s[42:43], v[196:197], v[166:167]
	v_pk_fma_f32 v[168:169], s[42:43], v[196:197], v[168:169]
	v_pk_fma_f32 v[170:171], s[42:43], v[196:197], v[170:171]
	v_pk_fma_f32 v[172:173], s[42:43], v[196:197], v[172:173]
	v_pk_fma_f32 v[174:175], s[42:43], v[196:197], v[174:175]
	v_pk_mul_f32 v[176:177], v[160:161], v[160:161]
	v_pk_fma_f32 v[176:177], v[162:163], v[162:163], v[176:177]
	v_pk_fma_f32 v[176:177], v[164:165], v[164:165], v[176:177]
	v_pk_fma_f32 v[176:177], v[166:167], v[166:167], v[176:177]
	v_pk_fma_f32 v[176:177], v[168:169], v[168:169], v[176:177]
	v_pk_fma_f32 v[176:177], v[170:171], v[170:171], v[176:177]
	v_pk_fma_f32 v[176:177], v[172:173], v[172:173], v[176:177]
	v_pk_fma_f32 v[176:177], v[174:175], v[174:175], v[176:177]
	v_add_f32_e32 v194, v176, v177
	s_nop 1
	v_add_f32_dpp v192, v194, v194 quad_perm:[1,0,3,2] row_mask:0xf bank_mask:0xf
	s_nop 1
	v_add_f32_dpp v192, v192, v192 quad_perm:[2,3,0,1] row_mask:0xf bank_mask:0xf
	s_nop 1
	v_add_f32_dpp v192, v192, v192 row_half_mirror row_mask:0xf bank_mask:0xf
	s_nop 1
	v_add_f32_dpp v192, v192, v192 row_mirror row_mask:0xf bank_mask:0xf
	s_nop 1
	v_add_f32_dpp v192, v192, v192 row_bcast:15 row_mask:0xa bank_mask:0xf
	s_nop 1
	v_add_f32_dpp v192, v192, v192 row_bcast:31 row_mask:0xc bank_mask:0xf
	s_nop 1
	v_readlane_b32 s42, v192, 63
	s_nop 3
	v_fma_f32 v198, s42, v202, v203
	v_rsq_f32_e32 v198, v198
	s_nop 0
	v_pk_mul_f32 v[160:161], v[160:161], v[198:199] op_sel_hi:[1,0]
	v_pk_mul_f32 v[162:163], v[162:163], v[198:199] op_sel_hi:[1,0]
	v_pk_mul_f32 v[164:165], v[164:165], v[198:199] op_sel_hi:[1,0]
	v_pk_mul_f32 v[166:167], v[166:167], v[198:199] op_sel_hi:[1,0]
	v_pk_mul_f32 v[168:169], v[168:169], v[198:199] op_sel_hi:[1,0]
	v_pk_mul_f32 v[170:171], v[170:171], v[198:199] op_sel_hi:[1,0]
	v_pk_mul_f32 v[172:173], v[172:173], v[198:199] op_sel_hi:[1,0]
	v_pk_mul_f32 v[174:175], v[174:175], v[198:199] op_sel_hi:[1,0]
	v_pk_fma_f32 v[160:161], v[160:161], v[32:33], v[48:49]
	v_pk_fma_f32 v[162:163], v[162:163], v[34:35], v[50:51]
	v_pk_fma_f32 v[164:165], v[164:165], v[36:37], v[52:53]
	v_pk_fma_f32 v[166:167], v[166:167], v[38:39], v[54:55]
	v_pk_fma_f32 v[168:169], v[168:169], v[40:41], v[56:57]
	v_pk_fma_f32 v[170:171], v[170:171], v[42:43], v[58:59]
	v_pk_fma_f32 v[172:173], v[172:173], v[44:45], v[60:61]
	v_pk_fma_f32 v[174:175], v[174:175], v[46:47], v[62:63]
	v_cvt_pk_bf16_f32 v176, v160, v161
	v_cvt_pk_bf16_f32 v177, v162, v163
	v_cvt_pk_bf16_f32 v178, v164, v165
	v_cvt_pk_bf16_f32 v179, v166, v167
	v_cvt_pk_bf16_f32 v180, v168, v169
	v_cvt_pk_bf16_f32 v181, v170, v171
	v_cvt_pk_bf16_f32 v182, v172, v173
	v_cvt_pk_bf16_f32 v183, v174, v175
	global_store_dwordx2 v201, v[176:177], s[12:13] offset:0
	global_store_dwordx2 v201, v[178:179], s[12:13] offset:512
	global_store_dwordx2 v201, v[180:181], s[12:13] offset:1024
	global_store_dwordx2 v201, v[182:183], s[12:13] offset:1536
	s_add_u32 s8, s8, 0x1000
	s_addc_u32 s9, s9, 0
	s_add_u32 s12, s12, 0x800
	s_addc_u32 s13, s13, 0
	s_waitcnt vmcnt(32)
	v_lshlrev_b32_e32 v160, 16, v144
	v_and_b32_e32 v161, 0xffff0000, v144
	v_lshlrev_b32_e32 v162, 16, v145
	v_and_b32_e32 v163, 0xffff0000, v145
	v_lshlrev_b32_e32 v164, 16, v146
	v_and_b32_e32 v165, 0xffff0000, v146
	v_lshlrev_b32_e32 v166, 16, v147
	v_and_b32_e32 v167, 0xffff0000, v147
	v_lshlrev_b32_e32 v168, 16, v148
	v_and_b32_e32 v169, 0xffff0000, v148
	v_lshlrev_b32_e32 v170, 16, v149
	v_and_b32_e32 v171, 0xffff0000, v149
	v_lshlrev_b32_e32 v172, 16, v150
	v_and_b32_e32 v173, 0xffff0000, v150
	v_lshlrev_b32_e32 v174, 16, v151
	v_and_b32_e32 v175, 0xffff0000, v151
	v_pk_fma_f32 v[160:161], v[96:97], s[44:45], v[160:161]
	v_pk_fma_f32 v[162:163], v[98:99], s[44:45], v[162:163]
	v_pk_fma_f32 v[164:165], v[100:101], s[44:45], v[164:165]
	v_pk_fma_f32 v[166:167], v[102:103], s[44:45], v[166:167]
	v_pk_fma_f32 v[168:169], v[104:105], s[44:45], v[168:169]
	v_pk_fma_f32 v[170:171], v[106:107], s[44:45], v[170:171]
	v_pk_fma_f32 v[172:173], v[108:109], s[44:45], v[172:173]
	v_pk_fma_f32 v[174:175], v[110:111], s[44:45], v[174:175]
	v_pk_add_f32 v[176:177], v[160:161], v[162:163]
	v_pk_add_f32 v[176:177], v[176:177], v[164:165]
	v_pk_add_f32 v[176:177], v[176:177], v[166:167]
	v_pk_add_f32 v[176:177], v[176:177], v[168:169]
	v_pk_add_f32 v[176:177], v[176:177], v[170:171]
	v_pk_add_f32 v[176:177], v[176:177], v[172:173]
	v_pk_add_f32 v[176:177], v[176:177], v[174:175]
	v_add_f32_e32 v194, v176, v177
	s_nop 1
	v_add_f32_dpp v192, v194, v194 quad_perm:[1,0,3,2] row_mask:0xf bank_mask:0xf
	s_nop 1
	v_add_f32_dpp v192, v192, v192 quad_perm:[2,3,0,1] row_mask:0xf bank_mask:0xf
	s_nop 1
	v_add_f32_dpp v192, v192, v192 row_half_mirror row_mask:0xf bank_mask:0xf
	s_nop 1
	v_add_f32_dpp v192, v192, v192 row_mirror row_mask:0xf bank_mask:0xf
	s_nop 1
	v_add_f32_dpp v192, v192, v192 row_bcast:15 row_mask:0xa bank_mask:0xf
	s_nop 1
	v_add_f32_dpp v192, v192, v192 row_bcast:31 row_mask:0xc bank_mask:0xf
	s_nop 1
	v_readlane_b32 s42, v192, 63
	s_nop 3
	s_mov_b32 s43, s42
	v_pk_fma_f32 v[160:161], s[42:43], v[196:197], v[160:161]
	v_pk_fma_f32 v[162:163], s[42:43], v[196:197], v[162:163]
	v_pk_fma_f32 v[164:165], s[42:43], v[196:197], v[164:165]
	v_pk_fma_f32 v[166:167], s[42:43], v[196:197], v[166:167]
	v_pk_fma_f32 v[168:169], s[42:43], v[196:197], v[168:169]
	v_pk_fma_f32 v[170:171], s[42:43], v[196:197], v[170:171]
	v_pk_fma_f32 v[172:173], s[42:43], v[196:197], v[172:173]
	v_pk_fma_f32 v[174:175], s[42:43], v[196:197], v[174:175]
	v_pk_mul_f32 v[176:177], v[160:161], v[160:161]
	v_pk_fma_f32 v[176:177], v[162:163], v[162:163], v[176:177]
	v_pk_fma_f32 v[176:177], v[164:165], v[164:165], v[176:177]
	v_pk_fma_f32 v[176:177], v[166:167], v[166:167], v[176:177]
	v_pk_fma_f32 v[176:177], v[168:169], v[168:169], v[176:177]
	v_pk_fma_f32 v[176:177], v[170:171], v[170:171], v[176:177]
	v_pk_fma_f32 v[176:177], v[172:173], v[172:173], v[176:177]
	v_pk_fma_f32 v[176:177], v[174:175], v[174:175], v[176:177]
	v_add_f32_e32 v194, v176, v177
	s_nop 1
	v_add_f32_dpp v192, v194, v194 quad_perm:[1,0,3,2] row_mask:0xf bank_mask:0xf
	s_nop 1
	v_add_f32_dpp v192, v192, v192 quad_perm:[2,3,0,1] row_mask:0xf bank_mask:0xf
	s_nop 1
	v_add_f32_dpp v192, v192, v192 row_half_mirror row_mask:0xf bank_mask:0xf
	s_nop 1
	v_add_f32_dpp v192, v192, v192 row_mirror row_mask:0xf bank_mask:0xf
	s_nop 1
	v_add_f32_dpp v192, v192, v192 row_bcast:15 row_mask:0xa bank_mask:0xf
	s_nop 1
	v_add_f32_dpp v192, v192, v192 row_bcast:31 row_mask:0xc bank_mask:0xf
	s_nop 1
	v_readlane_b32 s42, v192, 63
	s_nop 3
	v_fma_f32 v198, s42, v202, v203
	v_rsq_f32_e32 v198, v198
	s_nop 0
	v_pk_mul_f32 v[160:161], v[160:161], v[198:199] op_sel_hi:[1,0]
	v_pk_mul_f32 v[162:163], v[162:163], v[198:199] op_sel_hi:[1,0]
	v_pk_mul_f32 v[164:165], v[164:165], v[198:199] op_sel_hi:[1,0]
	v_pk_mul_f32 v[166:167], v[166:167], v[198:199] op_sel_hi:[1,0]
	v_pk_mul_f32 v[168:169], v[168:169], v[198:199] op_sel_hi:[1,0]
	v_pk_mul_f32 v[170:171], v[170:171], v[198:199] op_sel_hi:[1,0]
	v_pk_mul_f32 v[172:173], v[172:173], v[198:199] op_sel_hi:[1,0]
	v_pk_mul_f32 v[174:175], v[174:175], v[198:199] op_sel_hi:[1,0]
	v_pk_fma_f32 v[160:161], v[160:161], v[0:1], v[16:17]
	v_pk_fma_f32 v[162:163], v[162:163], v[2:3], v[18:19]
	v_pk_fma_f32 v[164:165], v[164:165], v[4:5], v[20:21]
	v_pk_fma_f32 v[166:167], v[166:167], v[6:7], v[22:23]
	v_pk_fma_f32 v[168:169], v[168:169], v[8:9], v[24:25]
	v_pk_fma_f32 v[170:171], v[170:171], v[10:11], v[26:27]
	v_pk_fma_f32 v[172:173], v[172:173], v[12:13], v[28:29]
	v_pk_fma_f32 v[174:175], v[174:175], v[14:15], v[30:31]
	global_store_dwordx4 v200, v[160:163], s[8:9] offset:0
	global_store_dwordx4 v200, v[164:167], s[8:9] offset:1024
	global_store_dwordx4 v200, v[168:171], s[8:9] offset:2048
	global_store_dwordx4 v200, v[172:175], s[8:9] offset:3072
	v_pk_add_f32 v[176:177], v[160:161], v[162:163]
	v_pk_add_f32 v[176:177], v[176:177], v[164:165]
	v_pk_add_f32 v[176:177], v[176:177], v[166:167]
	v_pk_add_f32 v[176:177], v[176:177], v[168:169]
	v_pk_add_f32 v[176:177], v[176:177], v[170:171]
	v_pk_add_f32 v[176:177], v[176:177], v[172:173]
	v_pk_add_f32 v[176:177], v[176:177], v[174:175]
	v_add_f32_e32 v194, v176, v177
	s_nop 1
	v_add_f32_dpp v192, v194, v194 quad_perm:[1,0,3,2] row_mask:0xf bank_mask:0xf
	s_nop 1
	v_add_f32_dpp v192, v192, v192 quad_perm:[2,3,0,1] row_mask:0xf bank_mask:0xf
	s_nop 1
	v_add_f32_dpp v192, v192, v192 row_half_mirror row_mask:0xf bank_mask:0xf
	s_nop 1
	v_add_f32_dpp v192, v192, v192 row_mirror row_mask:0xf bank_mask:0xf
	s_nop 1
	v_add_f32_dpp v192, v192, v192 row_bcast:15 row_mask:0xa bank_mask:0xf
	s_nop 1
	v_add_f32_dpp v192, v192, v192 row_bcast:31 row_mask:0xc bank_mask:0xf
	s_nop 1
	v_readlane_b32 s42, v192, 63
	s_nop 3
	s_mov_b32 s43, s42
	v_pk_fma_f32 v[160:161], s[42:43], v[196:197], v[160:161]
	v_pk_fma_f32 v[162:163], s[42:43], v[196:197], v[162:163]
	v_pk_fma_f32 v[164:165], s[42:43], v[196:197], v[164:165]
	v_pk_fma_f32 v[166:167], s[42:43], v[196:197], v[166:167]
	v_pk_fma_f32 v[168:169], s[42:43], v[196:197], v[168:169]
	v_pk_fma_f32 v[170:171], s[42:43], v[196:197], v[170:171]
	v_pk_fma_f32 v[172:173], s[42:43], v[196:197], v[172:173]
	v_pk_fma_f32 v[174:175], s[42:43], v[196:197], v[174:175]
	v_pk_mul_f32 v[176:177], v[160:161], v[160:161]
	v_pk_fma_f32 v[176:177], v[162:163], v[162:163], v[176:177]
	v_pk_fma_f32 v[176:177], v[164:165], v[164:165], v[176:177]
	v_pk_fma_f32 v[176:177], v[166:167], v[166:167], v[176:177]
	v_pk_fma_f32 v[176:177], v[168:169], v[168:169], v[176:177]
	v_pk_fma_f32 v[176:177], v[170:171], v[170:171], v[176:177]
	v_pk_fma_f32 v[176:177], v[172:173], v[172:173], v[176:177]
	v_pk_fma_f32 v[176:177], v[174:175], v[174:175], v[176:177]
	v_add_f32_e32 v194, v176, v177
	s_nop 1
	v_add_f32_dpp v192, v194, v194 quad_perm:[1,0,3,2] row_mask:0xf bank_mask:0xf
	s_nop 1
	v_add_f32_dpp v192, v192, v192 quad_perm:[2,3,0,1] row_mask:0xf bank_mask:0xf
	s_nop 1
	v_add_f32_dpp v192, v192, v192 row_half_mirror row_mask:0xf bank_mask:0xf
	s_nop 1
	v_add_f32_dpp v192, v192, v192 row_mirror row_mask:0xf bank_mask:0xf
	s_nop 1
	v_add_f32_dpp v192, v192, v192 row_bcast:15 row_mask:0xa bank_mask:0xf
	s_nop 1
	v_add_f32_dpp v192, v192, v192 row_bcast:31 row_mask:0xc bank_mask:0xf
	s_nop 1
	v_readlane_b32 s42, v192, 63
	s_nop 3
	v_fma_f32 v198, s42, v202, v203
	v_rsq_f32_e32 v198, v198
	s_nop 0
	v_pk_mul_f32 v[160:161], v[160:161], v[198:199] op_sel_hi:[1,0]
	v_pk_mul_f32 v[162:163], v[162:163], v[198:199] op_sel_hi:[1,0]
	v_pk_mul_f32 v[164:165], v[164:165], v[198:199] op_sel_hi:[1,0]
	v_pk_mul_f32 v[166:167], v[166:167], v[198:199] op_sel_hi:[1,0]
	v_pk_mul_f32 v[168:169], v[168:169], v[198:199] op_sel_hi:[1,0]
	v_pk_mul_f32 v[170:171], v[170:171], v[198:199] op_sel_hi:[1,0]
	v_pk_mul_f32 v[172:173], v[172:173], v[198:199] op_sel_hi:[1,0]
	v_pk_mul_f32 v[174:175], v[174:175], v[198:199] op_sel_hi:[1,0]
	v_pk_fma_f32 v[160:161], v[160:161], v[32:33], v[48:49]
	v_pk_fma_f32 v[162:163], v[162:163], v[34:35], v[50:51]
	v_pk_fma_f32 v[164:165], v[164:165], v[36:37], v[52:53]
	v_pk_fma_f32 v[166:167], v[166:167], v[38:39], v[54:55]
	v_pk_fma_f32 v[168:169], v[168:169], v[40:41], v[56:57]
	v_pk_fma_f32 v[170:171], v[170:171], v[42:43], v[58:59]
	v_pk_fma_f32 v[172:173], v[172:173], v[44:45], v[60:61]
	v_pk_fma_f32 v[174:175], v[174:175], v[46:47], v[62:63]
	v_cvt_pk_bf16_f32 v176, v160, v161
	v_cvt_pk_bf16_f32 v177, v162, v163
	v_cvt_pk_bf16_f32 v178, v164, v165
	v_cvt_pk_bf16_f32 v179, v166, v167
	v_cvt_pk_bf16_f32 v180, v168, v169
	v_cvt_pk_bf16_f32 v181, v170, v171
	v_cvt_pk_bf16_f32 v182, v172, v173
	v_cvt_pk_bf16_f32 v183, v174, v175
	global_store_dwordx2 v201, v[176:177], s[12:13] offset:0
	global_store_dwordx2 v201, v[178:179], s[12:13] offset:512
	global_store_dwordx2 v201, v[180:181], s[12:13] offset:1024
	global_store_dwordx2 v201, v[182:183], s[12:13] offset:1536
	s_add_u32 s8, s8, 0x1000
	s_addc_u32 s9, s9, 0
	s_add_u32 s12, s12, 0x800
	s_addc_u32 s13, s13, 0
	s_waitcnt vmcnt(24)
	v_lshlrev_b32_e32 v160, 16, v152
	v_and_b32_e32 v161, 0xffff0000, v152
	v_lshlrev_b32_e32 v162, 16, v153
	v_and_b32_e32 v163, 0xffff0000, v153
	v_lshlrev_b32_e32 v164, 16, v154
	v_and_b32_e32 v165, 0xffff0000, v154
	v_lshlrev_b32_e32 v166, 16, v155
	v_and_b32_e32 v167, 0xffff0000, v155
	v_lshlrev_b32_e32 v168, 16, v156
	v_and_b32_e32 v169, 0xffff0000, v156
	v_lshlrev_b32_e32 v170, 16, v157
	v_and_b32_e32 v171, 0xffff0000, v157
	v_lshlrev_b32_e32 v172, 16, v158
	v_and_b32_e32 v173, 0xffff0000, v158
	v_lshlrev_b32_e32 v174, 16, v159
	v_and_b32_e32 v175, 0xffff0000, v159
	v_pk_fma_f32 v[160:161], v[112:113], s[44:45], v[160:161]
	v_pk_fma_f32 v[162:163], v[114:115], s[44:45], v[162:163]
	v_pk_fma_f32 v[164:165], v[116:117], s[44:45], v[164:165]
	v_pk_fma_f32 v[166:167], v[118:119], s[44:45], v[166:167]
	v_pk_fma_f32 v[168:169], v[120:121], s[44:45], v[168:169]
	v_pk_fma_f32 v[170:171], v[122:123], s[44:45], v[170:171]
	v_pk_fma_f32 v[172:173], v[124:125], s[44:45], v[172:173]
	v_pk_fma_f32 v[174:175], v[126:127], s[44:45], v[174:175]
	v_pk_add_f32 v[176:177], v[160:161], v[162:163]
	v_pk_add_f32 v[176:177], v[176:177], v[164:165]
	v_pk_add_f32 v[176:177], v[176:177], v[166:167]
	v_pk_add_f32 v[176:177], v[176:177], v[168:169]
	v_pk_add_f32 v[176:177], v[176:177], v[170:171]
	v_pk_add_f32 v[176:177], v[176:177], v[172:173]
	v_pk_add_f32 v[176:177], v[176:177], v[174:175]
	v_add_f32_e32 v194, v176, v177
	s_nop 1
	v_add_f32_dpp v192, v194, v194 quad_perm:[1,0,3,2] row_mask:0xf bank_mask:0xf
	s_nop 1
	v_add_f32_dpp v192, v192, v192 quad_perm:[2,3,0,1] row_mask:0xf bank_mask:0xf
	s_nop 1
	v_add_f32_dpp v192, v192, v192 row_half_mirror row_mask:0xf bank_mask:0xf
	s_nop 1
	v_add_f32_dpp v192, v192, v192 row_mirror row_mask:0xf bank_mask:0xf
	s_nop 1
	v_add_f32_dpp v192, v192, v192 row_bcast:15 row_mask:0xa bank_mask:0xf
	s_nop 1
	v_add_f32_dpp v192, v192, v192 row_bcast:31 row_mask:0xc bank_mask:0xf
	s_nop 1
	v_readlane_b32 s42, v192, 63
	s_nop 3
	s_mov_b32 s43, s42
	v_pk_fma_f32 v[160:161], s[42:43], v[196:197], v[160:161]
	v_pk_fma_f32 v[162:163], s[42:43], v[196:197], v[162:163]
	v_pk_fma_f32 v[164:165], s[42:43], v[196:197], v[164:165]
	v_pk_fma_f32 v[166:167], s[42:43], v[196:197], v[166:167]
	v_pk_fma_f32 v[168:169], s[42:43], v[196:197], v[168:169]
	v_pk_fma_f32 v[170:171], s[42:43], v[196:197], v[170:171]
	v_pk_fma_f32 v[172:173], s[42:43], v[196:197], v[172:173]
	v_pk_fma_f32 v[174:175], s[42:43], v[196:197], v[174:175]
	v_pk_mul_f32 v[176:177], v[160:161], v[160:161]
	v_pk_fma_f32 v[176:177], v[162:163], v[162:163], v[176:177]
	v_pk_fma_f32 v[176:177], v[164:165], v[164:165], v[176:177]
	v_pk_fma_f32 v[176:177], v[166:167], v[166:167], v[176:177]
	v_pk_fma_f32 v[176:177], v[168:169], v[168:169], v[176:177]
	v_pk_fma_f32 v[176:177], v[170:171], v[170:171], v[176:177]
	v_pk_fma_f32 v[176:177], v[172:173], v[172:173], v[176:177]
	v_pk_fma_f32 v[176:177], v[174:175], v[174:175], v[176:177]
	v_add_f32_e32 v194, v176, v177
	s_nop 1
	v_add_f32_dpp v192, v194, v194 quad_perm:[1,0,3,2] row_mask:0xf bank_mask:0xf
	s_nop 1
	v_add_f32_dpp v192, v192, v192 quad_perm:[2,3,0,1] row_mask:0xf bank_mask:0xf
	s_nop 1
	v_add_f32_dpp v192, v192, v192 row_half_mirror row_mask:0xf bank_mask:0xf
	s_nop 1
	v_add_f32_dpp v192, v192, v192 row_mirror row_mask:0xf bank_mask:0xf
	s_nop 1
	v_add_f32_dpp v192, v192, v192 row_bcast:15 row_mask:0xa bank_mask:0xf
	s_nop 1
	v_add_f32_dpp v192, v192, v192 row_bcast:31 row_mask:0xc bank_mask:0xf
	s_nop 1
	v_readlane_b32 s42, v192, 63
	s_nop 3
	v_fma_f32 v198, s42, v202, v203
	v_rsq_f32_e32 v198, v198
	s_nop 0
	v_pk_mul_f32 v[160:161], v[160:161], v[198:199] op_sel_hi:[1,0]
	v_pk_mul_f32 v[162:163], v[162:163], v[198:199] op_sel_hi:[1,0]
	v_pk_mul_f32 v[164:165], v[164:165], v[198:199] op_sel_hi:[1,0]
	v_pk_mul_f32 v[166:167], v[166:167], v[198:199] op_sel_hi:[1,0]
	v_pk_mul_f32 v[168:169], v[168:169], v[198:199] op_sel_hi:[1,0]
	v_pk_mul_f32 v[170:171], v[170:171], v[198:199] op_sel_hi:[1,0]
	v_pk_mul_f32 v[172:173], v[172:173], v[198:199] op_sel_hi:[1,0]
	v_pk_mul_f32 v[174:175], v[174:175], v[198:199] op_sel_hi:[1,0]
	v_pk_fma_f32 v[160:161], v[160:161], v[0:1], v[16:17]
	v_pk_fma_f32 v[162:163], v[162:163], v[2:3], v[18:19]
	v_pk_fma_f32 v[164:165], v[164:165], v[4:5], v[20:21]
	v_pk_fma_f32 v[166:167], v[166:167], v[6:7], v[22:23]
	v_pk_fma_f32 v[168:169], v[168:169], v[8:9], v[24:25]
	v_pk_fma_f32 v[170:171], v[170:171], v[10:11], v[26:27]
	v_pk_fma_f32 v[172:173], v[172:173], v[12:13], v[28:29]
	v_pk_fma_f32 v[174:175], v[174:175], v[14:15], v[30:31]
	global_store_dwordx4 v200, v[160:163], s[8:9] offset:0
	global_store_dwordx4 v200, v[164:167], s[8:9] offset:1024
	global_store_dwordx4 v200, v[168:171], s[8:9] offset:2048
	global_store_dwordx4 v200, v[172:175], s[8:9] offset:3072
	v_pk_add_f32 v[176:177], v[160:161], v[162:163]
	v_pk_add_f32 v[176:177], v[176:177], v[164:165]
	v_pk_add_f32 v[176:177], v[176:177], v[166:167]
	v_pk_add_f32 v[176:177], v[176:177], v[168:169]
	v_pk_add_f32 v[176:177], v[176:177], v[170:171]
	v_pk_add_f32 v[176:177], v[176:177], v[172:173]
	v_pk_add_f32 v[176:177], v[176:177], v[174:175]
	v_add_f32_e32 v194, v176, v177
	s_nop 1
	v_add_f32_dpp v192, v194, v194 quad_perm:[1,0,3,2] row_mask:0xf bank_mask:0xf
	s_nop 1
	v_add_f32_dpp v192, v192, v192 quad_perm:[2,3,0,1] row_mask:0xf bank_mask:0xf
	s_nop 1
	v_add_f32_dpp v192, v192, v192 row_half_mirror row_mask:0xf bank_mask:0xf
	s_nop 1
	v_add_f32_dpp v192, v192, v192 row_mirror row_mask:0xf bank_mask:0xf
	s_nop 1
	v_add_f32_dpp v192, v192, v192 row_bcast:15 row_mask:0xa bank_mask:0xf
	s_nop 1
	v_add_f32_dpp v192, v192, v192 row_bcast:31 row_mask:0xc bank_mask:0xf
	s_nop 1
	v_readlane_b32 s42, v192, 63
	s_nop 3
	s_mov_b32 s43, s42
	v_pk_fma_f32 v[160:161], s[42:43], v[196:197], v[160:161]
	v_pk_fma_f32 v[162:163], s[42:43], v[196:197], v[162:163]
	v_pk_fma_f32 v[164:165], s[42:43], v[196:197], v[164:165]
	v_pk_fma_f32 v[166:167], s[42:43], v[196:197], v[166:167]
	v_pk_fma_f32 v[168:169], s[42:43], v[196:197], v[168:169]
	v_pk_fma_f32 v[170:171], s[42:43], v[196:197], v[170:171]
	v_pk_fma_f32 v[172:173], s[42:43], v[196:197], v[172:173]
	v_pk_fma_f32 v[174:175], s[42:43], v[196:197], v[174:175]
	v_pk_mul_f32 v[176:177], v[160:161], v[160:161]
	v_pk_fma_f32 v[176:177], v[162:163], v[162:163], v[176:177]
	v_pk_fma_f32 v[176:177], v[164:165], v[164:165], v[176:177]
	v_pk_fma_f32 v[176:177], v[166:167], v[166:167], v[176:177]
	v_pk_fma_f32 v[176:177], v[168:169], v[168:169], v[176:177]
	v_pk_fma_f32 v[176:177], v[170:171], v[170:171], v[176:177]
	v_pk_fma_f32 v[176:177], v[172:173], v[172:173], v[176:177]
	v_pk_fma_f32 v[176:177], v[174:175], v[174:175], v[176:177]
	v_add_f32_e32 v194, v176, v177
	s_nop 1
	v_add_f32_dpp v192, v194, v194 quad_perm:[1,0,3,2] row_mask:0xf bank_mask:0xf
	s_nop 1
	v_add_f32_dpp v192, v192, v192 quad_perm:[2,3,0,1] row_mask:0xf bank_mask:0xf
	s_nop 1
	v_add_f32_dpp v192, v192, v192 row_half_mirror row_mask:0xf bank_mask:0xf
	s_nop 1
	v_add_f32_dpp v192, v192, v192 row_mirror row_mask:0xf bank_mask:0xf
	s_nop 1
	v_add_f32_dpp v192, v192, v192 row_bcast:15 row_mask:0xa bank_mask:0xf
	s_nop 1
	v_add_f32_dpp v192, v192, v192 row_bcast:31 row_mask:0xc bank_mask:0xf
	s_nop 1
	v_readlane_b32 s42, v192, 63
	s_nop 3
	v_fma_f32 v198, s42, v202, v203
	v_rsq_f32_e32 v198, v198
	s_nop 0
	v_pk_mul_f32 v[160:161], v[160:161], v[198:199] op_sel_hi:[1,0]
	v_pk_mul_f32 v[162:163], v[162:163], v[198:199] op_sel_hi:[1,0]
	v_pk_mul_f32 v[164:165], v[164:165], v[198:199] op_sel_hi:[1,0]
	v_pk_mul_f32 v[166:167], v[166:167], v[198:199] op_sel_hi:[1,0]
	v_pk_mul_f32 v[168:169], v[168:169], v[198:199] op_sel_hi:[1,0]
	v_pk_mul_f32 v[170:171], v[170:171], v[198:199] op_sel_hi:[1,0]
	v_pk_mul_f32 v[172:173], v[172:173], v[198:199] op_sel_hi:[1,0]
	v_pk_mul_f32 v[174:175], v[174:175], v[198:199] op_sel_hi:[1,0]
	v_pk_fma_f32 v[160:161], v[160:161], v[32:33], v[48:49]
	v_pk_fma_f32 v[162:163], v[162:163], v[34:35], v[50:51]
	v_pk_fma_f32 v[164:165], v[164:165], v[36:37], v[52:53]
	v_pk_fma_f32 v[166:167], v[166:167], v[38:39], v[54:55]
	v_pk_fma_f32 v[168:169], v[168:169], v[40:41], v[56:57]
	v_pk_fma_f32 v[170:171], v[170:171], v[42:43], v[58:59]
	v_pk_fma_f32 v[172:173], v[172:173], v[44:45], v[60:61]
	v_pk_fma_f32 v[174:175], v[174:175], v[46:47], v[62:63]
	v_cvt_pk_bf16_f32 v176, v160, v161
	v_cvt_pk_bf16_f32 v177, v162, v163
	v_cvt_pk_bf16_f32 v178, v164, v165
	v_cvt_pk_bf16_f32 v179, v166, v167
	v_cvt_pk_bf16_f32 v180, v168, v169
	v_cvt_pk_bf16_f32 v181, v170, v171
	v_cvt_pk_bf16_f32 v182, v172, v173
	v_cvt_pk_bf16_f32 v183, v174, v175
	global_store_dwordx2 v201, v[176:177], s[12:13] offset:0
	global_store_dwordx2 v201, v[178:179], s[12:13] offset:512
	global_store_dwordx2 v201, v[180:181], s[12:13] offset:1024
	global_store_dwordx2 v201, v[182:183], s[12:13] offset:1536
	s_add_u32 s8, s8, 0x1000
	s_addc_u32 s9, s9, 0
	s_add_u32 s12, s12, 0x800
	s_addc_u32 s13, s13, 0
	s_mov_b64 s[16:17], 0x1000
	s_mov_b32 s18, 0x800000
	s_mov_b32 s19, 0xec00000
	s_mov_b32 s20, 0x2400000
	s_add_u32 s28, s90, 0x21b3000
	s_addc_u32 s29, s91, 0
	s_mov_b32 s15, 0x8000
	s_mov_b32 s14, 0x3fb504f3

.LBB0_1448:
	s_or_b64 exec, exec, s[2:3]
	s_waitcnt lgkmcnt(0)
	s_barrier
	s_mov_b32 s5, 0x8000
	v_ashrrev_i32_e32 v0, 6, v208
	v_add_u32_e32 v38, s60, v0
	v_cmp_gt_i32_e32 vcc, s5, v38
	s_and_saveexec_b64 s[2:3], vcc
	s_add_u32 s46, s90, 0xec00000
	s_addc_u32 s47, s91, 0
	s_add_u32 s48, s64, 0x1000
	s_addc_u32 s49, s65, 0
	s_add_u32 s50, s66, 0x1000
	s_addc_u32 s51, s67, 0
	v_lshrrev_b32_e32 v192, 6, v208
	v_and_b32_e32 v193, 63, v208
	v_readfirstlane_b32 s42, v192
	v_lshlrev_b32_e32 v200, 4, v193
	v_lshlrev_b32_e32 v201, 3, v193
	s_nop 1
	s_add_u32 s1, s60, s42
	s_lshl_b32 s42, s1, 16
	s_add_u32 s14, s46, s42
	s_addc_u32 s15, s47, 0
	s_add_u32 s8, s88, s42
	s_addc_u32 s9, s89, 0
	s_lshr_b32 s42, s42, 1
	s_add_u32 s6, s90, s42
	s_addc_u32 s7, s91, 0
	s_add_u32 s12, s6, 0x2400000
	s_addc_u32 s13, s7, 0
	s_add_u32 s6, s6, 0x16c00000
	s_addc_u32 s7, s7, 0
	s_lshr_b32 s42, s1, 7
	s_mul_i32 s42, s42, 0x3000
	s_add_u32 s38, s90, s42
	s_addc_u32 s39, s91, 0
	s_add_u32 s38, s38, 0x21b3000
	s_addc_u32 s39, s39, 0
	s_add_u32 s40, s38, 0x1000
	s_addc_u32 s41, s39, 0
	global_load_dwordx4 v[0:3], v200, s[48:49] offset:0
	global_load_dwordx4 v[4:7], v200, s[48:49] offset:1024
	global_load_dwordx4 v[8:11], v200, s[48:49] offset:2048
	global_load_dwordx4 v[12:15], v200, s[48:49] offset:3072
	global_load_dwordx4 v[16:19], v200, s[50:51] offset:0
	global_load_dwordx4 v[20:23], v200, s[50:51] offset:1024
	global_load_dwordx4 v[24:27], v200, s[50:51] offset:2048
	global_load_dwordx4 v[28:31], v200, s[50:51] offset:3072
	global_load_dwordx4 v[32:35], v200, s[40:41] offset:0
	global_load_dwordx4 v[36:39], v200, s[40:41] offset:1024
	global_load_dwordx4 v[40:43], v200, s[40:41] offset:2048
	global_load_dwordx4 v[44:47], v200, s[40:41] offset:3072
	global_load_dwordx4 v[48:51], v200, s[38:39] offset:0
	global_load_dwordx4 v[52:55], v200, s[38:39] offset:1024
	global_load_dwordx4 v[56:59], v200, s[38:39] offset:2048
	global_load_dwordx4 v[60:63], v200, s[38:39] offset:3072
	v_mov_b32_e32 v196, 0xba800000
	v_mov_b32_e32 v197, 0xba800000
	v_mov_b32_e32 v202, 0x3a800000
	v_mov_b32_e32 v203, 0x358637bd
	s_mov_b32 s44, 0x3fb504f3
	s_mov_b32 s45, 0x3fb504f3
	global_load_dwordx4 v[64:67], v200, s[14:15] offset:0
	global_load_dwordx4 v[68:71], v200, s[14:15] offset:1024
	global_load_dwordx4 v[72:75], v200, s[14:15] offset:2048
	global_load_dwordx4 v[76:79], v200, s[14:15] offset:3072
	global_load_dwordx2 v[128:129], v201, s[6:7] offset:0
	global_load_dwordx2 v[130:131], v201, s[6:7] offset:512
	global_load_dwordx2 v[132:133], v201, s[6:7] offset:1024
	global_load_dwordx2 v[134:135], v201, s[6:7] offset:1536
	s_add_u32 s14, s14, 0x1000
	s_addc_u32 s15, s15, 0
	s_add_u32 s6, s6, 0x800
	s_addc_u32 s7, s7, 0
	global_load_dwordx4 v[80:83], v200, s[14:15] offset:0
	global_load_dwordx4 v[84:87], v200, s[14:15] offset:1024
	global_load_dwordx4 v[88:91], v200, s[14:15] offset:2048
	global_load_dwordx4 v[92:95], v200, s[14:15] offset:3072
	global_load_dwordx2 v[136:137], v201, s[6:7] offset:0
	global_load_dwordx2 v[138:139], v201, s[6:7] offset:512
	global_load_dwordx2 v[140:141], v201, s[6:7] offset:1024
	global_load_dwordx2 v[142:143], v201, s[6:7] offset:1536
	s_add_u32 s14, s14, 0x1000
	s_addc_u32 s15, s15, 0
	s_add_u32 s6, s6, 0x800
	s_addc_u32 s7, s7, 0
	global_load_dwordx4 v[96:99], v200, s[14:15] offset:0
	global_load_dwordx4 v[100:103], v200, s[14:15] offset:1024
	global_load_dwordx4 v[104:107], v200, s[14:15] offset:2048
	global_load_dwordx4 v[108:111], v200, s[14:15] offset:3072
	global_load_dwordx2 v[144:145], v201, s[6:7] offset:0
	global_load_dwordx2 v[146:147], v201, s[6:7] offset:512
	global_load_dwordx2 v[148:149], v201, s[6:7] offset:1024
	global_load_dwordx2 v[150:151], v201, s[6:7] offset:1536
	s_add_u32 s14, s14, 0x1000
	s_addc_u32 s15, s15, 0
	s_add_u32 s6, s6, 0x800
	s_addc_u32 s7, s7, 0
	global_load_dwordx4 v[112:115], v200, s[14:15] offset:0
	global_load_dwordx4 v[116:119], v200, s[14:15] offset:1024
	global_load_dwordx4 v[120:123], v200, s[14:15] offset:2048
	global_load_dwordx4 v[124:127], v200, s[14:15] offset:3072
	global_load_dwordx2 v[152:153], v201, s[6:7] offset:0
	global_load_dwordx2 v[154:155], v201, s[6:7] offset:512
	global_load_dwordx2 v[156:157], v201, s[6:7] offset:1024
	global_load_dwordx2 v[158:159], v201, s[6:7] offset:1536
	s_add_u32 s14, s14, 0x1000
	s_addc_u32 s15, s15, 0
	s_add_u32 s6, s6, 0x800
	s_addc_u32 s7, s7, 0
	s_waitcnt vmcnt(24)
	v_pk_add_f32 v[32:33], v[32:33], 1.0 op_sel_hi:[1,0]
	v_pk_add_f32 v[34:35], v[34:35], 1.0 op_sel_hi:[1,0]
	v_pk_add_f32 v[36:37], v[36:37], 1.0 op_sel_hi:[1,0]
	v_pk_add_f32 v[38:39], v[38:39], 1.0 op_sel_hi:[1,0]
	v_pk_add_f32 v[40:41], v[40:41], 1.0 op_sel_hi:[1,0]
	v_pk_add_f32 v[42:43], v[42:43], 1.0 op_sel_hi:[1,0]
	v_pk_add_f32 v[44:45], v[44:45], 1.0 op_sel_hi:[1,0]
	v_pk_add_f32 v[46:47], v[46:47], 1.0 op_sel_hi:[1,0]
	v_lshlrev_b32_e32 v160, 16, v128
	v_and_b32_e32 v161, 0xffff0000, v128
	v_lshlrev_b32_e32 v162, 16, v129
	v_and_b32_e32 v163, 0xffff0000, v129
	v_lshlrev_b32_e32 v164, 16, v130
	v_and_b32_e32 v165, 0xffff0000, v130
	v_lshlrev_b32_e32 v166, 16, v131
	v_and_b32_e32 v167, 0xffff0000, v131
	v_lshlrev_b32_e32 v168, 16, v132
	v_and_b32_e32 v169, 0xffff0000, v132
	v_lshlrev_b32_e32 v170, 16, v133
	v_and_b32_e32 v171, 0xffff0000, v133
	v_lshlrev_b32_e32 v172, 16, v134
	v_and_b32_e32 v173, 0xffff0000, v134
	v_lshlrev_b32_e32 v174, 16, v135
	v_and_b32_e32 v175, 0xffff0000, v135
	v_pk_fma_f32 v[160:161], v[64:65], s[44:45], v[160:161]
	v_pk_fma_f32 v[162:163], v[66:67], s[44:45], v[162:163]
	v_pk_fma_f32 v[164:165], v[68:69], s[44:45], v[164:165]
	v_pk_fma_f32 v[166:167], v[70:71], s[44:45], v[166:167]
	v_pk_fma_f32 v[168:169], v[72:73], s[44:45], v[168:169]
	v_pk_fma_f32 v[170:171], v[74:75], s[44:45], v[170:171]
	v_pk_fma_f32 v[172:173], v[76:77], s[44:45], v[172:173]
	v_pk_fma_f32 v[174:175], v[78:79], s[44:45], v[174:175]
	v_pk_add_f32 v[176:177], v[160:161], v[162:163]
	v_pk_add_f32 v[176:177], v[176:177], v[164:165]
	v_pk_add_f32 v[176:177], v[176:177], v[166:167]
	v_pk_add_f32 v[176:177], v[176:177], v[168:169]
	v_pk_add_f32 v[176:177], v[176:177], v[170:171]
	v_pk_add_f32 v[176:177], v[176:177], v[172:173]
	v_pk_add_f32 v[176:177], v[176:177], v[174:175]
	v_add_f32_e32 v194, v176, v177
	s_nop 1
	v_add_f32_dpp v192, v194, v194 quad_perm:[1,0,3,2] row_mask:0xf bank_mask:0xf
	s_nop 1
	v_add_f32_dpp v192, v192, v192 quad_perm:[2,3,0,1] row_mask:0xf bank_mask:0xf
	s_nop 1
	v_add_f32_dpp v192, v192, v192 row_half_mirror row_mask:0xf bank_mask:0xf
	s_nop 1
	v_add_f32_dpp v192, v192, v192 row_mirror row_mask:0xf bank_mask:0xf
	s_nop 1
	v_add_f32_dpp v192, v192, v192 row_bcast:15 row_mask:0xa bank_mask:0xf
	s_nop 1
	v_add_f32_dpp v192, v192, v192 row_bcast:31 row_mask:0xc bank_mask:0xf
	s_nop 1
	v_readlane_b32 s42, v192, 63
	s_nop 3
	s_mov_b32 s43, s42
	v_pk_fma_f32 v[160:161], s[42:43], v[196:197], v[160:161]
	v_pk_fma_f32 v[162:163], s[42:43], v[196:197], v[162:163]
	v_pk_fma_f32 v[164:165], s[42:43], v[196:197], v[164:165]
	v_pk_fma_f32 v[166:167], s[42:43], v[196:197], v[166:167]
	v_pk_fma_f32 v[168:169], s[42:43], v[196:197], v[168:169]
	v_pk_fma_f32 v[170:171], s[42:43], v[196:197], v[170:171]
	v_pk_fma_f32 v[172:173], s[42:43], v[196:197], v[172:173]
	v_pk_fma_f32 v[174:175], s[42:43], v[196:197], v[174:175]
	v_pk_mul_f32 v[176:177], v[160:161], v[160:161]
	v_pk_fma_f32 v[176:177], v[162:163], v[162:163], v[176:177]
	v_pk_fma_f32 v[176:177], v[164:165], v[164:165], v[176:177]
	v_pk_fma_f32 v[176:177], v[166:167], v[166:167], v[176:177]
	v_pk_fma_f32 v[176:177], v[168:169], v[168:169], v[176:177]
	v_pk_fma_f32 v[176:177], v[170:171], v[170:171], v[176:177]
	v_pk_fma_f32 v[176:177], v[172:173], v[172:173], v[176:177]
	v_pk_fma_f32 v[176:177], v[174:175], v[174:175], v[176:177]
	v_add_f32_e32 v194, v176, v177
	s_nop 1
	v_add_f32_dpp v192, v194, v194 quad_perm:[1,0,3,2] row_mask:0xf bank_mask:0xf
	s_nop 1
	v_add_f32_dpp v192, v192, v192 quad_perm:[2,3,0,1] row_mask:0xf bank_mask:0xf
	s_nop 1
	v_add_f32_dpp v192, v192, v192 row_half_mirror row_mask:0xf bank_mask:0xf
	s_nop 1
	v_add_f32_dpp v192, v192, v192 row_mirror row_mask:0xf bank_mask:0xf
	s_nop 1
	v_add_f32_dpp v192, v192, v192 row_bcast:15 row_mask:0xa bank_mask:0xf
	s_nop 1
	v_add_f32_dpp v192, v192, v192 row_bcast:31 row_mask:0xc bank_mask:0xf
	s_nop 1
	v_readlane_b32 s42, v192, 63
	s_nop 3
	v_fma_f32 v198, s42, v202, v203
	v_rsq_f32_e32 v198, v198
	s_nop 0
	v_pk_mul_f32 v[160:161], v[160:161], v[198:199] op_sel_hi:[1,0]
	v_pk_mul_f32 v[162:163], v[162:163], v[198:199] op_sel_hi:[1,0]
	v_pk_mul_f32 v[164:165], v[164:165], v[198:199] op_sel_hi:[1,0]
	v_pk_mul_f32 v[166:167], v[166:167], v[198:199] op_sel_hi:[1,0]
	v_pk_mul_f32 v[168:169], v[168:169], v[198:199] op_sel_hi:[1,0]
	v_pk_mul_f32 v[170:171], v[170:171], v[198:199] op_sel_hi:[1,0]
	v_pk_mul_f32 v[172:173], v[172:173], v[198:199] op_sel_hi:[1,0]
	v_pk_mul_f32 v[174:175], v[174:175], v[198:199] op_sel_hi:[1,0]
	v_pk_fma_f32 v[160:161], v[160:161], v[0:1], v[16:17]
	v_pk_fma_f32 v[162:163], v[162:163], v[2:3], v[18:19]
	v_pk_fma_f32 v[164:165], v[164:165], v[4:5], v[20:21]
	v_pk_fma_f32 v[166:167], v[166:167], v[6:7], v[22:23]
	v_pk_fma_f32 v[168:169], v[168:169], v[8:9], v[24:25]
	v_pk_fma_f32 v[170:171], v[170:171], v[10:11], v[26:27]
	v_pk_fma_f32 v[172:173], v[172:173], v[12:13], v[28:29]
	v_pk_fma_f32 v[174:175], v[174:175], v[14:15], v[30:31]
	global_store_dwordx4 v200, v[160:163], s[8:9] offset:0
	global_store_dwordx4 v200, v[164:167], s[8:9] offset:1024
	global_store_dwordx4 v200, v[168:171], s[8:9] offset:2048
	global_store_dwordx4 v200, v[172:175], s[8:9] offset:3072
	s_add_u32 s8, s8, 0x1000
	s_addc_u32 s9, s9, 0
	s_add_u32 s12, s12, 0x800
	s_addc_u32 s13, s13, 0
	global_load_dwordx4 v[64:67], v200, s[14:15] offset:0
	global_load_dwordx4 v[68:71], v200, s[14:15] offset:1024
	global_load_dwordx4 v[72:75], v200, s[14:15] offset:2048
	global_load_dwordx4 v[76:79], v200, s[14:15] offset:3072
	global_load_dwordx2 v[128:129], v201, s[6:7] offset:0
	global_load_dwordx2 v[130:131], v201, s[6:7] offset:512
	global_load_dwordx2 v[132:133], v201, s[6:7] offset:1024
	global_load_dwordx2 v[134:135], v201, s[6:7] offset:1536
	s_add_u32 s14, s14, 0x1000
	s_addc_u32 s15, s15, 0
	s_add_u32 s6, s6, 0x800
	s_addc_u32 s7, s7, 0
	s_waitcnt vmcnt(28)
	v_lshlrev_b32_e32 v160, 16, v136
	v_and_b32_e32 v161, 0xffff0000, v136
	v_lshlrev_b32_e32 v162, 16, v137
	v_and_b32_e32 v163, 0xffff0000, v137
	v_lshlrev_b32_e32 v164, 16, v138
	v_and_b32_e32 v165, 0xffff0000, v138
	v_lshlrev_b32_e32 v166, 16, v139
	v_and_b32_e32 v167, 0xffff0000, v139
	v_lshlrev_b32_e32 v168, 16, v140
	v_and_b32_e32 v169, 0xffff0000, v140
	v_lshlrev_b32_e32 v170, 16, v141
	v_and_b32_e32 v171, 0xffff0000, v141
	v_lshlrev_b32_e32 v172, 16, v142
	v_and_b32_e32 v173, 0xffff0000, v142
	v_lshlrev_b32_e32 v174, 16, v143
	v_and_b32_e32 v175, 0xffff0000, v143
	v_pk_fma_f32 v[160:161], v[80:81], s[44:45], v[160:161]
	v_pk_fma_f32 v[162:163], v[82:83], s[44:45], v[162:163]
	v_pk_fma_f32 v[164:165], v[84:85], s[44:45], v[164:165]
	v_pk_fma_f32 v[166:167], v[86:87], s[44:45], v[166:167]
	v_pk_fma_f32 v[168:169], v[88:89], s[44:45], v[168:169]
	v_pk_fma_f32 v[170:171], v[90:91], s[44:45], v[170:171]
	v_pk_fma_f32 v[172:173], v[92:93], s[44:45], v[172:173]
	v_pk_fma_f32 v[174:175], v[94:95], s[44:45], v[174:175]
	v_pk_add_f32 v[176:177], v[160:161], v[162:163]
	v_pk_add_f32 v[176:177], v[176:177], v[164:165]
	v_pk_add_f32 v[176:177], v[176:177], v[166:167]
	v_pk_add_f32 v[176:177], v[176:177], v[168:169]
	v_pk_add_f32 v[176:177], v[176:177], v[170:171]
	v_pk_add_f32 v[176:177], v[176:177], v[172:173]
	v_pk_add_f32 v[176:177], v[176:177], v[174:175]
	v_add_f32_e32 v194, v176, v177
	s_nop 1
	v_add_f32_dpp v192, v194, v194 quad_perm:[1,0,3,2] row_mask:0xf bank_mask:0xf
	s_nop 1
	v_add_f32_dpp v192, v192, v192 quad_perm:[2,3,0,1] row_mask:0xf bank_mask:0xf
	s_nop 1
	v_add_f32_dpp v192, v192, v192 row_half_mirror row_mask:0xf bank_mask:0xf
	s_nop 1
	v_add_f32_dpp v192, v192, v192 row_mirror row_mask:0xf bank_mask:0xf
	s_nop 1
	v_add_f32_dpp v192, v192, v192 row_bcast:15 row_mask:0xa bank_mask:0xf
	s_nop 1
	v_add_f32_dpp v192, v192, v192 row_bcast:31 row_mask:0xc bank_mask:0xf
	s_nop 1
	v_readlane_b32 s42, v192, 63
	s_nop 3
	s_mov_b32 s43, s42
	v_pk_fma_f32 v[160:161], s[42:43], v[196:197], v[160:161]
	v_pk_fma_f32 v[162:163], s[42:43], v[196:197], v[162:163]
	v_pk_fma_f32 v[164:165], s[42:43], v[196:197], v[164:165]
	v_pk_fma_f32 v[166:167], s[42:43], v[196:197], v[166:167]
	v_pk_fma_f32 v[168:169], s[42:43], v[196:197], v[168:169]
	v_pk_fma_f32 v[170:171], s[42:43], v[196:197], v[170:171]
	v_pk_fma_f32 v[172:173], s[42:43], v[196:197], v[172:173]
	v_pk_fma_f32 v[174:175], s[42:43], v[196:197], v[174:175]
	v_pk_mul_f32 v[176:177], v[160:161], v[160:161]
	v_pk_fma_f32 v[176:177], v[162:163], v[162:163], v[176:177]
	v_pk_fma_f32 v[176:177], v[164:165], v[164:165], v[176:177]
	v_pk_fma_f32 v[176:177], v[166:167], v[166:167], v[176:177]
	v_pk_fma_f32 v[176:177], v[168:169], v[168:169], v[176:177]
	v_pk_fma_f32 v[176:177], v[170:171], v[170:171], v[176:177]
	v_pk_fma_f32 v[176:177], v[172:173], v[172:173], v[176:177]
	v_pk_fma_f32 v[176:177], v[174:175], v[174:175], v[176:177]
	v_add_f32_e32 v194, v176, v177
	s_nop 1
	v_add_f32_dpp v192, v194, v194 quad_perm:[1,0,3,2] row_mask:0xf bank_mask:0xf
	s_nop 1
	v_add_f32_dpp v192, v192, v192 quad_perm:[2,3,0,1] row_mask:0xf bank_mask:0xf
	s_nop 1
	v_add_f32_dpp v192, v192, v192 row_half_mirror row_mask:0xf bank_mask:0xf
	s_nop 1
	v_add_f32_dpp v192, v192, v192 row_mirror row_mask:0xf bank_mask:0xf
	s_nop 1
	v_add_f32_dpp v192, v192, v192 row_bcast:15 row_mask:0xa bank_mask:0xf
	s_nop 1
	v_add_f32_dpp v192, v192, v192 row_bcast:31 row_mask:0xc bank_mask:0xf
	s_nop 1
	v_readlane_b32 s42, v192, 63
	s_nop 3
	v_fma_f32 v198, s42, v202, v203
	v_rsq_f32_e32 v198, v198
	s_nop 0
	v_pk_mul_f32 v[160:161], v[160:161], v[198:199] op_sel_hi:[1,0]
	v_pk_mul_f32 v[162:163], v[162:163], v[198:199] op_sel_hi:[1,0]
	v_pk_mul_f32 v[164:165], v[164:165], v[198:199] op_sel_hi:[1,0]
	v_pk_mul_f32 v[166:167], v[166:167], v[198:199] op_sel_hi:[1,0]
	v_pk_mul_f32 v[168:169], v[168:169], v[198:199] op_sel_hi:[1,0]
	v_pk_mul_f32 v[170:171], v[170:171], v[198:199] op_sel_hi:[1,0]
	v_pk_mul_f32 v[172:173], v[172:173], v[198:199] op_sel_hi:[1,0]
	v_pk_mul_f32 v[174:175], v[174:175], v[198:199] op_sel_hi:[1,0]
	v_pk_fma_f32 v[160:161], v[160:161], v[0:1], v[16:17]
	v_pk_fma_f32 v[162:163], v[162:163], v[2:3], v[18:19]
	v_pk_fma_f32 v[164:165], v[164:165], v[4:5], v[20:21]
	v_pk_fma_f32 v[166:167], v[166:167], v[6:7], v[22:23]
	v_pk_fma_f32 v[168:169], v[168:169], v[8:9], v[24:25]
	v_pk_fma_f32 v[170:171], v[170:171], v[10:11], v[26:27]
	v_pk_fma_f32 v[172:173], v[172:173], v[12:13], v[28:29]
	v_pk_fma_f32 v[174:175], v[174:175], v[14:15], v[30:31]
	global_store_dwordx4 v200, v[160:163], s[8:9] offset:0
	global_store_dwordx4 v200, v[164:167], s[8:9] offset:1024
	global_store_dwordx4 v200, v[168:171], s[8:9] offset:2048
	global_store_dwordx4 v200, v[172:175], s[8:9] offset:3072
	s_add_u32 s8, s8, 0x1000
	s_addc_u32 s9, s9, 0
	s_add_u32 s12, s12, 0x800
	s_addc_u32 s13, s13, 0
	global_load_dwordx4 v[80:83], v200, s[14:15] offset:0
	global_load_dwordx4 v[84:87], v200, s[14:15] offset:1024
	global_load_dwordx4 v[88:91], v200, s[14:15] offset:2048
	global_load_dwordx4 v[92:95], v200, s[14:15] offset:3072
	global_load_dwordx2 v[136:137], v201, s[6:7] offset:0
	global_load_dwordx2 v[138:139], v201, s[6:7] offset:512
	global_load_dwordx2 v[140:141], v201, s[6:7] offset:1024
	global_load_dwordx2 v[142:143], v201, s[6:7] offset:1536
	s_add_u32 s14, s14, 0x1000
	s_addc_u32 s15, s15, 0
	s_add_u32 s6, s6, 0x800
	s_addc_u32 s7, s7, 0
	s_waitcnt vmcnt(32)
	v_lshlrev_b32_e32 v160, 16, v144
	v_and_b32_e32 v161, 0xffff0000, v144
	v_lshlrev_b32_e32 v162, 16, v145
	v_and_b32_e32 v163, 0xffff0000, v145
	v_lshlrev_b32_e32 v164, 16, v146
	v_and_b32_e32 v165, 0xffff0000, v146
	v_lshlrev_b32_e32 v166, 16, v147
	v_and_b32_e32 v167, 0xffff0000, v147
	v_lshlrev_b32_e32 v168, 16, v148
	v_and_b32_e32 v169, 0xffff0000, v148
	v_lshlrev_b32_e32 v170, 16, v149
	v_and_b32_e32 v171, 0xffff0000, v149
	v_lshlrev_b32_e32 v172, 16, v150
	v_and_b32_e32 v173, 0xffff0000, v150
	v_lshlrev_b32_e32 v174, 16, v151
	v_and_b32_e32 v175, 0xffff0000, v151
	v_pk_fma_f32 v[160:161], v[96:97], s[44:45], v[160:161]
	v_pk_fma_f32 v[162:163], v[98:99], s[44:45], v[162:163]
	v_pk_fma_f32 v[164:165], v[100:101], s[44:45], v[164:165]
	v_pk_fma_f32 v[166:167], v[102:103], s[44:45], v[166:167]
	v_pk_fma_f32 v[168:169], v[104:105], s[44:45], v[168:169]
	v_pk_fma_f32 v[170:171], v[106:107], s[44:45], v[170:171]
	v_pk_fma_f32 v[172:173], v[108:109], s[44:45], v[172:173]
	v_pk_fma_f32 v[174:175], v[110:111], s[44:45], v[174:175]
	v_pk_add_f32 v[176:177], v[160:161], v[162:163]
	v_pk_add_f32 v[176:177], v[176:177], v[164:165]
	v_pk_add_f32 v[176:177], v[176:177], v[166:167]
	v_pk_add_f32 v[176:177], v[176:177], v[168:169]
	v_pk_add_f32 v[176:177], v[176:177], v[170:171]
	v_pk_add_f32 v[176:177], v[176:177], v[172:173]
	v_pk_add_f32 v[176:177], v[176:177], v[174:175]
	v_add_f32_e32 v194, v176, v177
	s_nop 1
	v_add_f32_dpp v192, v194, v194 quad_perm:[1,0,3,2] row_mask:0xf bank_mask:0xf
	s_nop 1
	v_add_f32_dpp v192, v192, v192 quad_perm:[2,3,0,1] row_mask:0xf bank_mask:0xf
	s_nop 1
	v_add_f32_dpp v192, v192, v192 row_half_mirror row_mask:0xf bank_mask:0xf
	s_nop 1
	v_add_f32_dpp v192, v192, v192 row_mirror row_mask:0xf bank_mask:0xf
	s_nop 1
	v_add_f32_dpp v192, v192, v192 row_bcast:15 row_mask:0xa bank_mask:0xf
	s_nop 1
	v_add_f32_dpp v192, v192, v192 row_bcast:31 row_mask:0xc bank_mask:0xf
	s_nop 1
	v_readlane_b32 s42, v192, 63
	s_nop 3
	s_mov_b32 s43, s42
	v_pk_fma_f32 v[160:161], s[42:43], v[196:197], v[160:161]
	v_pk_fma_f32 v[162:163], s[42:43], v[196:197], v[162:163]
	v_pk_fma_f32 v[164:165], s[42:43], v[196:197], v[164:165]
	v_pk_fma_f32 v[166:167], s[42:43], v[196:197], v[166:167]
	v_pk_fma_f32 v[168:169], s[42:43], v[196:197], v[168:169]
	v_pk_fma_f32 v[170:171], s[42:43], v[196:197], v[170:171]
	v_pk_fma_f32 v[172:173], s[42:43], v[196:197], v[172:173]
	v_pk_fma_f32 v[174:175], s[42:43], v[196:197], v[174:175]
	v_pk_mul_f32 v[176:177], v[160:161], v[160:161]
	v_pk_fma_f32 v[176:177], v[162:163], v[162:163], v[176:177]
	v_pk_fma_f32 v[176:177], v[164:165], v[164:165], v[176:177]
	v_pk_fma_f32 v[176:177], v[166:167], v[166:167], v[176:177]
	v_pk_fma_f32 v[176:177], v[168:169], v[168:169], v[176:177]
	v_pk_fma_f32 v[176:177], v[170:171], v[170:171], v[176:177]
	v_pk_fma_f32 v[176:177], v[172:173], v[172:173], v[176:177]
	v_pk_fma_f32 v[176:177], v[174:175], v[174:175], v[176:177]
	v_add_f32_e32 v194, v176, v177
	s_nop 1
	v_add_f32_dpp v192, v194, v194 quad_perm:[1,0,3,2] row_mask:0xf bank_mask:0xf
	s_nop 1
	v_add_f32_dpp v192, v192, v192 quad_perm:[2,3,0,1] row_mask:0xf bank_mask:0xf
	s_nop 1
	v_add_f32_dpp v192, v192, v192 row_half_mirror row_mask:0xf bank_mask:0xf
	s_nop 1
	v_add_f32_dpp v192, v192, v192 row_mirror row_mask:0xf bank_mask:0xf
	s_nop 1
	v_add_f32_dpp v192, v192, v192 row_bcast:15 row_mask:0xa bank_mask:0xf
	s_nop 1
	v_add_f32_dpp v192, v192, v192 row_bcast:31 row_mask:0xc bank_mask:0xf
	s_nop 1
	v_readlane_b32 s42, v192, 63
	s_nop 3
	v_fma_f32 v198, s42, v202, v203
	v_rsq_f32_e32 v198, v198
	s_nop 0
	v_pk_mul_f32 v[160:161], v[160:161], v[198:199] op_sel_hi:[1,0]
	v_pk_mul_f32 v[162:163], v[162:163], v[198:199] op_sel_hi:[1,0]
	v_pk_mul_f32 v[164:165], v[164:165], v[198:199] op_sel_hi:[1,0]
	v_pk_mul_f32 v[166:167], v[166:167], v[198:199] op_sel_hi:[1,0]
	v_pk_mul_f32 v[168:169], v[168:169], v[198:199] op_sel_hi:[1,0]
	v_pk_mul_f32 v[170:171], v[170:171], v[198:199] op_sel_hi:[1,0]
	v_pk_mul_f32 v[172:173], v[172:173], v[198:199] op_sel_hi:[1,0]
	v_pk_mul_f32 v[174:175], v[174:175], v[198:199] op_sel_hi:[1,0]
	v_pk_fma_f32 v[160:161], v[160:161], v[0:1], v[16:17]
	v_pk_fma_f32 v[162:163], v[162:163], v[2:3], v[18:19]
	v_pk_fma_f32 v[164:165], v[164:165], v[4:5], v[20:21]
	v_pk_fma_f32 v[166:167], v[166:167], v[6:7], v[22:23]
	v_pk_fma_f32 v[168:169], v[168:169], v[8:9], v[24:25]
	v_pk_fma_f32 v[170:171], v[170:171], v[10:11], v[26:27]
	v_pk_fma_f32 v[172:173], v[172:173], v[12:13], v[28:29]
	v_pk_fma_f32 v[174:175], v[174:175], v[14:15], v[30:31]
	global_store_dwordx4 v200, v[160:163], s[8:9] offset:0
	global_store_dwordx4 v200, v[164:167], s[8:9] offset:1024
	global_store_dwordx4 v200, v[168:171], s[8:9] offset:2048
	global_store_dwordx4 v200, v[172:175], s[8:9] offset:3072
	s_add_u32 s8, s8, 0x1000
	s_addc_u32 s9, s9, 0
	s_add_u32 s12, s12, 0x800
	s_addc_u32 s13, s13, 0
	global_load_dwordx4 v[96:99], v200, s[14:15] offset:0
	global_load_dwordx4 v[100:103], v200, s[14:15] offset:1024
	global_load_dwordx4 v[104:107], v200, s[14:15] offset:2048
	global_load_dwordx4 v[108:111], v200, s[14:15] offset:3072
	global_load_dwordx2 v[144:145], v201, s[6:7] offset:0
	global_load_dwordx2 v[146:147], v201, s[6:7] offset:512
	global_load_dwordx2 v[148:149], v201, s[6:7] offset:1024
	global_load_dwordx2 v[150:151], v201, s[6:7] offset:1536
	s_add_u32 s14, s14, 0x1000
	s_addc_u32 s15, s15, 0
	s_add_u32 s6, s6, 0x800
	s_addc_u32 s7, s7, 0
	s_waitcnt vmcnt(36)
	v_lshlrev_b32_e32 v160, 16, v152
	v_and_b32_e32 v161, 0xffff0000, v152
	v_lshlrev_b32_e32 v162, 16, v153
	v_and_b32_e32 v163, 0xffff0000, v153
	v_lshlrev_b32_e32 v164, 16, v154
	v_and_b32_e32 v165, 0xffff0000, v154
	v_lshlrev_b32_e32 v166, 16, v155
	v_and_b32_e32 v167, 0xffff0000, v155
	v_lshlrev_b32_e32 v168, 16, v156
	v_and_b32_e32 v169, 0xffff0000, v156
	v_lshlrev_b32_e32 v170, 16, v157
	v_and_b32_e32 v171, 0xffff0000, v157
	v_lshlrev_b32_e32 v172, 16, v158
	v_and_b32_e32 v173, 0xffff0000, v158
	v_lshlrev_b32_e32 v174, 16, v159
	v_and_b32_e32 v175, 0xffff0000, v159
	v_pk_fma_f32 v[160:161], v[112:113], s[44:45], v[160:161]
	v_pk_fma_f32 v[162:163], v[114:115], s[44:45], v[162:163]
	v_pk_fma_f32 v[164:165], v[116:117], s[44:45], v[164:165]
	v_pk_fma_f32 v[166:167], v[118:119], s[44:45], v[166:167]
	v_pk_fma_f32 v[168:169], v[120:121], s[44:45], v[168:169]
	v_pk_fma_f32 v[170:171], v[122:123], s[44:45], v[170:171]
	v_pk_fma_f32 v[172:173], v[124:125], s[44:45], v[172:173]
	v_pk_fma_f32 v[174:175], v[126:127], s[44:45], v[174:175]
	v_pk_add_f32 v[176:177], v[160:161], v[162:163]
	v_pk_add_f32 v[176:177], v[176:177], v[164:165]
	v_pk_add_f32 v[176:177], v[176:177], v[166:167]
	v_pk_add_f32 v[176:177], v[176:177], v[168:169]
	v_pk_add_f32 v[176:177], v[176:177], v[170:171]
	v_pk_add_f32 v[176:177], v[176:177], v[172:173]
	v_pk_add_f32 v[176:177], v[176:177], v[174:175]
	v_add_f32_e32 v194, v176, v177
	s_nop 1
	v_add_f32_dpp v192, v194, v194 quad_perm:[1,0,3,2] row_mask:0xf bank_mask:0xf
	s_nop 1
	v_add_f32_dpp v192, v192, v192 quad_perm:[2,3,0,1] row_mask:0xf bank_mask:0xf
	s_nop 1
	v_add_f32_dpp v192, v192, v192 row_half_mirror row_mask:0xf bank_mask:0xf
	s_nop 1
	v_add_f32_dpp v192, v192, v192 row_mirror row_mask:0xf bank_mask:0xf
	s_nop 1
	v_add_f32_dpp v192, v192, v192 row_bcast:15 row_mask:0xa bank_mask:0xf
	s_nop 1
	v_add_f32_dpp v192, v192, v192 row_bcast:31 row_mask:0xc bank_mask:0xf
	s_nop 1
	v_readlane_b32 s42, v192, 63
	s_nop 3
	s_mov_b32 s43, s42
	v_pk_fma_f32 v[160:161], s[42:43], v[196:197], v[160:161]
	v_pk_fma_f32 v[162:163], s[42:43], v[196:197], v[162:163]
	v_pk_fma_f32 v[164:165], s[42:43], v[196:197], v[164:165]
	v_pk_fma_f32 v[166:167], s[42:43], v[196:197], v[166:167]
	v_pk_fma_f32 v[168:169], s[42:43], v[196:197], v[168:169]
	v_pk_fma_f32 v[170:171], s[42:43], v[196:197], v[170:171]
	v_pk_fma_f32 v[172:173], s[42:43], v[196:197], v[172:173]
	v_pk_fma_f32 v[174:175], s[42:43], v[196:197], v[174:175]
	v_pk_mul_f32 v[176:177], v[160:161], v[160:161]
	v_pk_fma_f32 v[176:177], v[162:163], v[162:163], v[176:177]
	v_pk_fma_f32 v[176:177], v[164:165], v[164:165], v[176:177]
	v_pk_fma_f32 v[176:177], v[166:167], v[166:167], v[176:177]
	v_pk_fma_f32 v[176:177], v[168:169], v[168:169], v[176:177]
	v_pk_fma_f32 v[176:177], v[170:171], v[170:171], v[176:177]
	v_pk_fma_f32 v[176:177], v[172:173], v[172:173], v[176:177]
	v_pk_fma_f32 v[176:177], v[174:175], v[174:175], v[176:177]
	v_add_f32_e32 v194, v176, v177
	s_nop 1
	v_add_f32_dpp v192, v194, v194 quad_perm:[1,0,3,2] row_mask:0xf bank_mask:0xf
	s_nop 1
	v_add_f32_dpp v192, v192, v192 quad_perm:[2,3,0,1] row_mask:0xf bank_mask:0xf
	s_nop 1
	v_add_f32_dpp v192, v192, v192 row_half_mirror row_mask:0xf bank_mask:0xf
	s_nop 1
	v_add_f32_dpp v192, v192, v192 row_mirror row_mask:0xf bank_mask:0xf
	s_nop 1
	v_add_f32_dpp v192, v192, v192 row_bcast:15 row_mask:0xa bank_mask:0xf
	s_nop 1
	v_add_f32_dpp v192, v192, v192 row_bcast:31 row_mask:0xc bank_mask:0xf
	s_nop 1
	v_readlane_b32 s42, v192, 63
	s_nop 3
	v_fma_f32 v198, s42, v202, v203
	v_rsq_f32_e32 v198, v198
	s_nop 0
	v_pk_mul_f32 v[160:161], v[160:161], v[198:199] op_sel_hi:[1,0]
	v_pk_mul_f32 v[162:163], v[162:163], v[198:199] op_sel_hi:[1,0]
	v_pk_mul_f32 v[164:165], v[164:165], v[198:199] op_sel_hi:[1,0]
	v_pk_mul_f32 v[166:167], v[166:167], v[198:199] op_sel_hi:[1,0]
	v_pk_mul_f32 v[168:169], v[168:169], v[198:199] op_sel_hi:[1,0]
	v_pk_mul_f32 v[170:171], v[170:171], v[198:199] op_sel_hi:[1,0]
	v_pk_mul_f32 v[172:173], v[172:173], v[198:199] op_sel_hi:[1,0]
	v_pk_mul_f32 v[174:175], v[174:175], v[198:199] op_sel_hi:[1,0]
	v_pk_fma_f32 v[160:161], v[160:161], v[0:1], v[16:17]
	v_pk_fma_f32 v[162:163], v[162:163], v[2:3], v[18:19]
	v_pk_fma_f32 v[164:165], v[164:165], v[4:5], v[20:21]
	v_pk_fma_f32 v[166:167], v[166:167], v[6:7], v[22:23]
	v_pk_fma_f32 v[168:169], v[168:169], v[8:9], v[24:25]
	v_pk_fma_f32 v[170:171], v[170:171], v[10:11], v[26:27]
	v_pk_fma_f32 v[172:173], v[172:173], v[12:13], v[28:29]
	v_pk_fma_f32 v[174:175], v[174:175], v[14:15], v[30:31]
	global_store_dwordx4 v200, v[160:163], s[8:9] offset:0
	global_store_dwordx4 v200, v[164:167], s[8:9] offset:1024
	global_store_dwordx4 v200, v[168:171], s[8:9] offset:2048
	global_store_dwordx4 v200, v[172:175], s[8:9] offset:3072
	s_add_u32 s8, s8, 0x1000
	s_addc_u32 s9, s9, 0
	s_add_u32 s12, s12, 0x800
	s_addc_u32 s13, s13, 0
	global_load_dwordx4 v[112:115], v200, s[14:15] offset:0
	global_load_dwordx4 v[116:119], v200, s[14:15] offset:1024
	global_load_dwordx4 v[120:123], v200, s[14:15] offset:2048
	global_load_dwordx4 v[124:127], v200, s[14:15] offset:3072
	global_load_dwordx2 v[152:153], v201, s[6:7] offset:0
	global_load_dwordx2 v[154:155], v201, s[6:7] offset:512
	global_load_dwordx2 v[156:157], v201, s[6:7] offset:1024
	global_load_dwordx2 v[158:159], v201, s[6:7] offset:1536
	s_add_u32 s14, s14, 0x1000
	s_addc_u32 s15, s15, 0
	s_add_u32 s6, s6, 0x800
	s_addc_u32 s7, s7, 0
	s_waitcnt vmcnt(36)
	v_lshlrev_b32_e32 v160, 16, v128
	v_and_b32_e32 v161, 0xffff0000, v128
	v_lshlrev_b32_e32 v162, 16, v129
	v_and_b32_e32 v163, 0xffff0000, v129
	v_lshlrev_b32_e32 v164, 16, v130
	v_and_b32_e32 v165, 0xffff0000, v130
	v_lshlrev_b32_e32 v166, 16, v131
	v_and_b32_e32 v167, 0xffff0000, v131
	v_lshlrev_b32_e32 v168, 16, v132
	v_and_b32_e32 v169, 0xffff0000, v132
	v_lshlrev_b32_e32 v170, 16, v133
	v_and_b32_e32 v171, 0xffff0000, v133
	v_lshlrev_b32_e32 v172, 16, v134
	v_and_b32_e32 v173, 0xffff0000, v134
	v_lshlrev_b32_e32 v174, 16, v135
	v_and_b32_e32 v175, 0xffff0000, v135
	v_pk_fma_f32 v[160:161], v[64:65], s[44:45], v[160:161]
	v_pk_fma_f32 v[162:163], v[66:67], s[44:45], v[162:163]
	v_pk_fma_f32 v[164:165], v[68:69], s[44:45], v[164:165]
	v_pk_fma_f32 v[166:167], v[70:71], s[44:45], v[166:167]
	v_pk_fma_f32 v[168:169], v[72:73], s[44:45], v[168:169]
	v_pk_fma_f32 v[170:171], v[74:75], s[44:45], v[170:171]
	v_pk_fma_f32 v[172:173], v[76:77], s[44:45], v[172:173]
	v_pk_fma_f32 v[174:175], v[78:79], s[44:45], v[174:175]
	v_pk_add_f32 v[176:177], v[160:161], v[162:163]
	v_pk_add_f32 v[176:177], v[176:177], v[164:165]
	v_pk_add_f32 v[176:177], v[176:177], v[166:167]
	v_pk_add_f32 v[176:177], v[176:177], v[168:169]
	v_pk_add_f32 v[176:177], v[176:177], v[170:171]
	v_pk_add_f32 v[176:177], v[176:177], v[172:173]
	v_pk_add_f32 v[176:177], v[176:177], v[174:175]
	v_add_f32_e32 v194, v176, v177
	s_nop 1
	v_add_f32_dpp v192, v194, v194 quad_perm:[1,0,3,2] row_mask:0xf bank_mask:0xf
	s_nop 1
	v_add_f32_dpp v192, v192, v192 quad_perm:[2,3,0,1] row_mask:0xf bank_mask:0xf
	s_nop 1
	v_add_f32_dpp v192, v192, v192 row_half_mirror row_mask:0xf bank_mask:0xf
	s_nop 1
	v_add_f32_dpp v192, v192, v192 row_mirror row_mask:0xf bank_mask:0xf
	s_nop 1
	v_add_f32_dpp v192, v192, v192 row_bcast:15 row_mask:0xa bank_mask:0xf
	s_nop 1
	v_add_f32_dpp v192, v192, v192 row_bcast:31 row_mask:0xc bank_mask:0xf
	s_nop 1
	v_readlane_b32 s42, v192, 63
	s_nop 3
	s_mov_b32 s43, s42
	v_pk_fma_f32 v[160:161], s[42:43], v[196:197], v[160:161]
	v_pk_fma_f32 v[162:163], s[42:43], v[196:197], v[162:163]
	v_pk_fma_f32 v[164:165], s[42:43], v[196:197], v[164:165]
	v_pk_fma_f32 v[166:167], s[42:43], v[196:197], v[166:167]
	v_pk_fma_f32 v[168:169], s[42:43], v[196:197], v[168:169]
	v_pk_fma_f32 v[170:171], s[42:43], v[196:197], v[170:171]
	v_pk_fma_f32 v[172:173], s[42:43], v[196:197], v[172:173]
	v_pk_fma_f32 v[174:175], s[42:43], v[196:197], v[174:175]
	v_pk_mul_f32 v[176:177], v[160:161], v[160:161]
	v_pk_fma_f32 v[176:177], v[162:163], v[162:163], v[176:177]
	v_pk_fma_f32 v[176:177], v[164:165], v[164:165], v[176:177]
	v_pk_fma_f32 v[176:177], v[166:167], v[166:167], v[176:177]
	v_pk_fma_f32 v[176:177], v[168:169], v[168:169], v[176:177]
	v_pk_fma_f32 v[176:177], v[170:171], v[170:171], v[176:177]
	v_pk_fma_f32 v[176:177], v[172:173], v[172:173], v[176:177]
	v_pk_fma_f32 v[176:177], v[174:175], v[174:175], v[176:177]
	v_add_f32_e32 v194, v176, v177
	s_nop 1
	v_add_f32_dpp v192, v194, v194 quad_perm:[1,0,3,2] row_mask:0xf bank_mask:0xf
	s_nop 1
	v_add_f32_dpp v192, v192, v192 quad_perm:[2,3,0,1] row_mask:0xf bank_mask:0xf
	s_nop 1
	v_add_f32_dpp v192, v192, v192 row_half_mirror row_mask:0xf bank_mask:0xf
	s_nop 1
	v_add_f32_dpp v192, v192, v192 row_mirror row_mask:0xf bank_mask:0xf
	s_nop 1
	v_add_f32_dpp v192, v192, v192 row_bcast:15 row_mask:0xa bank_mask:0xf
	s_nop 1
	v_add_f32_dpp v192, v192, v192 row_bcast:31 row_mask:0xc bank_mask:0xf
	s_nop 1
	v_readlane_b32 s42, v192, 63
	s_nop 3
	v_fma_f32 v198, s42, v202, v203
	v_rsq_f32_e32 v198, v198
	s_nop 0
	v_pk_mul_f32 v[160:161], v[160:161], v[198:199] op_sel_hi:[1,0]
	v_pk_mul_f32 v[162:163], v[162:163], v[198:199] op_sel_hi:[1,0]
	v_pk_mul_f32 v[164:165], v[164:165], v[198:199] op_sel_hi:[1,0]
	v_pk_mul_f32 v[166:167], v[166:167], v[198:199] op_sel_hi:[1,0]
	v_pk_mul_f32 v[168:169], v[168:169], v[198:199] op_sel_hi:[1,0]
	v_pk_mul_f32 v[170:171], v[170:171], v[198:199] op_sel_hi:[1,0]
	v_pk_mul_f32 v[172:173], v[172:173], v[198:199] op_sel_hi:[1,0]
	v_pk_mul_f32 v[174:175], v[174:175], v[198:199] op_sel_hi:[1,0]
	v_pk_fma_f32 v[160:161], v[160:161], v[0:1], v[16:17]
	v_pk_fma_f32 v[162:163], v[162:163], v[2:3], v[18:19]
	v_pk_fma_f32 v[164:165], v[164:165], v[4:5], v[20:21]
	v_pk_fma_f32 v[166:167], v[166:167], v[6:7], v[22:23]
	v_pk_fma_f32 v[168:169], v[168:169], v[8:9], v[24:25]
	v_pk_fma_f32 v[170:171], v[170:171], v[10:11], v[26:27]
	v_pk_fma_f32 v[172:173], v[172:173], v[12:13], v[28:29]
	v_pk_fma_f32 v[174:175], v[174:175], v[14:15], v[30:31]
	global_store_dwordx4 v200, v[160:163], s[8:9] offset:0
	global_store_dwordx4 v200, v[164:167], s[8:9] offset:1024
	global_store_dwordx4 v200, v[168:171], s[8:9] offset:2048
	global_store_dwordx4 v200, v[172:175], s[8:9] offset:3072
	s_add_u32 s8, s8, 0x1000
	s_addc_u32 s9, s9, 0
	s_add_u32 s12, s12, 0x800
	s_addc_u32 s13, s13, 0
	global_load_dwordx4 v[64:67], v200, s[14:15] offset:0
	global_load_dwordx4 v[68:71], v200, s[14:15] offset:1024
	global_load_dwordx4 v[72:75], v200, s[14:15] offset:2048
	global_load_dwordx4 v[76:79], v200, s[14:15] offset:3072
	global_load_dwordx2 v[128:129], v201, s[6:7] offset:0
	global_load_dwordx2 v[130:131], v201, s[6:7] offset:512
	global_load_dwordx2 v[132:133], v201, s[6:7] offset:1024
	global_load_dwordx2 v[134:135], v201, s[6:7] offset:1536
	s_add_u32 s14, s14, 0x1000
	s_addc_u32 s15, s15, 0
	s_add_u32 s6, s6, 0x800
	s_addc_u32 s7, s7, 0
	s_waitcnt vmcnt(36)
	v_lshlrev_b32_e32 v160, 16, v136
	v_and_b32_e32 v161, 0xffff0000, v136
	v_lshlrev_b32_e32 v162, 16, v137
	v_and_b32_e32 v163, 0xffff0000, v137
	v_lshlrev_b32_e32 v164, 16, v138
	v_and_b32_e32 v165, 0xffff0000, v138
	v_lshlrev_b32_e32 v166, 16, v139
	v_and_b32_e32 v167, 0xffff0000, v139
	v_lshlrev_b32_e32 v168, 16, v140
	v_and_b32_e32 v169, 0xffff0000, v140
	v_lshlrev_b32_e32 v170, 16, v141
	v_and_b32_e32 v171, 0xffff0000, v141
	v_lshlrev_b32_e32 v172, 16, v142
	v_and_b32_e32 v173, 0xffff0000, v142
	v_lshlrev_b32_e32 v174, 16, v143
	v_and_b32_e32 v175, 0xffff0000, v143
	v_pk_fma_f32 v[160:161], v[80:81], s[44:45], v[160:161]
	v_pk_fma_f32 v[162:163], v[82:83], s[44:45], v[162:163]
	v_pk_fma_f32 v[164:165], v[84:85], s[44:45], v[164:165]
	v_pk_fma_f32 v[166:167], v[86:87], s[44:45], v[166:167]
	v_pk_fma_f32 v[168:169], v[88:89], s[44:45], v[168:169]
	v_pk_fma_f32 v[170:171], v[90:91], s[44:45], v[170:171]
	v_pk_fma_f32 v[172:173], v[92:93], s[44:45], v[172:173]
	v_pk_fma_f32 v[174:175], v[94:95], s[44:45], v[174:175]
	v_pk_add_f32 v[176:177], v[160:161], v[162:163]
	v_pk_add_f32 v[176:177], v[176:177], v[164:165]
	v_pk_add_f32 v[176:177], v[176:177], v[166:167]
	v_pk_add_f32 v[176:177], v[176:177], v[168:169]
	v_pk_add_f32 v[176:177], v[176:177], v[170:171]
	v_pk_add_f32 v[176:177], v[176:177], v[172:173]
	v_pk_add_f32 v[176:177], v[176:177], v[174:175]
	v_add_f32_e32 v194, v176, v177
	s_nop 1
	v_add_f32_dpp v192, v194, v194 quad_perm:[1,0,3,2] row_mask:0xf bank_mask:0xf
	s_nop 1
	v_add_f32_dpp v192, v192, v192 quad_perm:[2,3,0,1] row_mask:0xf bank_mask:0xf
	s_nop 1
	v_add_f32_dpp v192, v192, v192 row_half_mirror row_mask:0xf bank_mask:0xf
	s_nop 1
	v_add_f32_dpp v192, v192, v192 row_mirror row_mask:0xf bank_mask:0xf
	s_nop 1
	v_add_f32_dpp v192, v192, v192 row_bcast:15 row_mask:0xa bank_mask:0xf
	s_nop 1
	v_add_f32_dpp v192, v192, v192 row_bcast:31 row_mask:0xc bank_mask:0xf
	s_nop 1
	v_readlane_b32 s42, v192, 63
	s_nop 3
	s_mov_b32 s43, s42
	v_pk_fma_f32 v[160:161], s[42:43], v[196:197], v[160:161]
	v_pk_fma_f32 v[162:163], s[42:43], v[196:197], v[162:163]
	v_pk_fma_f32 v[164:165], s[42:43], v[196:197], v[164:165]
	v_pk_fma_f32 v[166:167], s[42:43], v[196:197], v[166:167]
	v_pk_fma_f32 v[168:169], s[42:43], v[196:197], v[168:169]
	v_pk_fma_f32 v[170:171], s[42:43], v[196:197], v[170:171]
	v_pk_fma_f32 v[172:173], s[42:43], v[196:197], v[172:173]
	v_pk_fma_f32 v[174:175], s[42:43], v[196:197], v[174:175]
	v_pk_mul_f32 v[176:177], v[160:161], v[160:161]
	v_pk_fma_f32 v[176:177], v[162:163], v[162:163], v[176:177]
	v_pk_fma_f32 v[176:177], v[164:165], v[164:165], v[176:177]
	v_pk_fma_f32 v[176:177], v[166:167], v[166:167], v[176:177]
	v_pk_fma_f32 v[176:177], v[168:169], v[168:169], v[176:177]
	v_pk_fma_f32 v[176:177], v[170:171], v[170:171], v[176:177]
	v_pk_fma_f32 v[176:177], v[172:173], v[172:173], v[176:177]
	v_pk_fma_f32 v[176:177], v[174:175], v[174:175], v[176:177]
	v_add_f32_e32 v194, v176, v177
	s_nop 1
	v_add_f32_dpp v192, v194, v194 quad_perm:[1,0,3,2] row_mask:0xf bank_mask:0xf
	s_nop 1
	v_add_f32_dpp v192, v192, v192 quad_perm:[2,3,0,1] row_mask:0xf bank_mask:0xf
	s_nop 1
	v_add_f32_dpp v192, v192, v192 row_half_mirror row_mask:0xf bank_mask:0xf
	s_nop 1
	v_add_f32_dpp v192, v192, v192 row_mirror row_mask:0xf bank_mask:0xf
	s_nop 1
	v_add_f32_dpp v192, v192, v192 row_bcast:15 row_mask:0xa bank_mask:0xf
	s_nop 1
	v_add_f32_dpp v192, v192, v192 row_bcast:31 row_mask:0xc bank_mask:0xf
	s_nop 1
	v_readlane_b32 s42, v192, 63
	s_nop 3
	v_fma_f32 v198, s42, v202, v203
	v_rsq_f32_e32 v198, v198
	s_nop 0
	v_pk_mul_f32 v[160:161], v[160:161], v[198:199] op_sel_hi:[1,0]
	v_pk_mul_f32 v[162:163], v[162:163], v[198:199] op_sel_hi:[1,0]
	v_pk_mul_f32 v[164:165], v[164:165], v[198:199] op_sel_hi:[1,0]
	v_pk_mul_f32 v[166:167], v[166:167], v[198:199] op_sel_hi:[1,0]
	v_pk_mul_f32 v[168:169], v[168:169], v[198:199] op_sel_hi:[1,0]
	v_pk_mul_f32 v[170:171], v[170:171], v[198:199] op_sel_hi:[1,0]
	v_pk_mul_f32 v[172:173], v[172:173], v[198:199] op_sel_hi:[1,0]
	v_pk_mul_f32 v[174:175], v[174:175], v[198:199] op_sel_hi:[1,0]
	v_pk_fma_f32 v[160:161], v[160:161], v[0:1], v[16:17]
	v_pk_fma_f32 v[162:163], v[162:163], v[2:3], v[18:19]
	v_pk_fma_f32 v[164:165], v[164:165], v[4:5], v[20:21]
	v_pk_fma_f32 v[166:167], v[166:167], v[6:7], v[22:23]
	v_pk_fma_f32 v[168:169], v[168:169], v[8:9], v[24:25]
	v_pk_fma_f32 v[170:171], v[170:171], v[10:11], v[26:27]
	v_pk_fma_f32 v[172:173], v[172:173], v[12:13], v[28:29]
	v_pk_fma_f32 v[174:175], v[174:175], v[14:15], v[30:31]
	global_store_dwordx4 v200, v[160:163], s[8:9] offset:0
	global_store_dwordx4 v200, v[164:167], s[8:9] offset:1024
	global_store_dwordx4 v200, v[168:171], s[8:9] offset:2048
	global_store_dwordx4 v200, v[172:175], s[8:9] offset:3072
	s_add_u32 s8, s8, 0x1000
	s_addc_u32 s9, s9, 0
	s_add_u32 s12, s12, 0x800
	s_addc_u32 s13, s13, 0
	global_load_dwordx4 v[80:83], v200, s[14:15] offset:0
	global_load_dwordx4 v[84:87], v200, s[14:15] offset:1024
	global_load_dwordx4 v[88:91], v200, s[14:15] offset:2048
	global_load_dwordx4 v[92:95], v200, s[14:15] offset:3072
	global_load_dwordx2 v[136:137], v201, s[6:7] offset:0
	global_load_dwordx2 v[138:139], v201, s[6:7] offset:512
	global_load_dwordx2 v[140:141], v201, s[6:7] offset:1024
	global_load_dwordx2 v[142:143], v201, s[6:7] offset:1536
	s_add_u32 s14, s14, 0x1000
	s_addc_u32 s15, s15, 0
	s_add_u32 s6, s6, 0x800
	s_addc_u32 s7, s7, 0
	s_waitcnt vmcnt(36)
	v_lshlrev_b32_e32 v160, 16, v144
	v_and_b32_e32 v161, 0xffff0000, v144
	v_lshlrev_b32_e32 v162, 16, v145
	v_and_b32_e32 v163, 0xffff0000, v145
	v_lshlrev_b32_e32 v164, 16, v146
	v_and_b32_e32 v165, 0xffff0000, v146
	v_lshlrev_b32_e32 v166, 16, v147
	v_and_b32_e32 v167, 0xffff0000, v147
	v_lshlrev_b32_e32 v168, 16, v148
	v_and_b32_e32 v169, 0xffff0000, v148
	v_lshlrev_b32_e32 v170, 16, v149
	v_and_b32_e32 v171, 0xffff0000, v149
	v_lshlrev_b32_e32 v172, 16, v150
	v_and_b32_e32 v173, 0xffff0000, v150
	v_lshlrev_b32_e32 v174, 16, v151
	v_and_b32_e32 v175, 0xffff0000, v151
	v_pk_fma_f32 v[160:161], v[96:97], s[44:45], v[160:161]
	v_pk_fma_f32 v[162:163], v[98:99], s[44:45], v[162:163]
	v_pk_fma_f32 v[164:165], v[100:101], s[44:45], v[164:165]
	v_pk_fma_f32 v[166:167], v[102:103], s[44:45], v[166:167]
	v_pk_fma_f32 v[168:169], v[104:105], s[44:45], v[168:169]
	v_pk_fma_f32 v[170:171], v[106:107], s[44:45], v[170:171]
	v_pk_fma_f32 v[172:173], v[108:109], s[44:45], v[172:173]
	v_pk_fma_f32 v[174:175], v[110:111], s[44:45], v[174:175]
	v_pk_add_f32 v[176:177], v[160:161], v[162:163]
	v_pk_add_f32 v[176:177], v[176:177], v[164:165]
	v_pk_add_f32 v[176:177], v[176:177], v[166:167]
	v_pk_add_f32 v[176:177], v[176:177], v[168:169]
	v_pk_add_f32 v[176:177], v[176:177], v[170:171]
	v_pk_add_f32 v[176:177], v[176:177], v[172:173]
	v_pk_add_f32 v[176:177], v[176:177], v[174:175]
	v_add_f32_e32 v194, v176, v177
	s_nop 1
	v_add_f32_dpp v192, v194, v194 quad_perm:[1,0,3,2] row_mask:0xf bank_mask:0xf
	s_nop 1
	v_add_f32_dpp v192, v192, v192 quad_perm:[2,3,0,1] row_mask:0xf bank_mask:0xf
	s_nop 1
	v_add_f32_dpp v192, v192, v192 row_half_mirror row_mask:0xf bank_mask:0xf
	s_nop 1
	v_add_f32_dpp v192, v192, v192 row_mirror row_mask:0xf bank_mask:0xf
	s_nop 1
	v_add_f32_dpp v192, v192, v192 row_bcast:15 row_mask:0xa bank_mask:0xf
	s_nop 1
	v_add_f32_dpp v192, v192, v192 row_bcast:31 row_mask:0xc bank_mask:0xf
	s_nop 1
	v_readlane_b32 s42, v192, 63
	s_nop 3
	s_mov_b32 s43, s42
	v_pk_fma_f32 v[160:161], s[42:43], v[196:197], v[160:161]
	v_pk_fma_f32 v[162:163], s[42:43], v[196:197], v[162:163]
	v_pk_fma_f32 v[164:165], s[42:43], v[196:197], v[164:165]
	v_pk_fma_f32 v[166:167], s[42:43], v[196:197], v[166:167]
	v_pk_fma_f32 v[168:169], s[42:43], v[196:197], v[168:169]
	v_pk_fma_f32 v[170:171], s[42:43], v[196:197], v[170:171]
	v_pk_fma_f32 v[172:173], s[42:43], v[196:197], v[172:173]
	v_pk_fma_f32 v[174:175], s[42:43], v[196:197], v[174:175]
	v_pk_mul_f32 v[176:177], v[160:161], v[160:161]
	v_pk_fma_f32 v[176:177], v[162:163], v[162:163], v[176:177]
	v_pk_fma_f32 v[176:177], v[164:165], v[164:165], v[176:177]
	v_pk_fma_f32 v[176:177], v[166:167], v[166:167], v[176:177]
	v_pk_fma_f32 v[176:177], v[168:169], v[168:169], v[176:177]
	v_pk_fma_f32 v[176:177], v[170:171], v[170:171], v[176:177]
	v_pk_fma_f32 v[176:177], v[172:173], v[172:173], v[176:177]
	v_pk_fma_f32 v[176:177], v[174:175], v[174:175], v[176:177]
	v_add_f32_e32 v194, v176, v177
	s_nop 1
	v_add_f32_dpp v192, v194, v194 quad_perm:[1,0,3,2] row_mask:0xf bank_mask:0xf
	s_nop 1
	v_add_f32_dpp v192, v192, v192 quad_perm:[2,3,0,1] row_mask:0xf bank_mask:0xf
	s_nop 1
	v_add_f32_dpp v192, v192, v192 row_half_mirror row_mask:0xf bank_mask:0xf
	s_nop 1
	v_add_f32_dpp v192, v192, v192 row_mirror row_mask:0xf bank_mask:0xf
	s_nop 1
	v_add_f32_dpp v192, v192, v192 row_bcast:15 row_mask:0xa bank_mask:0xf
	s_nop 1
	v_add_f32_dpp v192, v192, v192 row_bcast:31 row_mask:0xc bank_mask:0xf
	s_nop 1
	v_readlane_b32 s42, v192, 63
	s_nop 3
	v_fma_f32 v198, s42, v202, v203
	v_rsq_f32_e32 v198, v198
	s_nop 0
	v_pk_mul_f32 v[160:161], v[160:161], v[198:199] op_sel_hi:[1,0]
	v_pk_mul_f32 v[162:163], v[162:163], v[198:199] op_sel_hi:[1,0]
	v_pk_mul_f32 v[164:165], v[164:165], v[198:199] op_sel_hi:[1,0]
	v_pk_mul_f32 v[166:167], v[166:167], v[198:199] op_sel_hi:[1,0]
	v_pk_mul_f32 v[168:169], v[168:169], v[198:199] op_sel_hi:[1,0]
	v_pk_mul_f32 v[170:171], v[170:171], v[198:199] op_sel_hi:[1,0]
	v_pk_mul_f32 v[172:173], v[172:173], v[198:199] op_sel_hi:[1,0]
	v_pk_mul_f32 v[174:175], v[174:175], v[198:199] op_sel_hi:[1,0]
	v_pk_fma_f32 v[160:161], v[160:161], v[0:1], v[16:17]
	v_pk_fma_f32 v[162:163], v[162:163], v[2:3], v[18:19]
	v_pk_fma_f32 v[164:165], v[164:165], v[4:5], v[20:21]
	v_pk_fma_f32 v[166:167], v[166:167], v[6:7], v[22:23]
	v_pk_fma_f32 v[168:169], v[168:169], v[8:9], v[24:25]
	v_pk_fma_f32 v[170:171], v[170:171], v[10:11], v[26:27]
	v_pk_fma_f32 v[172:173], v[172:173], v[12:13], v[28:29]
	v_pk_fma_f32 v[174:175], v[174:175], v[14:15], v[30:31]
	global_store_dwordx4 v200, v[160:163], s[8:9] offset:0
	global_store_dwordx4 v200, v[164:167], s[8:9] offset:1024
	global_store_dwordx4 v200, v[168:171], s[8:9] offset:2048
	global_store_dwordx4 v200, v[172:175], s[8:9] offset:3072
	s_add_u32 s8, s8, 0x1000
	s_addc_u32 s9, s9, 0
	s_add_u32 s12, s12, 0x800
	s_addc_u32 s13, s13, 0
	global_load_dwordx4 v[96:99], v200, s[14:15] offset:0
	global_load_dwordx4 v[100:103], v200, s[14:15] offset:1024
	global_load_dwordx4 v[104:107], v200, s[14:15] offset:2048
	global_load_dwordx4 v[108:111], v200, s[14:15] offset:3072
	global_load_dwordx2 v[144:145], v201, s[6:7] offset:0
	global_load_dwordx2 v[146:147], v201, s[6:7] offset:512
	global_load_dwordx2 v[148:149], v201, s[6:7] offset:1024
	global_load_dwordx2 v[150:151], v201, s[6:7] offset:1536
	s_add_u32 s14, s14, 0x1000
	s_addc_u32 s15, s15, 0
	s_add_u32 s6, s6, 0x800
	s_addc_u32 s7, s7, 0
	s_waitcnt vmcnt(36)
	v_lshlrev_b32_e32 v160, 16, v152
	v_and_b32_e32 v161, 0xffff0000, v152
	v_lshlrev_b32_e32 v162, 16, v153
	v_and_b32_e32 v163, 0xffff0000, v153
	v_lshlrev_b32_e32 v164, 16, v154
	v_and_b32_e32 v165, 0xffff0000, v154
	v_lshlrev_b32_e32 v166, 16, v155
	v_and_b32_e32 v167, 0xffff0000, v155
	v_lshlrev_b32_e32 v168, 16, v156
	v_and_b32_e32 v169, 0xffff0000, v156
	v_lshlrev_b32_e32 v170, 16, v157
	v_and_b32_e32 v171, 0xffff0000, v157
	v_lshlrev_b32_e32 v172, 16, v158
	v_and_b32_e32 v173, 0xffff0000, v158
	v_lshlrev_b32_e32 v174, 16, v159
	v_and_b32_e32 v175, 0xffff0000, v159
	v_pk_fma_f32 v[160:161], v[112:113], s[44:45], v[160:161]
	v_pk_fma_f32 v[162:163], v[114:115], s[44:45], v[162:163]
	v_pk_fma_f32 v[164:165], v[116:117], s[44:45], v[164:165]
	v_pk_fma_f32 v[166:167], v[118:119], s[44:45], v[166:167]
	v_pk_fma_f32 v[168:169], v[120:121], s[44:45], v[168:169]
	v_pk_fma_f32 v[170:171], v[122:123], s[44:45], v[170:171]
	v_pk_fma_f32 v[172:173], v[124:125], s[44:45], v[172:173]
	v_pk_fma_f32 v[174:175], v[126:127], s[44:45], v[174:175]
	v_pk_add_f32 v[176:177], v[160:161], v[162:163]
	v_pk_add_f32 v[176:177], v[176:177], v[164:165]
	v_pk_add_f32 v[176:177], v[176:177], v[166:167]
	v_pk_add_f32 v[176:177], v[176:177], v[168:169]
	v_pk_add_f32 v[176:177], v[176:177], v[170:171]
	v_pk_add_f32 v[176:177], v[176:177], v[172:173]
	v_pk_add_f32 v[176:177], v[176:177], v[174:175]
	v_add_f32_e32 v194, v176, v177
	s_nop 1
	v_add_f32_dpp v192, v194, v194 quad_perm:[1,0,3,2] row_mask:0xf bank_mask:0xf
	s_nop 1
	v_add_f32_dpp v192, v192, v192 quad_perm:[2,3,0,1] row_mask:0xf bank_mask:0xf
	s_nop 1
	v_add_f32_dpp v192, v192, v192 row_half_mirror row_mask:0xf bank_mask:0xf
	s_nop 1
	v_add_f32_dpp v192, v192, v192 row_mirror row_mask:0xf bank_mask:0xf
	s_nop 1
	v_add_f32_dpp v192, v192, v192 row_bcast:15 row_mask:0xa bank_mask:0xf
	s_nop 1
	v_add_f32_dpp v192, v192, v192 row_bcast:31 row_mask:0xc bank_mask:0xf
	s_nop 1
	v_readlane_b32 s42, v192, 63
	s_nop 3
	s_mov_b32 s43, s42
	v_pk_fma_f32 v[160:161], s[42:43], v[196:197], v[160:161]
	v_pk_fma_f32 v[162:163], s[42:43], v[196:197], v[162:163]
	v_pk_fma_f32 v[164:165], s[42:43], v[196:197], v[164:165]
	v_pk_fma_f32 v[166:167], s[42:43], v[196:197], v[166:167]
	v_pk_fma_f32 v[168:169], s[42:43], v[196:197], v[168:169]
	v_pk_fma_f32 v[170:171], s[42:43], v[196:197], v[170:171]
	v_pk_fma_f32 v[172:173], s[42:43], v[196:197], v[172:173]
	v_pk_fma_f32 v[174:175], s[42:43], v[196:197], v[174:175]
	v_pk_mul_f32 v[176:177], v[160:161], v[160:161]
	v_pk_fma_f32 v[176:177], v[162:163], v[162:163], v[176:177]
	v_pk_fma_f32 v[176:177], v[164:165], v[164:165], v[176:177]
	v_pk_fma_f32 v[176:177], v[166:167], v[166:167], v[176:177]
	v_pk_fma_f32 v[176:177], v[168:169], v[168:169], v[176:177]
	v_pk_fma_f32 v[176:177], v[170:171], v[170:171], v[176:177]
	v_pk_fma_f32 v[176:177], v[172:173], v[172:173], v[176:177]
	v_pk_fma_f32 v[176:177], v[174:175], v[174:175], v[176:177]
	v_add_f32_e32 v194, v176, v177
	s_nop 1
	v_add_f32_dpp v192, v194, v194 quad_perm:[1,0,3,2] row_mask:0xf bank_mask:0xf
	s_nop 1
	v_add_f32_dpp v192, v192, v192 quad_perm:[2,3,0,1] row_mask:0xf bank_mask:0xf
	s_nop 1
	v_add_f32_dpp v192, v192, v192 row_half_mirror row_mask:0xf bank_mask:0xf
	s_nop 1
	v_add_f32_dpp v192, v192, v192 row_mirror row_mask:0xf bank_mask:0xf
	s_nop 1
	v_add_f32_dpp v192, v192, v192 row_bcast:15 row_mask:0xa bank_mask:0xf
	s_nop 1
	v_add_f32_dpp v192, v192, v192 row_bcast:31 row_mask:0xc bank_mask:0xf
	s_nop 1
	v_readlane_b32 s42, v192, 63
	s_nop 3
	v_fma_f32 v198, s42, v202, v203
	v_rsq_f32_e32 v198, v198
	s_nop 0
	v_pk_mul_f32 v[160:161], v[160:161], v[198:199] op_sel_hi:[1,0]
	v_pk_mul_f32 v[162:163], v[162:163], v[198:199] op_sel_hi:[1,0]
	v_pk_mul_f32 v[164:165], v[164:165], v[198:199] op_sel_hi:[1,0]
	v_pk_mul_f32 v[166:167], v[166:167], v[198:199] op_sel_hi:[1,0]
	v_pk_mul_f32 v[168:169], v[168:169], v[198:199] op_sel_hi:[1,0]
	v_pk_mul_f32 v[170:171], v[170:171], v[198:199] op_sel_hi:[1,0]
	v_pk_mul_f32 v[172:173], v[172:173], v[198:199] op_sel_hi:[1,0]
	v_pk_mul_f32 v[174:175], v[174:175], v[198:199] op_sel_hi:[1,0]
	v_pk_fma_f32 v[160:161], v[160:161], v[0:1], v[16:17]
	v_pk_fma_f32 v[162:163], v[162:163], v[2:3], v[18:19]
	v_pk_fma_f32 v[164:165], v[164:165], v[4:5], v[20:21]
	v_pk_fma_f32 v[166:167], v[166:167], v[6:7], v[22:23]
	v_pk_fma_f32 v[168:169], v[168:169], v[8:9], v[24:25]
	v_pk_fma_f32 v[170:171], v[170:171], v[10:11], v[26:27]
	v_pk_fma_f32 v[172:173], v[172:173], v[12:13], v[28:29]
	v_pk_fma_f32 v[174:175], v[174:175], v[14:15], v[30:31]
	global_store_dwordx4 v200, v[160:163], s[8:9] offset:0
	global_store_dwordx4 v200, v[164:167], s[8:9] offset:1024
	global_store_dwordx4 v200, v[168:171], s[8:9] offset:2048
	global_store_dwordx4 v200, v[172:175], s[8:9] offset:3072
	s_add_u32 s8, s8, 0x1000
	s_addc_u32 s9, s9, 0
	s_add_u32 s12, s12, 0x800
	s_addc_u32 s13, s13, 0
	global_load_dwordx4 v[112:115], v200, s[14:15] offset:0
	global_load_dwordx4 v[116:119], v200, s[14:15] offset:1024
	global_load_dwordx4 v[120:123], v200, s[14:15] offset:2048
	global_load_dwordx4 v[124:127], v200, s[14:15] offset:3072
	global_load_dwordx2 v[152:153], v201, s[6:7] offset:0
	global_load_dwordx2 v[154:155], v201, s[6:7] offset:512
	global_load_dwordx2 v[156:157], v201, s[6:7] offset:1024
	global_load_dwordx2 v[158:159], v201, s[6:7] offset:1536
	s_add_u32 s14, s14, 0x1000
	s_addc_u32 s15, s15, 0
	s_add_u32 s6, s6, 0x800
	s_addc_u32 s7, s7, 0
	s_waitcnt vmcnt(36)
	v_lshlrev_b32_e32 v160, 16, v128
	v_and_b32_e32 v161, 0xffff0000, v128
	v_lshlrev_b32_e32 v162, 16, v129
	v_and_b32_e32 v163, 0xffff0000, v129
	v_lshlrev_b32_e32 v164, 16, v130
	v_and_b32_e32 v165, 0xffff0000, v130
	v_lshlrev_b32_e32 v166, 16, v131
	v_and_b32_e32 v167, 0xffff0000, v131
	v_lshlrev_b32_e32 v168, 16, v132
	v_and_b32_e32 v169, 0xffff0000, v132
	v_lshlrev_b32_e32 v170, 16, v133
	v_and_b32_e32 v171, 0xffff0000, v133
	v_lshlrev_b32_e32 v172, 16, v134
	v_and_b32_e32 v173, 0xffff0000, v134
	v_lshlrev_b32_e32 v174, 16, v135
	v_and_b32_e32 v175, 0xffff0000, v135
	v_pk_fma_f32 v[160:161], v[64:65], s[44:45], v[160:161]
	v_pk_fma_f32 v[162:163], v[66:67], s[44:45], v[162:163]
	v_pk_fma_f32 v[164:165], v[68:69], s[44:45], v[164:165]
	v_pk_fma_f32 v[166:167], v[70:71], s[44:45], v[166:167]
	v_pk_fma_f32 v[168:169], v[72:73], s[44:45], v[168:169]
	v_pk_fma_f32 v[170:171], v[74:75], s[44:45], v[170:171]
	v_pk_fma_f32 v[172:173], v[76:77], s[44:45], v[172:173]
	v_pk_fma_f32 v[174:175], v[78:79], s[44:45], v[174:175]
	v_pk_add_f32 v[176:177], v[160:161], v[162:163]
	v_pk_add_f32 v[176:177], v[176:177], v[164:165]
	v_pk_add_f32 v[176:177], v[176:177], v[166:167]
	v_pk_add_f32 v[176:177], v[176:177], v[168:169]
	v_pk_add_f32 v[176:177], v[176:177], v[170:171]
	v_pk_add_f32 v[176:177], v[176:177], v[172:173]
	v_pk_add_f32 v[176:177], v[176:177], v[174:175]
	v_add_f32_e32 v194, v176, v177
	s_nop 1
	v_add_f32_dpp v192, v194, v194 quad_perm:[1,0,3,2] row_mask:0xf bank_mask:0xf
	s_nop 1
	v_add_f32_dpp v192, v192, v192 quad_perm:[2,3,0,1] row_mask:0xf bank_mask:0xf
	s_nop 1
	v_add_f32_dpp v192, v192, v192 row_half_mirror row_mask:0xf bank_mask:0xf
	s_nop 1
	v_add_f32_dpp v192, v192, v192 row_mirror row_mask:0xf bank_mask:0xf
	s_nop 1
	v_add_f32_dpp v192, v192, v192 row_bcast:15 row_mask:0xa bank_mask:0xf
	s_nop 1
	v_add_f32_dpp v192, v192, v192 row_bcast:31 row_mask:0xc bank_mask:0xf
	s_nop 1
	v_readlane_b32 s42, v192, 63
	s_nop 3
	s_mov_b32 s43, s42
	v_pk_fma_f32 v[160:161], s[42:43], v[196:197], v[160:161]
	v_pk_fma_f32 v[162:163], s[42:43], v[196:197], v[162:163]
	v_pk_fma_f32 v[164:165], s[42:43], v[196:197], v[164:165]
	v_pk_fma_f32 v[166:167], s[42:43], v[196:197], v[166:167]
	v_pk_fma_f32 v[168:169], s[42:43], v[196:197], v[168:169]
	v_pk_fma_f32 v[170:171], s[42:43], v[196:197], v[170:171]
	v_pk_fma_f32 v[172:173], s[42:43], v[196:197], v[172:173]
	v_pk_fma_f32 v[174:175], s[42:43], v[196:197], v[174:175]
	v_pk_mul_f32 v[176:177], v[160:161], v[160:161]
	v_pk_fma_f32 v[176:177], v[162:163], v[162:163], v[176:177]
	v_pk_fma_f32 v[176:177], v[164:165], v[164:165], v[176:177]
	v_pk_fma_f32 v[176:177], v[166:167], v[166:167], v[176:177]
	v_pk_fma_f32 v[176:177], v[168:169], v[168:169], v[176:177]
	v_pk_fma_f32 v[176:177], v[170:171], v[170:171], v[176:177]
	v_pk_fma_f32 v[176:177], v[172:173], v[172:173], v[176:177]
	v_pk_fma_f32 v[176:177], v[174:175], v[174:175], v[176:177]
	v_add_f32_e32 v194, v176, v177
	s_nop 1
	v_add_f32_dpp v192, v194, v194 quad_perm:[1,0,3,2] row_mask:0xf bank_mask:0xf
	s_nop 1
	v_add_f32_dpp v192, v192, v192 quad_perm:[2,3,0,1] row_mask:0xf bank_mask:0xf
	s_nop 1
	v_add_f32_dpp v192, v192, v192 row_half_mirror row_mask:0xf bank_mask:0xf
	s_nop 1
	v_add_f32_dpp v192, v192, v192 row_mirror row_mask:0xf bank_mask:0xf
	s_nop 1
	v_add_f32_dpp v192, v192, v192 row_bcast:15 row_mask:0xa bank_mask:0xf
	s_nop 1
	v_add_f32_dpp v192, v192, v192 row_bcast:31 row_mask:0xc bank_mask:0xf
	s_nop 1
	v_readlane_b32 s42, v192, 63
	s_nop 3
	v_fma_f32 v198, s42, v202, v203
	v_rsq_f32_e32 v198, v198
	s_nop 0
	v_pk_mul_f32 v[160:161], v[160:161], v[198:199] op_sel_hi:[1,0]
	v_pk_mul_f32 v[162:163], v[162:163], v[198:199] op_sel_hi:[1,0]
	v_pk_mul_f32 v[164:165], v[164:165], v[198:199] op_sel_hi:[1,0]
	v_pk_mul_f32 v[166:167], v[166:167], v[198:199] op_sel_hi:[1,0]
	v_pk_mul_f32 v[168:169], v[168:169], v[198:199] op_sel_hi:[1,0]
	v_pk_mul_f32 v[170:171], v[170:171], v[198:199] op_sel_hi:[1,0]
	v_pk_mul_f32 v[172:173], v[172:173], v[198:199] op_sel_hi:[1,0]
	v_pk_mul_f32 v[174:175], v[174:175], v[198:199] op_sel_hi:[1,0]
	v_pk_fma_f32 v[160:161], v[160:161], v[0:1], v[16:17]
	v_pk_fma_f32 v[162:163], v[162:163], v[2:3], v[18:19]
	v_pk_fma_f32 v[164:165], v[164:165], v[4:5], v[20:21]
	v_pk_fma_f32 v[166:167], v[166:167], v[6:7], v[22:23]
	v_pk_fma_f32 v[168:169], v[168:169], v[8:9], v[24:25]
	v_pk_fma_f32 v[170:171], v[170:171], v[10:11], v[26:27]
	v_pk_fma_f32 v[172:173], v[172:173], v[12:13], v[28:29]
	v_pk_fma_f32 v[174:175], v[174:175], v[14:15], v[30:31]
	global_store_dwordx4 v200, v[160:163], s[8:9] offset:0
	global_store_dwordx4 v200, v[164:167], s[8:9] offset:1024
	global_store_dwordx4 v200, v[168:171], s[8:9] offset:2048
	global_store_dwordx4 v200, v[172:175], s[8:9] offset:3072
	s_add_u32 s8, s8, 0x1000
	s_addc_u32 s9, s9, 0
	s_add_u32 s12, s12, 0x800
	s_addc_u32 s13, s13, 0
	global_load_dwordx4 v[64:67], v200, s[14:15] offset:0
	global_load_dwordx4 v[68:71], v200, s[14:15] offset:1024
	global_load_dwordx4 v[72:75], v200, s[14:15] offset:2048
	global_load_dwordx4 v[76:79], v200, s[14:15] offset:3072
	global_load_dwordx2 v[128:129], v201, s[6:7] offset:0
	global_load_dwordx2 v[130:131], v201, s[6:7] offset:512
	global_load_dwordx2 v[132:133], v201, s[6:7] offset:1024
	global_load_dwordx2 v[134:135], v201, s[6:7] offset:1536
	s_add_u32 s14, s14, 0x1000
	s_addc_u32 s15, s15, 0
	s_add_u32 s6, s6, 0x800
	s_addc_u32 s7, s7, 0
	s_waitcnt vmcnt(36)
	v_lshlrev_b32_e32 v160, 16, v136
	v_and_b32_e32 v161, 0xffff0000, v136
	v_lshlrev_b32_e32 v162, 16, v137
	v_and_b32_e32 v163, 0xffff0000, v137
	v_lshlrev_b32_e32 v164, 16, v138
	v_and_b32_e32 v165, 0xffff0000, v138
	v_lshlrev_b32_e32 v166, 16, v139
	v_and_b32_e32 v167, 0xffff0000, v139
	v_lshlrev_b32_e32 v168, 16, v140
	v_and_b32_e32 v169, 0xffff0000, v140
	v_lshlrev_b32_e32 v170, 16, v141
	v_and_b32_e32 v171, 0xffff0000, v141
	v_lshlrev_b32_e32 v172, 16, v142
	v_and_b32_e32 v173, 0xffff0000, v142
	v_lshlrev_b32_e32 v174, 16, v143
	v_and_b32_e32 v175, 0xffff0000, v143
	v_pk_fma_f32 v[160:161], v[80:81], s[44:45], v[160:161]
	v_pk_fma_f32 v[162:163], v[82:83], s[44:45], v[162:163]
	v_pk_fma_f32 v[164:165], v[84:85], s[44:45], v[164:165]
	v_pk_fma_f32 v[166:167], v[86:87], s[44:45], v[166:167]
	v_pk_fma_f32 v[168:169], v[88:89], s[44:45], v[168:169]
	v_pk_fma_f32 v[170:171], v[90:91], s[44:45], v[170:171]
	v_pk_fma_f32 v[172:173], v[92:93], s[44:45], v[172:173]
	v_pk_fma_f32 v[174:175], v[94:95], s[44:45], v[174:175]
	v_pk_add_f32 v[176:177], v[160:161], v[162:163]
	v_pk_add_f32 v[176:177], v[176:177], v[164:165]
	v_pk_add_f32 v[176:177], v[176:177], v[166:167]
	v_pk_add_f32 v[176:177], v[176:177], v[168:169]
	v_pk_add_f32 v[176:177], v[176:177], v[170:171]
	v_pk_add_f32 v[176:177], v[176:177], v[172:173]
	v_pk_add_f32 v[176:177], v[176:177], v[174:175]
	v_add_f32_e32 v194, v176, v177
	s_nop 1
	v_add_f32_dpp v192, v194, v194 quad_perm:[1,0,3,2] row_mask:0xf bank_mask:0xf
	s_nop 1
	v_add_f32_dpp v192, v192, v192 quad_perm:[2,3,0,1] row_mask:0xf bank_mask:0xf
	s_nop 1
	v_add_f32_dpp v192, v192, v192 row_half_mirror row_mask:0xf bank_mask:0xf
	s_nop 1
	v_add_f32_dpp v192, v192, v192 row_mirror row_mask:0xf bank_mask:0xf
	s_nop 1
	v_add_f32_dpp v192, v192, v192 row_bcast:15 row_mask:0xa bank_mask:0xf
	s_nop 1
	v_add_f32_dpp v192, v192, v192 row_bcast:31 row_mask:0xc bank_mask:0xf
	s_nop 1
	v_readlane_b32 s42, v192, 63
	s_nop 3
	s_mov_b32 s43, s42
	v_pk_fma_f32 v[160:161], s[42:43], v[196:197], v[160:161]
	v_pk_fma_f32 v[162:163], s[42:43], v[196:197], v[162:163]
	v_pk_fma_f32 v[164:165], s[42:43], v[196:197], v[164:165]
	v_pk_fma_f32 v[166:167], s[42:43], v[196:197], v[166:167]
	v_pk_fma_f32 v[168:169], s[42:43], v[196:197], v[168:169]
	v_pk_fma_f32 v[170:171], s[42:43], v[196:197], v[170:171]
	v_pk_fma_f32 v[172:173], s[42:43], v[196:197], v[172:173]
	v_pk_fma_f32 v[174:175], s[42:43], v[196:197], v[174:175]
	v_pk_mul_f32 v[176:177], v[160:161], v[160:161]
	v_pk_fma_f32 v[176:177], v[162:163], v[162:163], v[176:177]
	v_pk_fma_f32 v[176:177], v[164:165], v[164:165], v[176:177]
	v_pk_fma_f32 v[176:177], v[166:167], v[166:167], v[176:177]
	v_pk_fma_f32 v[176:177], v[168:169], v[168:169], v[176:177]
	v_pk_fma_f32 v[176:177], v[170:171], v[170:171], v[176:177]
	v_pk_fma_f32 v[176:177], v[172:173], v[172:173], v[176:177]
	v_pk_fma_f32 v[176:177], v[174:175], v[174:175], v[176:177]
	v_add_f32_e32 v194, v176, v177
	s_nop 1
	v_add_f32_dpp v192, v194, v194 quad_perm:[1,0,3,2] row_mask:0xf bank_mask:0xf
	s_nop 1
	v_add_f32_dpp v192, v192, v192 quad_perm:[2,3,0,1] row_mask:0xf bank_mask:0xf
	s_nop 1
	v_add_f32_dpp v192, v192, v192 row_half_mirror row_mask:0xf bank_mask:0xf
	s_nop 1
	v_add_f32_dpp v192, v192, v192 row_mirror row_mask:0xf bank_mask:0xf
	s_nop 1
	v_add_f32_dpp v192, v192, v192 row_bcast:15 row_mask:0xa bank_mask:0xf
	s_nop 1
	v_add_f32_dpp v192, v192, v192 row_bcast:31 row_mask:0xc bank_mask:0xf
	s_nop 1
	v_readlane_b32 s42, v192, 63
	s_nop 3
	v_fma_f32 v198, s42, v202, v203
	v_rsq_f32_e32 v198, v198
	s_nop 0
	v_pk_mul_f32 v[160:161], v[160:161], v[198:199] op_sel_hi:[1,0]
	v_pk_mul_f32 v[162:163], v[162:163], v[198:199] op_sel_hi:[1,0]
	v_pk_mul_f32 v[164:165], v[164:165], v[198:199] op_sel_hi:[1,0]
	v_pk_mul_f32 v[166:167], v[166:167], v[198:199] op_sel_hi:[1,0]
	v_pk_mul_f32 v[168:169], v[168:169], v[198:199] op_sel_hi:[1,0]
	v_pk_mul_f32 v[170:171], v[170:171], v[198:199] op_sel_hi:[1,0]
	v_pk_mul_f32 v[172:173], v[172:173], v[198:199] op_sel_hi:[1,0]
	v_pk_mul_f32 v[174:175], v[174:175], v[198:199] op_sel_hi:[1,0]
	v_pk_fma_f32 v[160:161], v[160:161], v[0:1], v[16:17]
	v_pk_fma_f32 v[162:163], v[162:163], v[2:3], v[18:19]
	v_pk_fma_f32 v[164:165], v[164:165], v[4:5], v[20:21]
	v_pk_fma_f32 v[166:167], v[166:167], v[6:7], v[22:23]
	v_pk_fma_f32 v[168:169], v[168:169], v[8:9], v[24:25]
	v_pk_fma_f32 v[170:171], v[170:171], v[10:11], v[26:27]
	v_pk_fma_f32 v[172:173], v[172:173], v[12:13], v[28:29]
	v_pk_fma_f32 v[174:175], v[174:175], v[14:15], v[30:31]
	global_store_dwordx4 v200, v[160:163], s[8:9] offset:0
	global_store_dwordx4 v200, v[164:167], s[8:9] offset:1024
	global_store_dwordx4 v200, v[168:171], s[8:9] offset:2048
	global_store_dwordx4 v200, v[172:175], s[8:9] offset:3072
	s_add_u32 s8, s8, 0x1000
	s_addc_u32 s9, s9, 0
	s_add_u32 s12, s12, 0x800
	s_addc_u32 s13, s13, 0
	global_load_dwordx4 v[80:83], v200, s[14:15] offset:0
	global_load_dwordx4 v[84:87], v200, s[14:15] offset:1024
	global_load_dwordx4 v[88:91], v200, s[14:15] offset:2048
	global_load_dwordx4 v[92:95], v200, s[14:15] offset:3072
	global_load_dwordx2 v[136:137], v201, s[6:7] offset:0
	global_load_dwordx2 v[138:139], v201, s[6:7] offset:512
	global_load_dwordx2 v[140:141], v201, s[6:7] offset:1024
	global_load_dwordx2 v[142:143], v201, s[6:7] offset:1536
	s_add_u32 s14, s14, 0x1000
	s_addc_u32 s15, s15, 0
	s_add_u32 s6, s6, 0x800
	s_addc_u32 s7, s7, 0
	s_waitcnt vmcnt(36)
	v_lshlrev_b32_e32 v160, 16, v144
	v_and_b32_e32 v161, 0xffff0000, v144
	v_lshlrev_b32_e32 v162, 16, v145
	v_and_b32_e32 v163, 0xffff0000, v145
	v_lshlrev_b32_e32 v164, 16, v146
	v_and_b32_e32 v165, 0xffff0000, v146
	v_lshlrev_b32_e32 v166, 16, v147
	v_and_b32_e32 v167, 0xffff0000, v147
	v_lshlrev_b32_e32 v168, 16, v148
	v_and_b32_e32 v169, 0xffff0000, v148
	v_lshlrev_b32_e32 v170, 16, v149
	v_and_b32_e32 v171, 0xffff0000, v149
	v_lshlrev_b32_e32 v172, 16, v150
	v_and_b32_e32 v173, 0xffff0000, v150
	v_lshlrev_b32_e32 v174, 16, v151
	v_and_b32_e32 v175, 0xffff0000, v151
	v_pk_fma_f32 v[160:161], v[96:97], s[44:45], v[160:161]
	v_pk_fma_f32 v[162:163], v[98:99], s[44:45], v[162:163]
	v_pk_fma_f32 v[164:165], v[100:101], s[44:45], v[164:165]
	v_pk_fma_f32 v[166:167], v[102:103], s[44:45], v[166:167]
	v_pk_fma_f32 v[168:169], v[104:105], s[44:45], v[168:169]
	v_pk_fma_f32 v[170:171], v[106:107], s[44:45], v[170:171]
	v_pk_fma_f32 v[172:173], v[108:109], s[44:45], v[172:173]
	v_pk_fma_f32 v[174:175], v[110:111], s[44:45], v[174:175]
	v_pk_add_f32 v[176:177], v[160:161], v[162:163]
	v_pk_add_f32 v[176:177], v[176:177], v[164:165]
	v_pk_add_f32 v[176:177], v[176:177], v[166:167]
	v_pk_add_f32 v[176:177], v[176:177], v[168:169]
	v_pk_add_f32 v[176:177], v[176:177], v[170:171]
	v_pk_add_f32 v[176:177], v[176:177], v[172:173]
	v_pk_add_f32 v[176:177], v[176:177], v[174:175]
	v_add_f32_e32 v194, v176, v177
	s_nop 1
	v_add_f32_dpp v192, v194, v194 quad_perm:[1,0,3,2] row_mask:0xf bank_mask:0xf
	s_nop 1
	v_add_f32_dpp v192, v192, v192 quad_perm:[2,3,0,1] row_mask:0xf bank_mask:0xf
	s_nop 1
	v_add_f32_dpp v192, v192, v192 row_half_mirror row_mask:0xf bank_mask:0xf
	s_nop 1
	v_add_f32_dpp v192, v192, v192 row_mirror row_mask:0xf bank_mask:0xf
	s_nop 1
	v_add_f32_dpp v192, v192, v192 row_bcast:15 row_mask:0xa bank_mask:0xf
	s_nop 1
	v_add_f32_dpp v192, v192, v192 row_bcast:31 row_mask:0xc bank_mask:0xf
	s_nop 1
	v_readlane_b32 s42, v192, 63
	s_nop 3
	s_mov_b32 s43, s42
	v_pk_fma_f32 v[160:161], s[42:43], v[196:197], v[160:161]
	v_pk_fma_f32 v[162:163], s[42:43], v[196:197], v[162:163]
	v_pk_fma_f32 v[164:165], s[42:43], v[196:197], v[164:165]
	v_pk_fma_f32 v[166:167], s[42:43], v[196:197], v[166:167]
	v_pk_fma_f32 v[168:169], s[42:43], v[196:197], v[168:169]
	v_pk_fma_f32 v[170:171], s[42:43], v[196:197], v[170:171]
	v_pk_fma_f32 v[172:173], s[42:43], v[196:197], v[172:173]
	v_pk_fma_f32 v[174:175], s[42:43], v[196:197], v[174:175]
	v_pk_mul_f32 v[176:177], v[160:161], v[160:161]
	v_pk_fma_f32 v[176:177], v[162:163], v[162:163], v[176:177]
	v_pk_fma_f32 v[176:177], v[164:165], v[164:165], v[176:177]
	v_pk_fma_f32 v[176:177], v[166:167], v[166:167], v[176:177]
	v_pk_fma_f32 v[176:177], v[168:169], v[168:169], v[176:177]
	v_pk_fma_f32 v[176:177], v[170:171], v[170:171], v[176:177]
	v_pk_fma_f32 v[176:177], v[172:173], v[172:173], v[176:177]
	v_pk_fma_f32 v[176:177], v[174:175], v[174:175], v[176:177]
	v_add_f32_e32 v194, v176, v177
	s_nop 1
	v_add_f32_dpp v192, v194, v194 quad_perm:[1,0,3,2] row_mask:0xf bank_mask:0xf
	s_nop 1
	v_add_f32_dpp v192, v192, v192 quad_perm:[2,3,0,1] row_mask:0xf bank_mask:0xf
	s_nop 1
	v_add_f32_dpp v192, v192, v192 row_half_mirror row_mask:0xf bank_mask:0xf
	s_nop 1
	v_add_f32_dpp v192, v192, v192 row_mirror row_mask:0xf bank_mask:0xf
	s_nop 1
	v_add_f32_dpp v192, v192, v192 row_bcast:15 row_mask:0xa bank_mask:0xf
	s_nop 1
	v_add_f32_dpp v192, v192, v192 row_bcast:31 row_mask:0xc bank_mask:0xf
	s_nop 1
	v_readlane_b32 s42, v192, 63
	s_nop 3
	v_fma_f32 v198, s42, v202, v203
	v_rsq_f32_e32 v198, v198
	s_nop 0
	v_pk_mul_f32 v[160:161], v[160:161], v[198:199] op_sel_hi:[1,0]
	v_pk_mul_f32 v[162:163], v[162:163], v[198:199] op_sel_hi:[1,0]
	v_pk_mul_f32 v[164:165], v[164:165], v[198:199] op_sel_hi:[1,0]
	v_pk_mul_f32 v[166:167], v[166:167], v[198:199] op_sel_hi:[1,0]
	v_pk_mul_f32 v[168:169], v[168:169], v[198:199] op_sel_hi:[1,0]
	v_pk_mul_f32 v[170:171], v[170:171], v[198:199] op_sel_hi:[1,0]
	v_pk_mul_f32 v[172:173], v[172:173], v[198:199] op_sel_hi:[1,0]
	v_pk_mul_f32 v[174:175], v[174:175], v[198:199] op_sel_hi:[1,0]
	v_pk_fma_f32 v[160:161], v[160:161], v[0:1], v[16:17]
	v_pk_fma_f32 v[162:163], v[162:163], v[2:3], v[18:19]
	v_pk_fma_f32 v[164:165], v[164:165], v[4:5], v[20:21]
	v_pk_fma_f32 v[166:167], v[166:167], v[6:7], v[22:23]
	v_pk_fma_f32 v[168:169], v[168:169], v[8:9], v[24:25]
	v_pk_fma_f32 v[170:171], v[170:171], v[10:11], v[26:27]
	v_pk_fma_f32 v[172:173], v[172:173], v[12:13], v[28:29]
	v_pk_fma_f32 v[174:175], v[174:175], v[14:15], v[30:31]
	global_store_dwordx4 v200, v[160:163], s[8:9] offset:0
	global_store_dwordx4 v200, v[164:167], s[8:9] offset:1024
	global_store_dwordx4 v200, v[168:171], s[8:9] offset:2048
	global_store_dwordx4 v200, v[172:175], s[8:9] offset:3072
	s_add_u32 s8, s8, 0x1000
	s_addc_u32 s9, s9, 0
	s_add_u32 s12, s12, 0x800
	s_addc_u32 s13, s13, 0
	global_load_dwordx4 v[96:99], v200, s[14:15] offset:0
	global_load_dwordx4 v[100:103], v200, s[14:15] offset:1024
	global_load_dwordx4 v[104:107], v200, s[14:15] offset:2048
	global_load_dwordx4 v[108:111], v200, s[14:15] offset:3072
	global_load_dwordx2 v[144:145], v201, s[6:7] offset:0
	global_load_dwordx2 v[146:147], v201, s[6:7] offset:512
	global_load_dwordx2 v[148:149], v201, s[6:7] offset:1024
	global_load_dwordx2 v[150:151], v201, s[6:7] offset:1536
	s_add_u32 s14, s14, 0x1000
	s_addc_u32 s15, s15, 0
	s_add_u32 s6, s6, 0x800
	s_addc_u32 s7, s7, 0
	s_waitcnt vmcnt(36)
	v_lshlrev_b32_e32 v160, 16, v152
	v_and_b32_e32 v161, 0xffff0000, v152
	v_lshlrev_b32_e32 v162, 16, v153
	v_and_b32_e32 v163, 0xffff0000, v153
	v_lshlrev_b32_e32 v164, 16, v154
	v_and_b32_e32 v165, 0xffff0000, v154
	v_lshlrev_b32_e32 v166, 16, v155
	v_and_b32_e32 v167, 0xffff0000, v155
	v_lshlrev_b32_e32 v168, 16, v156
	v_and_b32_e32 v169, 0xffff0000, v156
	v_lshlrev_b32_e32 v170, 16, v157
	v_and_b32_e32 v171, 0xffff0000, v157
	v_lshlrev_b32_e32 v172, 16, v158
	v_and_b32_e32 v173, 0xffff0000, v158
	v_lshlrev_b32_e32 v174, 16, v159
	v_and_b32_e32 v175, 0xffff0000, v159
	v_pk_fma_f32 v[160:161], v[112:113], s[44:45], v[160:161]
	v_pk_fma_f32 v[162:163], v[114:115], s[44:45], v[162:163]
	v_pk_fma_f32 v[164:165], v[116:117], s[44:45], v[164:165]
	v_pk_fma_f32 v[166:167], v[118:119], s[44:45], v[166:167]
	v_pk_fma_f32 v[168:169], v[120:121], s[44:45], v[168:169]
	v_pk_fma_f32 v[170:171], v[122:123], s[44:45], v[170:171]
	v_pk_fma_f32 v[172:173], v[124:125], s[44:45], v[172:173]
	v_pk_fma_f32 v[174:175], v[126:127], s[44:45], v[174:175]
	v_pk_add_f32 v[176:177], v[160:161], v[162:163]
	v_pk_add_f32 v[176:177], v[176:177], v[164:165]
	v_pk_add_f32 v[176:177], v[176:177], v[166:167]
	v_pk_add_f32 v[176:177], v[176:177], v[168:169]
	v_pk_add_f32 v[176:177], v[176:177], v[170:171]
	v_pk_add_f32 v[176:177], v[176:177], v[172:173]
	v_pk_add_f32 v[176:177], v[176:177], v[174:175]
	v_add_f32_e32 v194, v176, v177
	s_nop 1
	v_add_f32_dpp v192, v194, v194 quad_perm:[1,0,3,2] row_mask:0xf bank_mask:0xf
	s_nop 1
	v_add_f32_dpp v192, v192, v192 quad_perm:[2,3,0,1] row_mask:0xf bank_mask:0xf
	s_nop 1
	v_add_f32_dpp v192, v192, v192 row_half_mirror row_mask:0xf bank_mask:0xf
	s_nop 1
	v_add_f32_dpp v192, v192, v192 row_mirror row_mask:0xf bank_mask:0xf
	s_nop 1
	v_add_f32_dpp v192, v192, v192 row_bcast:15 row_mask:0xa bank_mask:0xf
	s_nop 1
	v_add_f32_dpp v192, v192, v192 row_bcast:31 row_mask:0xc bank_mask:0xf
	s_nop 1
	v_readlane_b32 s42, v192, 63
	s_nop 3
	s_mov_b32 s43, s42
	v_pk_fma_f32 v[160:161], s[42:43], v[196:197], v[160:161]
	v_pk_fma_f32 v[162:163], s[42:43], v[196:197], v[162:163]
	v_pk_fma_f32 v[164:165], s[42:43], v[196:197], v[164:165]
	v_pk_fma_f32 v[166:167], s[42:43], v[196:197], v[166:167]
	v_pk_fma_f32 v[168:169], s[42:43], v[196:197], v[168:169]
	v_pk_fma_f32 v[170:171], s[42:43], v[196:197], v[170:171]
	v_pk_fma_f32 v[172:173], s[42:43], v[196:197], v[172:173]
	v_pk_fma_f32 v[174:175], s[42:43], v[196:197], v[174:175]
	v_pk_mul_f32 v[176:177], v[160:161], v[160:161]
	v_pk_fma_f32 v[176:177], v[162:163], v[162:163], v[176:177]
	v_pk_fma_f32 v[176:177], v[164:165], v[164:165], v[176:177]
	v_pk_fma_f32 v[176:177], v[166:167], v[166:167], v[176:177]
	v_pk_fma_f32 v[176:177], v[168:169], v[168:169], v[176:177]
	v_pk_fma_f32 v[176:177], v[170:171], v[170:171], v[176:177]
	v_pk_fma_f32 v[176:177], v[172:173], v[172:173], v[176:177]
	v_pk_fma_f32 v[176:177], v[174:175], v[174:175], v[176:177]
	v_add_f32_e32 v194, v176, v177
	s_nop 1
	v_add_f32_dpp v192, v194, v194 quad_perm:[1,0,3,2] row_mask:0xf bank_mask:0xf
	s_nop 1
	v_add_f32_dpp v192, v192, v192 quad_perm:[2,3,0,1] row_mask:0xf bank_mask:0xf
	s_nop 1
	v_add_f32_dpp v192, v192, v192 row_half_mirror row_mask:0xf bank_mask:0xf
	s_nop 1
	v_add_f32_dpp v192, v192, v192 row_mirror row_mask:0xf bank_mask:0xf
	s_nop 1
	v_add_f32_dpp v192, v192, v192 row_bcast:15 row_mask:0xa bank_mask:0xf
	s_nop 1
	v_add_f32_dpp v192, v192, v192 row_bcast:31 row_mask:0xc bank_mask:0xf
	s_nop 1
	v_readlane_b32 s42, v192, 63
	s_nop 3
	v_fma_f32 v198, s42, v202, v203
	v_rsq_f32_e32 v198, v198
	s_nop 0
	v_pk_mul_f32 v[160:161], v[160:161], v[198:199] op_sel_hi:[1,0]
	v_pk_mul_f32 v[162:163], v[162:163], v[198:199] op_sel_hi:[1,0]
	v_pk_mul_f32 v[164:165], v[164:165], v[198:199] op_sel_hi:[1,0]
	v_pk_mul_f32 v[166:167], v[166:167], v[198:199] op_sel_hi:[1,0]
	v_pk_mul_f32 v[168:169], v[168:169], v[198:199] op_sel_hi:[1,0]
	v_pk_mul_f32 v[170:171], v[170:171], v[198:199] op_sel_hi:[1,0]
	v_pk_mul_f32 v[172:173], v[172:173], v[198:199] op_sel_hi:[1,0]
	v_pk_mul_f32 v[174:175], v[174:175], v[198:199] op_sel_hi:[1,0]
	v_pk_fma_f32 v[160:161], v[160:161], v[0:1], v[16:17]
	v_pk_fma_f32 v[162:163], v[162:163], v[2:3], v[18:19]
	v_pk_fma_f32 v[164:165], v[164:165], v[4:5], v[20:21]
	v_pk_fma_f32 v[166:167], v[166:167], v[6:7], v[22:23]
	v_pk_fma_f32 v[168:169], v[168:169], v[8:9], v[24:25]
	v_pk_fma_f32 v[170:171], v[170:171], v[10:11], v[26:27]
	v_pk_fma_f32 v[172:173], v[172:173], v[12:13], v[28:29]
	v_pk_fma_f32 v[174:175], v[174:175], v[14:15], v[30:31]
	global_store_dwordx4 v200, v[160:163], s[8:9] offset:0
	global_store_dwordx4 v200, v[164:167], s[8:9] offset:1024
	global_store_dwordx4 v200, v[168:171], s[8:9] offset:2048
	global_store_dwordx4 v200, v[172:175], s[8:9] offset:3072
	s_add_u32 s8, s8, 0x1000
	s_addc_u32 s9, s9, 0
	s_add_u32 s12, s12, 0x800
	s_addc_u32 s13, s13, 0
	global_load_dwordx4 v[112:115], v200, s[14:15] offset:0
	global_load_dwordx4 v[116:119], v200, s[14:15] offset:1024
	global_load_dwordx4 v[120:123], v200, s[14:15] offset:2048
	global_load_dwordx4 v[124:127], v200, s[14:15] offset:3072
	global_load_dwordx2 v[152:153], v201, s[6:7] offset:0
	global_load_dwordx2 v[154:155], v201, s[6:7] offset:512
	global_load_dwordx2 v[156:157], v201, s[6:7] offset:1024
	global_load_dwordx2 v[158:159], v201, s[6:7] offset:1536
	s_add_u32 s14, s14, 0x1000
	s_addc_u32 s15, s15, 0
	s_add_u32 s6, s6, 0x800
	s_addc_u32 s7, s7, 0
	s_waitcnt vmcnt(36)
	v_lshlrev_b32_e32 v160, 16, v128
	v_and_b32_e32 v161, 0xffff0000, v128
	v_lshlrev_b32_e32 v162, 16, v129
	v_and_b32_e32 v163, 0xffff0000, v129
	v_lshlrev_b32_e32 v164, 16, v130
	v_and_b32_e32 v165, 0xffff0000, v130
	v_lshlrev_b32_e32 v166, 16, v131
	v_and_b32_e32 v167, 0xffff0000, v131
	v_lshlrev_b32_e32 v168, 16, v132
	v_and_b32_e32 v169, 0xffff0000, v132
	v_lshlrev_b32_e32 v170, 16, v133
	v_and_b32_e32 v171, 0xffff0000, v133
	v_lshlrev_b32_e32 v172, 16, v134
	v_and_b32_e32 v173, 0xffff0000, v134
	v_lshlrev_b32_e32 v174, 16, v135
	v_and_b32_e32 v175, 0xffff0000, v135
	v_pk_fma_f32 v[160:161], v[64:65], s[44:45], v[160:161]
	v_pk_fma_f32 v[162:163], v[66:67], s[44:45], v[162:163]
	v_pk_fma_f32 v[164:165], v[68:69], s[44:45], v[164:165]
	v_pk_fma_f32 v[166:167], v[70:71], s[44:45], v[166:167]
	v_pk_fma_f32 v[168:169], v[72:73], s[44:45], v[168:169]
	v_pk_fma_f32 v[170:171], v[74:75], s[44:45], v[170:171]
	v_pk_fma_f32 v[172:173], v[76:77], s[44:45], v[172:173]
	v_pk_fma_f32 v[174:175], v[78:79], s[44:45], v[174:175]
	v_pk_add_f32 v[176:177], v[160:161], v[162:163]
	v_pk_add_f32 v[176:177], v[176:177], v[164:165]
	v_pk_add_f32 v[176:177], v[176:177], v[166:167]
	v_pk_add_f32 v[176:177], v[176:177], v[168:169]
	v_pk_add_f32 v[176:177], v[176:177], v[170:171]
	v_pk_add_f32 v[176:177], v[176:177], v[172:173]
	v_pk_add_f32 v[176:177], v[176:177], v[174:175]
	v_add_f32_e32 v194, v176, v177
	s_nop 1
	v_add_f32_dpp v192, v194, v194 quad_perm:[1,0,3,2] row_mask:0xf bank_mask:0xf
	s_nop 1
	v_add_f32_dpp v192, v192, v192 quad_perm:[2,3,0,1] row_mask:0xf bank_mask:0xf
	s_nop 1
	v_add_f32_dpp v192, v192, v192 row_half_mirror row_mask:0xf bank_mask:0xf
	s_nop 1
	v_add_f32_dpp v192, v192, v192 row_mirror row_mask:0xf bank_mask:0xf
	s_nop 1
	v_add_f32_dpp v192, v192, v192 row_bcast:15 row_mask:0xa bank_mask:0xf
	s_nop 1
	v_add_f32_dpp v192, v192, v192 row_bcast:31 row_mask:0xc bank_mask:0xf
	s_nop 1
	v_readlane_b32 s42, v192, 63
	s_nop 3
	s_mov_b32 s43, s42
	v_pk_fma_f32 v[160:161], s[42:43], v[196:197], v[160:161]
	v_pk_fma_f32 v[162:163], s[42:43], v[196:197], v[162:163]
	v_pk_fma_f32 v[164:165], s[42:43], v[196:197], v[164:165]
	v_pk_fma_f32 v[166:167], s[42:43], v[196:197], v[166:167]
	v_pk_fma_f32 v[168:169], s[42:43], v[196:197], v[168:169]
	v_pk_fma_f32 v[170:171], s[42:43], v[196:197], v[170:171]
	v_pk_fma_f32 v[172:173], s[42:43], v[196:197], v[172:173]
	v_pk_fma_f32 v[174:175], s[42:43], v[196:197], v[174:175]
	v_pk_mul_f32 v[176:177], v[160:161], v[160:161]
	v_pk_fma_f32 v[176:177], v[162:163], v[162:163], v[176:177]
	v_pk_fma_f32 v[176:177], v[164:165], v[164:165], v[176:177]
	v_pk_fma_f32 v[176:177], v[166:167], v[166:167], v[176:177]
	v_pk_fma_f32 v[176:177], v[168:169], v[168:169], v[176:177]
	v_pk_fma_f32 v[176:177], v[170:171], v[170:171], v[176:177]
	v_pk_fma_f32 v[176:177], v[172:173], v[172:173], v[176:177]
	v_pk_fma_f32 v[176:177], v[174:175], v[174:175], v[176:177]
	v_add_f32_e32 v194, v176, v177
	s_nop 1
	v_add_f32_dpp v192, v194, v194 quad_perm:[1,0,3,2] row_mask:0xf bank_mask:0xf
	s_nop 1
	v_add_f32_dpp v192, v192, v192 quad_perm:[2,3,0,1] row_mask:0xf bank_mask:0xf
	s_nop 1
	v_add_f32_dpp v192, v192, v192 row_half_mirror row_mask:0xf bank_mask:0xf
	s_nop 1
	v_add_f32_dpp v192, v192, v192 row_mirror row_mask:0xf bank_mask:0xf
	s_nop 1
	v_add_f32_dpp v192, v192, v192 row_bcast:15 row_mask:0xa bank_mask:0xf
	s_nop 1
	v_add_f32_dpp v192, v192, v192 row_bcast:31 row_mask:0xc bank_mask:0xf
	s_nop 1
	v_readlane_b32 s42, v192, 63
	s_nop 3
	v_fma_f32 v198, s42, v202, v203
	v_rsq_f32_e32 v198, v198
	s_nop 0
	v_pk_mul_f32 v[160:161], v[160:161], v[198:199] op_sel_hi:[1,0]
	v_pk_mul_f32 v[162:163], v[162:163], v[198:199] op_sel_hi:[1,0]
	v_pk_mul_f32 v[164:165], v[164:165], v[198:199] op_sel_hi:[1,0]
	v_pk_mul_f32 v[166:167], v[166:167], v[198:199] op_sel_hi:[1,0]
	v_pk_mul_f32 v[168:169], v[168:169], v[198:199] op_sel_hi:[1,0]
	v_pk_mul_f32 v[170:171], v[170:171], v[198:199] op_sel_hi:[1,0]
	v_pk_mul_f32 v[172:173], v[172:173], v[198:199] op_sel_hi:[1,0]
	v_pk_mul_f32 v[174:175], v[174:175], v[198:199] op_sel_hi:[1,0]
	v_pk_fma_f32 v[160:161], v[160:161], v[0:1], v[16:17]
	v_pk_fma_f32 v[162:163], v[162:163], v[2:3], v[18:19]
	v_pk_fma_f32 v[164:165], v[164:165], v[4:5], v[20:21]
	v_pk_fma_f32 v[166:167], v[166:167], v[6:7], v[22:23]
	v_pk_fma_f32 v[168:169], v[168:169], v[8:9], v[24:25]
	v_pk_fma_f32 v[170:171], v[170:171], v[10:11], v[26:27]
	v_pk_fma_f32 v[172:173], v[172:173], v[12:13], v[28:29]
	v_pk_fma_f32 v[174:175], v[174:175], v[14:15], v[30:31]
	global_store_dwordx4 v200, v[160:163], s[8:9] offset:0
	global_store_dwordx4 v200, v[164:167], s[8:9] offset:1024
	global_store_dwordx4 v200, v[168:171], s[8:9] offset:2048
	global_store_dwordx4 v200, v[172:175], s[8:9] offset:3072
	s_add_u32 s8, s8, 0x1000
	s_addc_u32 s9, s9, 0
	s_add_u32 s12, s12, 0x800
	s_addc_u32 s13, s13, 0
	s_waitcnt vmcnt(28)
	v_lshlrev_b32_e32 v160, 16, v136
	v_and_b32_e32 v161, 0xffff0000, v136
	v_lshlrev_b32_e32 v162, 16, v137
	v_and_b32_e32 v163, 0xffff0000, v137
	v_lshlrev_b32_e32 v164, 16, v138
	v_and_b32_e32 v165, 0xffff0000, v138
	v_lshlrev_b32_e32 v166, 16, v139
	v_and_b32_e32 v167, 0xffff0000, v139
	v_lshlrev_b32_e32 v168, 16, v140
	v_and_b32_e32 v169, 0xffff0000, v140
	v_lshlrev_b32_e32 v170, 16, v141
	v_and_b32_e32 v171, 0xffff0000, v141
	v_lshlrev_b32_e32 v172, 16, v142
	v_and_b32_e32 v173, 0xffff0000, v142
	v_lshlrev_b32_e32 v174, 16, v143
	v_and_b32_e32 v175, 0xffff0000, v143
	v_pk_fma_f32 v[160:161], v[80:81], s[44:45], v[160:161]
	v_pk_fma_f32 v[162:163], v[82:83], s[44:45], v[162:163]
	v_pk_fma_f32 v[164:165], v[84:85], s[44:45], v[164:165]
	v_pk_fma_f32 v[166:167], v[86:87], s[44:45], v[166:167]
	v_pk_fma_f32 v[168:169], v[88:89], s[44:45], v[168:169]
	v_pk_fma_f32 v[170:171], v[90:91], s[44:45], v[170:171]
	v_pk_fma_f32 v[172:173], v[92:93], s[44:45], v[172:173]
	v_pk_fma_f32 v[174:175], v[94:95], s[44:45], v[174:175]
	v_pk_add_f32 v[176:177], v[160:161], v[162:163]
	v_pk_add_f32 v[176:177], v[176:177], v[164:165]
	v_pk_add_f32 v[176:177], v[176:177], v[166:167]
	v_pk_add_f32 v[176:177], v[176:177], v[168:169]
	v_pk_add_f32 v[176:177], v[176:177], v[170:171]
	v_pk_add_f32 v[176:177], v[176:177], v[172:173]
	v_pk_add_f32 v[176:177], v[176:177], v[174:175]
	v_add_f32_e32 v194, v176, v177
	s_nop 1
	v_add_f32_dpp v192, v194, v194 quad_perm:[1,0,3,2] row_mask:0xf bank_mask:0xf
	s_nop 1
	v_add_f32_dpp v192, v192, v192 quad_perm:[2,3,0,1] row_mask:0xf bank_mask:0xf
	s_nop 1
	v_add_f32_dpp v192, v192, v192 row_half_mirror row_mask:0xf bank_mask:0xf
	s_nop 1
	v_add_f32_dpp v192, v192, v192 row_mirror row_mask:0xf bank_mask:0xf
	s_nop 1
	v_add_f32_dpp v192, v192, v192 row_bcast:15 row_mask:0xa bank_mask:0xf
	s_nop 1
	v_add_f32_dpp v192, v192, v192 row_bcast:31 row_mask:0xc bank_mask:0xf
	s_nop 1
	v_readlane_b32 s42, v192, 63
	s_nop 3
	s_mov_b32 s43, s42
	v_pk_fma_f32 v[160:161], s[42:43], v[196:197], v[160:161]
	v_pk_fma_f32 v[162:163], s[42:43], v[196:197], v[162:163]
	v_pk_fma_f32 v[164:165], s[42:43], v[196:197], v[164:165]
	v_pk_fma_f32 v[166:167], s[42:43], v[196:197], v[166:167]
	v_pk_fma_f32 v[168:169], s[42:43], v[196:197], v[168:169]
	v_pk_fma_f32 v[170:171], s[42:43], v[196:197], v[170:171]
	v_pk_fma_f32 v[172:173], s[42:43], v[196:197], v[172:173]
	v_pk_fma_f32 v[174:175], s[42:43], v[196:197], v[174:175]
	v_pk_mul_f32 v[176:177], v[160:161], v[160:161]
	v_pk_fma_f32 v[176:177], v[162:163], v[162:163], v[176:177]
	v_pk_fma_f32 v[176:177], v[164:165], v[164:165], v[176:177]
	v_pk_fma_f32 v[176:177], v[166:167], v[166:167], v[176:177]
	v_pk_fma_f32 v[176:177], v[168:169], v[168:169], v[176:177]
	v_pk_fma_f32 v[176:177], v[170:171], v[170:171], v[176:177]
	v_pk_fma_f32 v[176:177], v[172:173], v[172:173], v[176:177]
	v_pk_fma_f32 v[176:177], v[174:175], v[174:175], v[176:177]
	v_add_f32_e32 v194, v176, v177
	s_nop 1
	v_add_f32_dpp v192, v194, v194 quad_perm:[1,0,3,2] row_mask:0xf bank_mask:0xf
	s_nop 1
	v_add_f32_dpp v192, v192, v192 quad_perm:[2,3,0,1] row_mask:0xf bank_mask:0xf
	s_nop 1
	v_add_f32_dpp v192, v192, v192 row_half_mirror row_mask:0xf bank_mask:0xf
	s_nop 1
	v_add_f32_dpp v192, v192, v192 row_mirror row_mask:0xf bank_mask:0xf
	s_nop 1
	v_add_f32_dpp v192, v192, v192 row_bcast:15 row_mask:0xa bank_mask:0xf
	s_nop 1
	v_add_f32_dpp v192, v192, v192 row_bcast:31 row_mask:0xc bank_mask:0xf
	s_nop 1
	v_readlane_b32 s42, v192, 63
	s_nop 3
	v_fma_f32 v198, s42, v202, v203
	v_rsq_f32_e32 v198, v198
	s_nop 0
	v_pk_mul_f32 v[160:161], v[160:161], v[198:199] op_sel_hi:[1,0]
	v_pk_mul_f32 v[162:163], v[162:163], v[198:199] op_sel_hi:[1,0]
	v_pk_mul_f32 v[164:165], v[164:165], v[198:199] op_sel_hi:[1,0]
	v_pk_mul_f32 v[166:167], v[166:167], v[198:199] op_sel_hi:[1,0]
	v_pk_mul_f32 v[168:169], v[168:169], v[198:199] op_sel_hi:[1,0]
	v_pk_mul_f32 v[170:171], v[170:171], v[198:199] op_sel_hi:[1,0]
	v_pk_mul_f32 v[172:173], v[172:173], v[198:199] op_sel_hi:[1,0]
	v_pk_mul_f32 v[174:175], v[174:175], v[198:199] op_sel_hi:[1,0]
	v_pk_fma_f32 v[160:161], v[160:161], v[0:1], v[16:17]
	v_pk_fma_f32 v[162:163], v[162:163], v[2:3], v[18:19]
	v_pk_fma_f32 v[164:165], v[164:165], v[4:5], v[20:21]
	v_pk_fma_f32 v[166:167], v[166:167], v[6:7], v[22:23]
	v_pk_fma_f32 v[168:169], v[168:169], v[8:9], v[24:25]
	v_pk_fma_f32 v[170:171], v[170:171], v[10:11], v[26:27]
	v_pk_fma_f32 v[172:173], v[172:173], v[12:13], v[28:29]
	v_pk_fma_f32 v[174:175], v[174:175], v[14:15], v[30:31]
	global_store_dwordx4 v200, v[160:163], s[8:9] offset:0
	global_store_dwordx4 v200, v[164:167], s[8:9] offset:1024
	global_store_dwordx4 v200, v[168:171], s[8:9] offset:2048
	global_store_dwordx4 v200, v[172:175], s[8:9] offset:3072
	s_add_u32 s8, s8, 0x1000
	s_addc_u32 s9, s9, 0
	s_add_u32 s12, s12, 0x800
	s_addc_u32 s13, s13, 0
	s_waitcnt vmcnt(20)
	v_lshlrev_b32_e32 v160, 16, v144
	v_and_b32_e32 v161, 0xffff0000, v144
	v_lshlrev_b32_e32 v162, 16, v145
	v_and_b32_e32 v163, 0xffff0000, v145
	v_lshlrev_b32_e32 v164, 16, v146
	v_and_b32_e32 v165, 0xffff0000, v146
	v_lshlrev_b32_e32 v166, 16, v147
	v_and_b32_e32 v167, 0xffff0000, v147
	v_lshlrev_b32_e32 v168, 16, v148
	v_and_b32_e32 v169, 0xffff0000, v148
	v_lshlrev_b32_e32 v170, 16, v149
	v_and_b32_e32 v171, 0xffff0000, v149
	v_lshlrev_b32_e32 v172, 16, v150
	v_and_b32_e32 v173, 0xffff0000, v150
	v_lshlrev_b32_e32 v174, 16, v151
	v_and_b32_e32 v175, 0xffff0000, v151
	v_pk_fma_f32 v[160:161], v[96:97], s[44:45], v[160:161]
	v_pk_fma_f32 v[162:163], v[98:99], s[44:45], v[162:163]
	v_pk_fma_f32 v[164:165], v[100:101], s[44:45], v[164:165]
	v_pk_fma_f32 v[166:167], v[102:103], s[44:45], v[166:167]
	v_pk_fma_f32 v[168:169], v[104:105], s[44:45], v[168:169]
	v_pk_fma_f32 v[170:171], v[106:107], s[44:45], v[170:171]
	v_pk_fma_f32 v[172:173], v[108:109], s[44:45], v[172:173]
	v_pk_fma_f32 v[174:175], v[110:111], s[44:45], v[174:175]
	v_pk_add_f32 v[176:177], v[160:161], v[162:163]
	v_pk_add_f32 v[176:177], v[176:177], v[164:165]
	v_pk_add_f32 v[176:177], v[176:177], v[166:167]
	v_pk_add_f32 v[176:177], v[176:177], v[168:169]
	v_pk_add_f32 v[176:177], v[176:177], v[170:171]
	v_pk_add_f32 v[176:177], v[176:177], v[172:173]
	v_pk_add_f32 v[176:177], v[176:177], v[174:175]
	v_add_f32_e32 v194, v176, v177
	s_nop 1
	v_add_f32_dpp v192, v194, v194 quad_perm:[1,0,3,2] row_mask:0xf bank_mask:0xf
	s_nop 1
	v_add_f32_dpp v192, v192, v192 quad_perm:[2,3,0,1] row_mask:0xf bank_mask:0xf
	s_nop 1
	v_add_f32_dpp v192, v192, v192 row_half_mirror row_mask:0xf bank_mask:0xf
	s_nop 1
	v_add_f32_dpp v192, v192, v192 row_mirror row_mask:0xf bank_mask:0xf
	s_nop 1
	v_add_f32_dpp v192, v192, v192 row_bcast:15 row_mask:0xa bank_mask:0xf
	s_nop 1
	v_add_f32_dpp v192, v192, v192 row_bcast:31 row_mask:0xc bank_mask:0xf
	s_nop 1
	v_readlane_b32 s42, v192, 63
	s_nop 3
	s_mov_b32 s43, s42
	v_pk_fma_f32 v[160:161], s[42:43], v[196:197], v[160:161]
	v_pk_fma_f32 v[162:163], s[42:43], v[196:197], v[162:163]
	v_pk_fma_f32 v[164:165], s[42:43], v[196:197], v[164:165]
	v_pk_fma_f32 v[166:167], s[42:43], v[196:197], v[166:167]
	v_pk_fma_f32 v[168:169], s[42:43], v[196:197], v[168:169]
	v_pk_fma_f32 v[170:171], s[42:43], v[196:197], v[170:171]
	v_pk_fma_f32 v[172:173], s[42:43], v[196:197], v[172:173]
	v_pk_fma_f32 v[174:175], s[42:43], v[196:197], v[174:175]
	v_pk_mul_f32 v[176:177], v[160:161], v[160:161]
	v_pk_fma_f32 v[176:177], v[162:163], v[162:163], v[176:177]
	v_pk_fma_f32 v[176:177], v[164:165], v[164:165], v[176:177]
	v_pk_fma_f32 v[176:177], v[166:167], v[166:167], v[176:177]
	v_pk_fma_f32 v[176:177], v[168:169], v[168:169], v[176:177]
	v_pk_fma_f32 v[176:177], v[170:171], v[170:171], v[176:177]
	v_pk_fma_f32 v[176:177], v[172:173], v[172:173], v[176:177]
	v_pk_fma_f32 v[176:177], v[174:175], v[174:175], v[176:177]
	v_add_f32_e32 v194, v176, v177
	s_nop 1
	v_add_f32_dpp v192, v194, v194 quad_perm:[1,0,3,2] row_mask:0xf bank_mask:0xf
	s_nop 1
	v_add_f32_dpp v192, v192, v192 quad_perm:[2,3,0,1] row_mask:0xf bank_mask:0xf
	s_nop 1
	v_add_f32_dpp v192, v192, v192 row_half_mirror row_mask:0xf bank_mask:0xf
	s_nop 1
	v_add_f32_dpp v192, v192, v192 row_mirror row_mask:0xf bank_mask:0xf
	s_nop 1
	v_add_f32_dpp v192, v192, v192 row_bcast:15 row_mask:0xa bank_mask:0xf
	s_nop 1
	v_add_f32_dpp v192, v192, v192 row_bcast:31 row_mask:0xc bank_mask:0xf
	s_nop 1
	v_readlane_b32 s42, v192, 63
	s_nop 3
	v_fma_f32 v198, s42, v202, v203
	v_rsq_f32_e32 v198, v198
	s_nop 0
	v_pk_mul_f32 v[160:161], v[160:161], v[198:199] op_sel_hi:[1,0]
	v_pk_mul_f32 v[162:163], v[162:163], v[198:199] op_sel_hi:[1,0]
	v_pk_mul_f32 v[164:165], v[164:165], v[198:199] op_sel_hi:[1,0]
	v_pk_mul_f32 v[166:167], v[166:167], v[198:199] op_sel_hi:[1,0]
	v_pk_mul_f32 v[168:169], v[168:169], v[198:199] op_sel_hi:[1,0]
	v_pk_mul_f32 v[170:171], v[170:171], v[198:199] op_sel_hi:[1,0]
	v_pk_mul_f32 v[172:173], v[172:173], v[198:199] op_sel_hi:[1,0]
	v_pk_mul_f32 v[174:175], v[174:175], v[198:199] op_sel_hi:[1,0]
	v_pk_fma_f32 v[160:161], v[160:161], v[0:1], v[16:17]
	v_pk_fma_f32 v[162:163], v[162:163], v[2:3], v[18:19]
	v_pk_fma_f32 v[164:165], v[164:165], v[4:5], v[20:21]
	v_pk_fma_f32 v[166:167], v[166:167], v[6:7], v[22:23]
	v_pk_fma_f32 v[168:169], v[168:169], v[8:9], v[24:25]
	v_pk_fma_f32 v[170:171], v[170:171], v[10:11], v[26:27]
	v_pk_fma_f32 v[172:173], v[172:173], v[12:13], v[28:29]
	v_pk_fma_f32 v[174:175], v[174:175], v[14:15], v[30:31]
	global_store_dwordx4 v200, v[160:163], s[8:9] offset:0
	global_store_dwordx4 v200, v[164:167], s[8:9] offset:1024
	global_store_dwordx4 v200, v[168:171], s[8:9] offset:2048
	global_store_dwordx4 v200, v[172:175], s[8:9] offset:3072
	s_add_u32 s8, s8, 0x1000
	s_addc_u32 s9, s9, 0
	s_add_u32 s12, s12, 0x800
	s_addc_u32 s13, s13, 0
	s_waitcnt vmcnt(12)
	v_lshlrev_b32_e32 v160, 16, v152
	v_and_b32_e32 v161, 0xffff0000, v152
	v_lshlrev_b32_e32 v162, 16, v153
	v_and_b32_e32 v163, 0xffff0000, v153
	v_lshlrev_b32_e32 v164, 16, v154
	v_and_b32_e32 v165, 0xffff0000, v154
	v_lshlrev_b32_e32 v166, 16, v155
	v_and_b32_e32 v167, 0xffff0000, v155
	v_lshlrev_b32_e32 v168, 16, v156
	v_and_b32_e32 v169, 0xffff0000, v156
	v_lshlrev_b32_e32 v170, 16, v157
	v_and_b32_e32 v171, 0xffff0000, v157
	v_lshlrev_b32_e32 v172, 16, v158
	v_and_b32_e32 v173, 0xffff0000, v158
	v_lshlrev_b32_e32 v174, 16, v159
	v_and_b32_e32 v175, 0xffff0000, v159
	v_pk_fma_f32 v[160:161], v[112:113], s[44:45], v[160:161]
	v_pk_fma_f32 v[162:163], v[114:115], s[44:45], v[162:163]
	v_pk_fma_f32 v[164:165], v[116:117], s[44:45], v[164:165]
	v_pk_fma_f32 v[166:167], v[118:119], s[44:45], v[166:167]
	v_pk_fma_f32 v[168:169], v[120:121], s[44:45], v[168:169]
	v_pk_fma_f32 v[170:171], v[122:123], s[44:45], v[170:171]
	v_pk_fma_f32 v[172:173], v[124:125], s[44:45], v[172:173]
	v_pk_fma_f32 v[174:175], v[126:127], s[44:45], v[174:175]
	v_pk_add_f32 v[176:177], v[160:161], v[162:163]
	v_pk_add_f32 v[176:177], v[176:177], v[164:165]
	v_pk_add_f32 v[176:177], v[176:177], v[166:167]
	v_pk_add_f32 v[176:177], v[176:177], v[168:169]
	v_pk_add_f32 v[176:177], v[176:177], v[170:171]
	v_pk_add_f32 v[176:177], v[176:177], v[172:173]
	v_pk_add_f32 v[176:177], v[176:177], v[174:175]
	v_add_f32_e32 v194, v176, v177
	s_nop 1
	v_add_f32_dpp v192, v194, v194 quad_perm:[1,0,3,2] row_mask:0xf bank_mask:0xf
	s_nop 1
	v_add_f32_dpp v192, v192, v192 quad_perm:[2,3,0,1] row_mask:0xf bank_mask:0xf
	s_nop 1
	v_add_f32_dpp v192, v192, v192 row_half_mirror row_mask:0xf bank_mask:0xf
	s_nop 1
	v_add_f32_dpp v192, v192, v192 row_mirror row_mask:0xf bank_mask:0xf
	s_nop 1
	v_add_f32_dpp v192, v192, v192 row_bcast:15 row_mask:0xa bank_mask:0xf
	s_nop 1
	v_add_f32_dpp v192, v192, v192 row_bcast:31 row_mask:0xc bank_mask:0xf
	s_nop 1
	v_readlane_b32 s42, v192, 63
	s_nop 3
	s_mov_b32 s43, s42
	v_pk_fma_f32 v[160:161], s[42:43], v[196:197], v[160:161]
	v_pk_fma_f32 v[162:163], s[42:43], v[196:197], v[162:163]
	v_pk_fma_f32 v[164:165], s[42:43], v[196:197], v[164:165]
	v_pk_fma_f32 v[166:167], s[42:43], v[196:197], v[166:167]
	v_pk_fma_f32 v[168:169], s[42:43], v[196:197], v[168:169]
	v_pk_fma_f32 v[170:171], s[42:43], v[196:197], v[170:171]
	v_pk_fma_f32 v[172:173], s[42:43], v[196:197], v[172:173]
	v_pk_fma_f32 v[174:175], s[42:43], v[196:197], v[174:175]
	v_pk_mul_f32 v[176:177], v[160:161], v[160:161]
	v_pk_fma_f32 v[176:177], v[162:163], v[162:163], v[176:177]
	v_pk_fma_f32 v[176:177], v[164:165], v[164:165], v[176:177]
	v_pk_fma_f32 v[176:177], v[166:167], v[166:167], v[176:177]
	v_pk_fma_f32 v[176:177], v[168:169], v[168:169], v[176:177]
	v_pk_fma_f32 v[176:177], v[170:171], v[170:171], v[176:177]
	v_pk_fma_f32 v[176:177], v[172:173], v[172:173], v[176:177]
	v_pk_fma_f32 v[176:177], v[174:175], v[174:175], v[176:177]
	v_add_f32_e32 v194, v176, v177
	s_nop 1
	v_add_f32_dpp v192, v194, v194 quad_perm:[1,0,3,2] row_mask:0xf bank_mask:0xf
	s_nop 1
	v_add_f32_dpp v192, v192, v192 quad_perm:[2,3,0,1] row_mask:0xf bank_mask:0xf
	s_nop 1
	v_add_f32_dpp v192, v192, v192 row_half_mirror row_mask:0xf bank_mask:0xf
	s_nop 1
	v_add_f32_dpp v192, v192, v192 row_mirror row_mask:0xf bank_mask:0xf
	s_nop 1
	v_add_f32_dpp v192, v192, v192 row_bcast:15 row_mask:0xa bank_mask:0xf
	s_nop 1
	v_add_f32_dpp v192, v192, v192 row_bcast:31 row_mask:0xc bank_mask:0xf
	s_nop 1
	v_readlane_b32 s42, v192, 63
	s_nop 3
	v_fma_f32 v198, s42, v202, v203
	v_rsq_f32_e32 v198, v198
	s_nop 0
	v_pk_mul_f32 v[160:161], v[160:161], v[198:199] op_sel_hi:[1,0]
	v_pk_mul_f32 v[162:163], v[162:163], v[198:199] op_sel_hi:[1,0]
	v_pk_mul_f32 v[164:165], v[164:165], v[198:199] op_sel_hi:[1,0]
	v_pk_mul_f32 v[166:167], v[166:167], v[198:199] op_sel_hi:[1,0]
	v_pk_mul_f32 v[168:169], v[168:169], v[198:199] op_sel_hi:[1,0]
	v_pk_mul_f32 v[170:171], v[170:171], v[198:199] op_sel_hi:[1,0]
	v_pk_mul_f32 v[172:173], v[172:173], v[198:199] op_sel_hi:[1,0]
	v_pk_mul_f32 v[174:175], v[174:175], v[198:199] op_sel_hi:[1,0]
	v_pk_fma_f32 v[160:161], v[160:161], v[0:1], v[16:17]
	v_pk_fma_f32 v[162:163], v[162:163], v[2:3], v[18:19]
	v_pk_fma_f32 v[164:165], v[164:165], v[4:5], v[20:21]
	v_pk_fma_f32 v[166:167], v[166:167], v[6:7], v[22:23]
	v_pk_fma_f32 v[168:169], v[168:169], v[8:9], v[24:25]
	v_pk_fma_f32 v[170:171], v[170:171], v[10:11], v[26:27]
	v_pk_fma_f32 v[172:173], v[172:173], v[12:13], v[28:29]
	v_pk_fma_f32 v[174:175], v[174:175], v[14:15], v[30:31]
	global_store_dwordx4 v200, v[160:163], s[8:9] offset:0
	global_store_dwordx4 v200, v[164:167], s[8:9] offset:1024
	global_store_dwordx4 v200, v[168:171], s[8:9] offset:2048
	global_store_dwordx4 v200, v[172:175], s[8:9] offset:3072
	s_add_u32 s8, s8, 0x1000
	s_addc_u32 s9, s9, 0
	s_add_u32 s12, s12, 0x800
	s_addc_u32 s13, s13, 0
